# conformer conv inputs fetched a pass ahead; RG-LRU summaries-pass bias float4 loaded once per direction
# speedup vs baseline: 1.2353x; 1.0230x over previous
.LBB0_561:
	s_and_b64 vcc, exec, s[0:1]
	s_cbranch_vccz .LBB0_718
	v_mov_b32_e32 v0, v222
	s_mul_i32 s0, s16, 0x1f00
	s_waitcnt vmcnt(11)
	v_mov_b32_e32 v30, v3
	v_add_u32_e32 v4, s0, v0
	v_add_u32_e32 v14, 0x400, v4
	v_add_u32_e32 v16, 0x500, v4
	v_add_u32_e32 v18, 0x600, v4
	v_add_u32_e32 v20, 0x700, v4
	v_ashrrev_i32_e32 v5, 31, v4
	v_add_u32_e32 v8, 0x100, v4
	v_add_u32_e32 v10, 0x200, v4
	v_add_u32_e32 v12, 0x300, v4
	v_ashrrev_i32_e32 v15, 31, v14
	v_ashrrev_i32_e32 v17, 31, v16
	v_ashrrev_i32_e32 v19, 31, v18
	v_ashrrev_i32_e32 v21, 31, v20
	v_lshl_add_u64 v[6:7], v[4:5], 2, s[74:75]
	v_ashrrev_i32_e32 v9, 31, v8
	v_ashrrev_i32_e32 v11, 31, v10
	v_ashrrev_i32_e32 v13, 31, v12
	v_lshl_add_u64 v[14:15], v[14:15], 2, s[74:75]
	v_lshl_add_u64 v[16:17], v[16:17], 2, s[74:75]
	v_lshl_add_u64 v[18:19], v[18:19], 2, s[74:75]
	v_lshl_add_u64 v[20:21], v[20:21], 2, s[74:75]
	v_lshl_add_u64 v[8:9], v[8:9], 2, s[74:75]
	v_lshl_add_u64 v[10:11], v[10:11], 2, s[74:75]
	v_lshl_add_u64 v[12:13], v[12:13], 2, s[74:75]
	global_load_dword v60, v[6:7], off
	global_load_dword v61, v[8:9], off
	global_load_dword v62, v[10:11], off
	global_load_dword v63, v[12:13], off
	global_load_dword v64, v[14:15], off
	global_load_dword v65, v[16:17], off
	global_load_dword v66, v[18:19], off
	global_load_dword v67, v[20:21], off
	v_add_u32_e32 v14, 0x1000, v4
	v_add_u32_e32 v16, 0x1100, v4
	v_add_u32_e32 v18, 0x1200, v4
	v_add_u32_e32 v20, 0x1300, v4
	v_ashrrev_i32_e32 v15, 31, v14
	v_ashrrev_i32_e32 v17, 31, v16
	v_ashrrev_i32_e32 v19, 31, v18
	v_ashrrev_i32_e32 v21, 31, v20
	v_add_u32_e32 v22, 0x1400, v4
	v_add_u32_e32 v24, 0x1500, v4
	v_add_u32_e32 v26, 0x1600, v4
	v_add_u32_e32 v28, 0x1700, v4
	v_lshl_add_u64 v[14:15], v[14:15], 2, s[74:75]
	v_lshl_add_u64 v[16:17], v[16:17], 2, s[74:75]
	v_lshl_add_u64 v[18:19], v[18:19], 2, s[74:75]
	v_lshl_add_u64 v[20:21], v[20:21], 2, s[74:75]
	v_ashrrev_i32_e32 v23, 31, v22
	v_ashrrev_i32_e32 v25, 31, v24
	v_ashrrev_i32_e32 v27, 31, v26
	v_ashrrev_i32_e32 v29, 31, v28
	v_lshl_add_u64 v[22:23], v[22:23], 2, s[74:75]
	v_lshl_add_u64 v[24:25], v[24:25], 2, s[74:75]
	v_lshl_add_u64 v[26:27], v[26:27], 2, s[74:75]
	v_lshl_add_u64 v[28:29], v[28:29], 2, s[74:75]
	global_load_dword v68, v[14:15], off
	global_load_dword v69, v[16:17], off
	global_load_dword v70, v[18:19], off
	global_load_dword v36, v[20:21], off
	global_load_dword v37, v[22:23], off
	global_load_dword v38, v[24:25], off
	global_load_dword v39, v[26:27], off
	global_load_dword v40, v[28:29], off
	v_add_u32_e32 v14, 0x1800, v4
	v_add_u32_e32 v16, 0x1900, v4
	v_add_u32_e32 v18, 0x1a00, v4
	v_add_u32_e32 v20, 0x1b00, v4
	v_ashrrev_i32_e32 v15, 31, v14
	v_ashrrev_i32_e32 v17, 31, v16
	v_ashrrev_i32_e32 v19, 31, v18
	v_ashrrev_i32_e32 v21, 31, v20
	v_add_u32_e32 v22, 0x1c00, v4
	v_add_u32_e32 v6, 0x800, v4
	v_lshl_add_u64 v[14:15], v[14:15], 2, s[74:75]
	v_lshl_add_u64 v[16:17], v[16:17], 2, s[74:75]
	v_lshl_add_u64 v[18:19], v[18:19], 2, s[74:75]
	v_lshl_add_u64 v[20:21], v[20:21], 2, s[74:75]
	v_ashrrev_i32_e32 v23, 31, v22
	v_ashrrev_i32_e32 v7, 31, v6
	v_add_u32_e32 v8, 0x900, v4
	v_add_u32_e32 v10, 0xa00, v4
	v_add_u32_e32 v12, 0xb00, v4
	v_lshl_add_u64 v[22:23], v[22:23], 2, s[74:75]
	global_load_dword v41, v[14:15], off
	global_load_dword v42, v[16:17], off
	global_load_dword v43, v[18:19], off
	global_load_dword v44, v[20:21], off
	global_load_dword v45, v[22:23], off
	v_add_u32_e32 v14, 0xc00, v4
	v_add_u32_e32 v16, 0xd00, v4
	v_add_u32_e32 v18, 0xe00, v4
	v_add_u32_e32 v20, 0xf00, v4
	v_lshl_add_u64 v[6:7], v[6:7], 2, s[74:75]
	v_ashrrev_i32_e32 v9, 31, v8
	v_ashrrev_i32_e32 v11, 31, v10
	v_ashrrev_i32_e32 v13, 31, v12
	v_ashrrev_i32_e32 v15, 31, v14
	v_ashrrev_i32_e32 v17, 31, v16
	v_ashrrev_i32_e32 v19, 31, v18
	v_ashrrev_i32_e32 v21, 31, v20
	v_lshl_add_u64 v[8:9], v[8:9], 2, s[74:75]
	v_lshl_add_u64 v[10:11], v[10:11], 2, s[74:75]
	v_lshl_add_u64 v[12:13], v[12:13], 2, s[74:75]
	v_lshl_add_u64 v[14:15], v[14:15], 2, s[74:75]
	v_lshl_add_u64 v[16:17], v[16:17], 2, s[74:75]
	v_lshl_add_u64 v[18:19], v[18:19], 2, s[74:75]
	v_lshl_add_u64 v[20:21], v[20:21], 2, s[74:75]
	global_load_dword v71, v[6:7], off
	global_load_dword v72, v[8:9], off
	global_load_dword v73, v[10:11], off
	global_load_dword v74, v[12:13], off
	global_load_dword v75, v[14:15], off
	global_load_dword v76, v[16:17], off
	global_load_dword v77, v[18:19], off
	global_load_dword v78, v[20:21], off
	v_add_u32_e32 v6, 0x1d00, v4
	v_add_u32_e32 v4, 0x1e00, v4
	v_ashrrev_i32_e32 v7, 31, v6
	v_ashrrev_i32_e32 v5, 31, v4
	v_lshl_add_u64 v[6:7], v[6:7], 2, s[74:75]
	v_lshl_add_u64 v[4:5], v[4:5], 2, s[74:75]
	v_readlane_b32 s0, v252, 40
	global_load_dword v46, v[6:7], off
	global_load_dword v47, v[4:5], off
	v_add_u32_e32 v4, s0, v0
	v_ashrrev_i32_e32 v5, 31, v4
	v_lshl_add_u64 v[4:5], v[4:5], 2, s[76:77]
	global_load_dword v79, v[4:5], off
	v_readlane_b32 s1, v252, 41
	s_add_i32 s0, s6, 0xf9a0
	s_and_b32 s1, s0, 0xffff
	s_mul_i32 s1, s1, 0xf0f1
	s_lshr_b32 s1, s1, 22
	s_mul_i32 s4, s1, 0x44
	s_sub_i32 s0, s0, s4
	s_and_b32 s4, s0, 0xffff
	s_lshl_b32 s10, s0, 6
	s_cmp_lt_u32 s4, 4
	s_mul_i32 s0, s1, 0x1100
	s_movk_i32 s1, 0x1100
	v_ashrrev_i32_e32 v1, 31, v0
	v_mov_b32_e32 v4, v3
	v_mov_b32_e32 v5, v3
	v_mov_b32_e32 v6, v3
	v_mov_b32_e32 v7, v3
	v_mov_b32_e32 v8, v3
	v_mov_b32_e32 v9, v3
	v_mov_b32_e32 v10, v3
	v_mov_b32_e32 v11, v3
	v_mov_b32_e32 v12, v3
	v_mov_b32_e32 v13, v3
	v_mov_b32_e32 v14, v3
	v_mov_b32_e32 v15, v3
	v_mov_b32_e32 v16, v3
	v_mov_b32_e32 v17, v3
	v_mov_b32_e32 v18, v3
	v_mov_b32_e32 v19, v3
	v_mov_b32_e32 v20, v3
	v_mov_b32_e32 v21, v3
	v_mov_b32_e32 v22, v3
	v_mov_b32_e32 v23, v3
	v_mov_b32_e32 v24, v3
	v_mov_b32_e32 v25, v3
	v_mov_b32_e32 v26, v3
	v_mov_b32_e32 v27, v3
	v_mov_b32_e32 v28, v3
	v_mov_b32_e32 v29, v3
	s_cselect_b32 s4, 0, 0x100
	s_cselect_b32 s7, 0x100, s1
	s_and_b32 s1, s10, 0xffc0
	s_waitcnt vmcnt(40)
	v_lshl_add_u64 v[48:49], v[0:1], 1, s[24:25]
	v_mov_b32_e32 v1, v3
	v_mov_b32_e32 v2, v3
	v_mov_b64_e32 v[34:35], v[30:31]
	s_mov_b32 s5, 0
	s_add_i32 s10, s1, -15
	s_waitcnt vmcnt(19)
	v_mov_b32_e32 v50, v37
	v_mov_b32_e32 v51, v36
	s_waitcnt vmcnt(17)
	v_mov_b32_e32 v52, v39
	v_mov_b32_e32 v53, v38
	s_waitcnt vmcnt(15)
	v_mov_b32_e32 v54, v41
	v_mov_b32_e32 v55, v40
	s_waitcnt vmcnt(13)
	v_mov_b32_e32 v56, v43
	v_mov_b32_e32 v57, v42
	s_waitcnt vmcnt(11)
	v_mov_b32_e32 v58, v45
	v_mov_b32_e32 v59, v44
	s_and_b32 s11, s0, 0xff00
	v_mov_b64_e32 v[32:33], v[28:29]
	v_mov_b64_e32 v[30:31], v[26:27]
	v_mov_b64_e32 v[28:29], v[24:25]
	v_mov_b64_e32 v[26:27], v[22:23]
	v_mov_b64_e32 v[24:25], v[20:21]
	v_mov_b64_e32 v[22:23], v[18:19]
	v_mov_b64_e32 v[20:21], v[16:17]
	v_mov_b64_e32 v[18:19], v[14:15]
	v_mov_b64_e32 v[16:17], v[12:13]
	v_mov_b64_e32 v[14:15], v[10:11]
	v_mov_b64_e32 v[12:13], v[8:9]
	v_mov_b64_e32 v[10:11], v[6:7]
	v_mov_b64_e32 v[8:9], v[4:5]
	v_mov_b64_e32 v[6:7], v[2:3]
	v_mov_b64_e32 v[4:5], v[0:1]
	s_barrier
	s_add_i32 s98, s5, s10
	s_add_i32 s98, s98, s11
	v_add_co_u32_e32 v208, vcc, 0x800, v48
	s_nop 1
	v_addc_co_u32_e32 v209, vcc, 0, v49, vcc
	s_max_i32 s99, s98, 0
	v_mad_u64_u32 v[210:211], s[42:43], s99, v233, v[208:209]
	global_load_ushort v84, v[210:211], off offset:2048
	global_load_ushort v115, v[210:211], off offset:1536
	s_add_i32 s98, s98, 1
	s_max_i32 s99, s98, 0
	v_mad_u64_u32 v[212:213], s[42:43], s99, v233, v[208:209]
	global_load_ushort v85, v[212:213], off offset:2048
	global_load_ushort v116, v[212:213], off offset:1536
	s_add_i32 s98, s98, 1
	s_max_i32 s99, s98, 0
	v_mad_u64_u32 v[210:211], s[42:43], s99, v233, v[208:209]
	global_load_ushort v86, v[210:211], off offset:2048
	global_load_ushort v117, v[210:211], off offset:1536
	s_add_i32 s98, s98, 1
	s_max_i32 s99, s98, 0
	v_mad_u64_u32 v[212:213], s[42:43], s99, v233, v[208:209]
	global_load_ushort v87, v[212:213], off offset:2048
	global_load_ushort v118, v[212:213], off offset:1536
	s_add_i32 s98, s98, 1
	s_max_i32 s99, s98, 0
	v_mad_u64_u32 v[210:211], s[42:43], s99, v233, v[208:209]
	global_load_ushort v88, v[210:211], off offset:2048
	global_load_ushort v119, v[210:211], off offset:1536
	s_add_i32 s98, s98, 1
	s_max_i32 s99, s98, 0
	v_mad_u64_u32 v[212:213], s[42:43], s99, v233, v[208:209]
	global_load_ushort v89, v[212:213], off offset:2048
	global_load_ushort v120, v[212:213], off offset:1536
	s_add_i32 s98, s98, 1
	s_max_i32 s99, s98, 0
	v_mad_u64_u32 v[210:211], s[42:43], s99, v233, v[208:209]
	global_load_ushort v90, v[210:211], off offset:2048
	global_load_ushort v121, v[210:211], off offset:1536
	s_add_i32 s98, s98, 1
	s_max_i32 s99, s98, 0
	v_mad_u64_u32 v[212:213], s[42:43], s99, v233, v[208:209]
	global_load_ushort v91, v[212:213], off offset:2048
	global_load_ushort v122, v[212:213], off offset:1536
	s_add_i32 s98, s98, 1
	s_max_i32 s99, s98, 0
	v_mad_u64_u32 v[210:211], s[42:43], s99, v233, v[208:209]
	global_load_ushort v92, v[210:211], off offset:2048
	global_load_ushort v123, v[210:211], off offset:1536
	s_add_i32 s98, s98, 1
	s_max_i32 s99, s98, 0
	v_mad_u64_u32 v[212:213], s[42:43], s99, v233, v[208:209]
	global_load_ushort v93, v[212:213], off offset:2048
	global_load_ushort v124, v[212:213], off offset:1536
	s_add_i32 s98, s98, 1
	s_max_i32 s99, s98, 0
	v_mad_u64_u32 v[210:211], s[42:43], s99, v233, v[208:209]
	global_load_ushort v94, v[210:211], off offset:2048
	global_load_ushort v125, v[210:211], off offset:1536
	s_add_i32 s98, s98, 1
	s_max_i32 s99, s98, 0
	v_mad_u64_u32 v[212:213], s[42:43], s99, v233, v[208:209]
	global_load_ushort v95, v[212:213], off offset:2048
	global_load_ushort v126, v[212:213], off offset:1536
	s_add_i32 s98, s98, 1
	s_max_i32 s99, s98, 0
	v_mad_u64_u32 v[210:211], s[42:43], s99, v233, v[208:209]
	global_load_ushort v96, v[210:211], off offset:2048
	global_load_ushort v127, v[210:211], off offset:1536
	s_add_i32 s98, s98, 1
	s_max_i32 s99, s98, 0
	v_mad_u64_u32 v[212:213], s[42:43], s99, v233, v[208:209]
	global_load_ushort v97, v[212:213], off offset:2048
	global_load_ushort v128, v[212:213], off offset:1536
	s_add_i32 s98, s98, 1
	s_max_i32 s99, s98, 0
	v_mad_u64_u32 v[210:211], s[42:43], s99, v233, v[208:209]
	global_load_ushort v98, v[210:211], off offset:2048
	global_load_ushort v129, v[210:211], off offset:1536
	s_add_i32 s98, s98, 1
	s_max_i32 s99, s98, 0
	v_mad_u64_u32 v[212:213], s[42:43], s99, v233, v[208:209]
	global_load_ushort v99, v[212:213], off offset:2048
	global_load_ushort v130, v[212:213], off offset:1536
	s_add_i32 s98, s98, 1
	s_max_i32 s99, s98, 0
	v_mad_u64_u32 v[210:211], s[42:43], s99, v233, v[208:209]
	global_load_ushort v100, v[210:211], off offset:2048
	global_load_ushort v131, v[210:211], off offset:1536
	s_add_i32 s98, s98, 1
	s_max_i32 s99, s98, 0
	v_mad_u64_u32 v[212:213], s[42:43], s99, v233, v[208:209]
	global_load_ushort v101, v[212:213], off offset:2048
	global_load_ushort v132, v[212:213], off offset:1536
	s_add_i32 s98, s98, 1
	s_max_i32 s99, s98, 0
	v_mad_u64_u32 v[210:211], s[42:43], s99, v233, v[208:209]
	global_load_ushort v102, v[210:211], off offset:2048
	global_load_ushort v133, v[210:211], off offset:1536
	s_add_i32 s98, s98, 1
	s_max_i32 s99, s98, 0
	v_mad_u64_u32 v[212:213], s[42:43], s99, v233, v[208:209]
	global_load_ushort v103, v[212:213], off offset:2048
	global_load_ushort v134, v[212:213], off offset:1536
	s_add_i32 s98, s98, 1
	s_max_i32 s99, s98, 0
	v_mad_u64_u32 v[210:211], s[42:43], s99, v233, v[208:209]
	global_load_ushort v104, v[210:211], off offset:2048
	global_load_ushort v135, v[210:211], off offset:1536
	s_add_i32 s98, s98, 1
	s_max_i32 s99, s98, 0
	v_mad_u64_u32 v[212:213], s[42:43], s99, v233, v[208:209]
	global_load_ushort v105, v[212:213], off offset:2048
	global_load_ushort v136, v[212:213], off offset:1536
	s_add_i32 s98, s98, 1
	s_max_i32 s99, s98, 0
	v_mad_u64_u32 v[210:211], s[42:43], s99, v233, v[208:209]
	global_load_ushort v106, v[210:211], off offset:2048
	global_load_ushort v137, v[210:211], off offset:1536
	s_add_i32 s98, s98, 1
	s_max_i32 s99, s98, 0
	v_mad_u64_u32 v[212:213], s[42:43], s99, v233, v[208:209]
	global_load_ushort v107, v[212:213], off offset:2048
	global_load_ushort v138, v[212:213], off offset:1536
	s_add_i32 s98, s98, 1
	s_max_i32 s99, s98, 0
	v_mad_u64_u32 v[210:211], s[42:43], s99, v233, v[208:209]
	global_load_ushort v108, v[210:211], off offset:2048
	global_load_ushort v139, v[210:211], off offset:1536
	s_add_i32 s98, s98, 1
	s_max_i32 s99, s98, 0
	v_mad_u64_u32 v[212:213], s[42:43], s99, v233, v[208:209]
	global_load_ushort v109, v[212:213], off offset:2048
	global_load_ushort v140, v[212:213], off offset:1536
	s_add_i32 s98, s98, 1
	s_max_i32 s99, s98, 0
	v_mad_u64_u32 v[210:211], s[42:43], s99, v233, v[208:209]
	global_load_ushort v110, v[210:211], off offset:2048
	global_load_ushort v141, v[210:211], off offset:1536
	s_add_i32 s98, s98, 1
	s_max_i32 s99, s98, 0
	v_mad_u64_u32 v[212:213], s[42:43], s99, v233, v[208:209]
	global_load_ushort v111, v[212:213], off offset:2048
	global_load_ushort v142, v[212:213], off offset:1536
	s_add_i32 s98, s98, 1
	s_max_i32 s99, s98, 0
	v_mad_u64_u32 v[210:211], s[42:43], s99, v233, v[208:209]
	global_load_ushort v112, v[210:211], off offset:2048
	global_load_ushort v143, v[210:211], off offset:1536
	s_add_i32 s98, s98, 1
	s_max_i32 s99, s98, 0
	v_mad_u64_u32 v[212:213], s[42:43], s99, v233, v[208:209]
	global_load_ushort v113, v[212:213], off offset:2048
	global_load_ushort v144, v[212:213], off offset:1536
	s_add_i32 s98, s98, 1
	s_max_i32 s99, s98, 0
	v_mad_u64_u32 v[210:211], s[42:43], s99, v233, v[208:209]
	global_load_ushort v114, v[210:211], off offset:2048
	global_load_ushort v145, v[210:211], off offset:1536
	s_add_i32 s98, s98, 1
.Lconf_pf_done_a:
	s_branch .LBB0_565
.LBB0_563:
	s_waitcnt vmcnt(0)
	v_fma_f32 v1, v60, v4, v79
	v_fmac_f32_e32 v1, v61, v5
	v_fmac_f32_e32 v1, v62, v6
	v_fmac_f32_e32 v1, v63, v7
	v_fmac_f32_e32 v1, v64, v8
	v_fmac_f32_e32 v1, v65, v9
	v_fmac_f32_e32 v1, v66, v10
	v_fmac_f32_e32 v1, v67, v11
	v_fmac_f32_e32 v1, v71, v12
	v_fmac_f32_e32 v1, v72, v13
	v_fmac_f32_e32 v1, v73, v14
	v_fmac_f32_e32 v1, v74, v15
	v_fmac_f32_e32 v1, v75, v16
	v_fmac_f32_e32 v1, v76, v17
	v_fmac_f32_e32 v1, v77, v18
	v_fmac_f32_e32 v1, v78, v19
	v_fmac_f32_e32 v1, v68, v20
	v_fmac_f32_e32 v1, v69, v21
	v_mov_b32_e32 v80, v23
	v_mov_b32_e32 v81, v24
	v_fmac_f32_e32 v1, v70, v22
	v_pk_mul_f32 v[80:81], v[36:37], v[80:81]
	s_lshl_b32 s12, s12, 10
	v_add_f32_e32 v1, v80, v1
	v_add_f32_e32 v1, v81, v1
	v_mov_b32_e32 v80, v25
	v_mov_b32_e32 v81, v26
	v_pk_mul_f32 v[80:81], v[38:39], v[80:81]
	s_add_i32 s12, s12, 32
	v_add_f32_e32 v1, v80, v1
	v_add_f32_e32 v1, v81, v1
	v_mov_b32_e32 v80, v27
	v_mov_b32_e32 v81, v28
	v_pk_mul_f32 v[80:81], v[40:41], v[80:81]
	v_lshl_add_u32 v2, v0, 2, s12
	v_add_f32_e32 v1, v80, v1
	v_add_f32_e32 v1, v81, v1
	v_mov_b32_e32 v80, v29
	v_mov_b32_e32 v81, v30
	v_pk_mul_f32 v[80:81], v[42:43], v[80:81]
	v_add_u32_e32 v2, 0xffff8800, v2
	v_add_f32_e32 v1, v80, v1
	v_add_f32_e32 v1, v81, v1
	v_mov_b32_e32 v80, v31
	v_mov_b32_e32 v81, v32
	v_pk_mul_f32 v[80:81], v[44:45], v[80:81]
	s_nop 0
	v_add_f32_e32 v1, v80, v1
	v_add_f32_e32 v1, v81, v1
	v_mov_b32_e32 v80, v33
	v_mov_b32_e32 v81, v34
	v_pk_mul_f32 v[80:81], v[46:47], v[80:81]
	s_nop 0
	v_add_f32_e32 v1, v80, v1
	v_add_f32_e32 v1, v1, v81
	ds_write_b32 v2, v1

.LBB0_565:
	s_waitcnt vmcnt(0)
	v_mov_b32_e32 v146, v84
	v_mov_b32_e32 v177, v115
	v_mov_b32_e32 v147, v85
	v_mov_b32_e32 v178, v116
	v_mov_b32_e32 v148, v86
	v_mov_b32_e32 v179, v117
	v_mov_b32_e32 v149, v87
	v_mov_b32_e32 v180, v118
	v_mov_b32_e32 v150, v88
	v_mov_b32_e32 v181, v119
	v_mov_b32_e32 v151, v89
	v_mov_b32_e32 v182, v120
	v_mov_b32_e32 v152, v90
	v_mov_b32_e32 v183, v121
	v_mov_b32_e32 v153, v91
	v_mov_b32_e32 v184, v122
	v_mov_b32_e32 v154, v92
	v_mov_b32_e32 v185, v123
	v_mov_b32_e32 v155, v93
	v_mov_b32_e32 v186, v124
	v_mov_b32_e32 v156, v94
	v_mov_b32_e32 v187, v125
	v_mov_b32_e32 v157, v95
	v_mov_b32_e32 v188, v126
	v_mov_b32_e32 v158, v96
	v_mov_b32_e32 v189, v127
	v_mov_b32_e32 v159, v97
	v_mov_b32_e32 v190, v128
	v_mov_b32_e32 v160, v98
	v_mov_b32_e32 v191, v129
	v_mov_b32_e32 v161, v99
	v_mov_b32_e32 v192, v130
	v_mov_b32_e32 v162, v100
	v_mov_b32_e32 v193, v131
	v_mov_b32_e32 v163, v101
	v_mov_b32_e32 v194, v132
	v_mov_b32_e32 v164, v102
	v_mov_b32_e32 v195, v133
	v_mov_b32_e32 v165, v103
	v_mov_b32_e32 v196, v134
	v_mov_b32_e32 v166, v104
	v_mov_b32_e32 v197, v135
	v_mov_b32_e32 v167, v105
	v_mov_b32_e32 v198, v136
	v_mov_b32_e32 v168, v106
	v_mov_b32_e32 v199, v137
	v_mov_b32_e32 v169, v107
	v_mov_b32_e32 v200, v138
	v_mov_b32_e32 v170, v108
	v_mov_b32_e32 v201, v139
	v_mov_b32_e32 v171, v109
	v_mov_b32_e32 v202, v140
	v_mov_b32_e32 v172, v110
	v_mov_b32_e32 v203, v141
	v_mov_b32_e32 v173, v111
	v_mov_b32_e32 v204, v142
	v_mov_b32_e32 v174, v112
	v_mov_b32_e32 v205, v143
	v_mov_b32_e32 v175, v113
	v_mov_b32_e32 v206, v144
	v_mov_b32_e32 v176, v114
	v_mov_b32_e32 v207, v145
	s_cmp_gt_u32 s5, 62
	s_cbranch_scc1 .Lconf_pf_done_b
	s_add_i32 s98, s5, s10
	s_add_i32 s98, s98, s11
	s_add_i32 s98, s98, 31
	v_add_co_u32_e32 v208, vcc, 0x800, v48
	s_nop 1
	v_addc_co_u32_e32 v209, vcc, 0, v49, vcc
	s_max_i32 s99, s98, 0
	v_mad_u64_u32 v[210:211], s[42:43], s99, v233, v[208:209]
	global_load_ushort v84, v[210:211], off offset:2048
	global_load_ushort v115, v[210:211], off offset:1536
	s_add_i32 s98, s98, 1
	s_cmp_eq_u32 s5, 62
	s_cbranch_scc1 .Lconf_pf_done_b
	s_max_i32 s99, s98, 0
	v_mad_u64_u32 v[212:213], s[42:43], s99, v233, v[208:209]
	global_load_ushort v85, v[212:213], off offset:2048
	global_load_ushort v116, v[212:213], off offset:1536
	s_add_i32 s98, s98, 1
	s_max_i32 s99, s98, 0
	v_mad_u64_u32 v[210:211], s[42:43], s99, v233, v[208:209]
	global_load_ushort v86, v[210:211], off offset:2048
	global_load_ushort v117, v[210:211], off offset:1536
	s_add_i32 s98, s98, 1
	s_max_i32 s99, s98, 0
	v_mad_u64_u32 v[212:213], s[42:43], s99, v233, v[208:209]
	global_load_ushort v87, v[212:213], off offset:2048
	global_load_ushort v118, v[212:213], off offset:1536
	s_add_i32 s98, s98, 1
	s_max_i32 s99, s98, 0
	v_mad_u64_u32 v[210:211], s[42:43], s99, v233, v[208:209]
	global_load_ushort v88, v[210:211], off offset:2048
	global_load_ushort v119, v[210:211], off offset:1536
	s_add_i32 s98, s98, 1
	s_max_i32 s99, s98, 0
	v_mad_u64_u32 v[212:213], s[42:43], s99, v233, v[208:209]
	global_load_ushort v89, v[212:213], off offset:2048
	global_load_ushort v120, v[212:213], off offset:1536
	s_add_i32 s98, s98, 1
	s_max_i32 s99, s98, 0
	v_mad_u64_u32 v[210:211], s[42:43], s99, v233, v[208:209]
	global_load_ushort v90, v[210:211], off offset:2048
	global_load_ushort v121, v[210:211], off offset:1536
	s_add_i32 s98, s98, 1
	s_max_i32 s99, s98, 0
	v_mad_u64_u32 v[212:213], s[42:43], s99, v233, v[208:209]
	global_load_ushort v91, v[212:213], off offset:2048
	global_load_ushort v122, v[212:213], off offset:1536
	s_add_i32 s98, s98, 1
	s_max_i32 s99, s98, 0
	v_mad_u64_u32 v[210:211], s[42:43], s99, v233, v[208:209]
	global_load_ushort v92, v[210:211], off offset:2048
	global_load_ushort v123, v[210:211], off offset:1536
	s_add_i32 s98, s98, 1
	s_max_i32 s99, s98, 0
	v_mad_u64_u32 v[212:213], s[42:43], s99, v233, v[208:209]
	global_load_ushort v93, v[212:213], off offset:2048
	global_load_ushort v124, v[212:213], off offset:1536
	s_add_i32 s98, s98, 1
	s_max_i32 s99, s98, 0
	v_mad_u64_u32 v[210:211], s[42:43], s99, v233, v[208:209]
	global_load_ushort v94, v[210:211], off offset:2048
	global_load_ushort v125, v[210:211], off offset:1536
	s_add_i32 s98, s98, 1
	s_max_i32 s99, s98, 0
	v_mad_u64_u32 v[212:213], s[42:43], s99, v233, v[208:209]
	global_load_ushort v95, v[212:213], off offset:2048
	global_load_ushort v126, v[212:213], off offset:1536
	s_add_i32 s98, s98, 1
	s_max_i32 s99, s98, 0
	v_mad_u64_u32 v[210:211], s[42:43], s99, v233, v[208:209]
	global_load_ushort v96, v[210:211], off offset:2048
	global_load_ushort v127, v[210:211], off offset:1536
	s_add_i32 s98, s98, 1
	s_max_i32 s99, s98, 0
	v_mad_u64_u32 v[212:213], s[42:43], s99, v233, v[208:209]
	global_load_ushort v97, v[212:213], off offset:2048
	global_load_ushort v128, v[212:213], off offset:1536
	s_add_i32 s98, s98, 1
	s_max_i32 s99, s98, 0
	v_mad_u64_u32 v[210:211], s[42:43], s99, v233, v[208:209]
	global_load_ushort v98, v[210:211], off offset:2048
	global_load_ushort v129, v[210:211], off offset:1536
	s_add_i32 s98, s98, 1
	s_max_i32 s99, s98, 0
	v_mad_u64_u32 v[212:213], s[42:43], s99, v233, v[208:209]
	global_load_ushort v99, v[212:213], off offset:2048
	global_load_ushort v130, v[212:213], off offset:1536
	s_add_i32 s98, s98, 1
	s_max_i32 s99, s98, 0
	v_mad_u64_u32 v[210:211], s[42:43], s99, v233, v[208:209]
	global_load_ushort v100, v[210:211], off offset:2048
	global_load_ushort v131, v[210:211], off offset:1536
	s_add_i32 s98, s98, 1
	s_max_i32 s99, s98, 0
	v_mad_u64_u32 v[212:213], s[42:43], s99, v233, v[208:209]
	global_load_ushort v101, v[212:213], off offset:2048
	global_load_ushort v132, v[212:213], off offset:1536
	s_add_i32 s98, s98, 1
	s_max_i32 s99, s98, 0
	v_mad_u64_u32 v[210:211], s[42:43], s99, v233, v[208:209]
	global_load_ushort v102, v[210:211], off offset:2048
	global_load_ushort v133, v[210:211], off offset:1536
	s_add_i32 s98, s98, 1
	s_max_i32 s99, s98, 0
	v_mad_u64_u32 v[212:213], s[42:43], s99, v233, v[208:209]
	global_load_ushort v103, v[212:213], off offset:2048
	global_load_ushort v134, v[212:213], off offset:1536
	s_add_i32 s98, s98, 1
	s_max_i32 s99, s98, 0
	v_mad_u64_u32 v[210:211], s[42:43], s99, v233, v[208:209]
	global_load_ushort v104, v[210:211], off offset:2048
	global_load_ushort v135, v[210:211], off offset:1536
	s_add_i32 s98, s98, 1
	s_max_i32 s99, s98, 0
	v_mad_u64_u32 v[212:213], s[42:43], s99, v233, v[208:209]
	global_load_ushort v105, v[212:213], off offset:2048
	global_load_ushort v136, v[212:213], off offset:1536
	s_add_i32 s98, s98, 1
	s_max_i32 s99, s98, 0
	v_mad_u64_u32 v[210:211], s[42:43], s99, v233, v[208:209]
	global_load_ushort v106, v[210:211], off offset:2048
	global_load_ushort v137, v[210:211], off offset:1536
	s_add_i32 s98, s98, 1
	s_max_i32 s99, s98, 0
	v_mad_u64_u32 v[212:213], s[42:43], s99, v233, v[208:209]
	global_load_ushort v107, v[212:213], off offset:2048
	global_load_ushort v138, v[212:213], off offset:1536
	s_add_i32 s98, s98, 1
	s_max_i32 s99, s98, 0
	v_mad_u64_u32 v[210:211], s[42:43], s99, v233, v[208:209]
	global_load_ushort v108, v[210:211], off offset:2048
	global_load_ushort v139, v[210:211], off offset:1536
	s_add_i32 s98, s98, 1
	s_max_i32 s99, s98, 0
	v_mad_u64_u32 v[212:213], s[42:43], s99, v233, v[208:209]
	global_load_ushort v109, v[212:213], off offset:2048
	global_load_ushort v140, v[212:213], off offset:1536
	s_add_i32 s98, s98, 1
	s_max_i32 s99, s98, 0
	v_mad_u64_u32 v[210:211], s[42:43], s99, v233, v[208:209]
	global_load_ushort v110, v[210:211], off offset:2048
	global_load_ushort v141, v[210:211], off offset:1536
	s_add_i32 s98, s98, 1
	s_max_i32 s99, s98, 0
	v_mad_u64_u32 v[212:213], s[42:43], s99, v233, v[208:209]
	global_load_ushort v111, v[212:213], off offset:2048
	global_load_ushort v142, v[212:213], off offset:1536
	s_add_i32 s98, s98, 1
	s_max_i32 s99, s98, 0
	v_mad_u64_u32 v[210:211], s[42:43], s99, v233, v[208:209]
	global_load_ushort v112, v[210:211], off offset:2048
	global_load_ushort v143, v[210:211], off offset:1536
	s_add_i32 s98, s98, 1
	s_max_i32 s99, s98, 0
	v_mad_u64_u32 v[212:213], s[42:43], s99, v233, v[208:209]
	global_load_ushort v113, v[212:213], off offset:2048
	global_load_ushort v144, v[212:213], off offset:1536
	s_add_i32 s98, s98, 1
	s_max_i32 s99, s98, 0
	v_mad_u64_u32 v[210:211], s[42:43], s99, v233, v[208:209]
	global_load_ushort v114, v[210:211], off offset:2048
	global_load_ushort v145, v[210:211], off offset:1536
	s_add_i32 s98, s98, 1

.LBB0_568:
	s_add_i32 s12, s12, s11
	v_mad_u64_u32 v[80:81], s[12:13], s12, v233, v[48:49]
	v_add_co_u32_e32 v82, vcc, 0x1000, v80
	s_nop 1
	v_addc_co_u32_e32 v83, vcc, 0, v81, vcc
	v_mov_b32_e32 v1, v146
	v_mov_b32_e32 v2, v177
	s_waitcnt vmcnt(1)
	v_lshlrev_b32_e32 v1, 16, v1
	s_waitcnt vmcnt(0)
	v_lshlrev_b32_e32 v2, 16, v2
	v_mul_f32_e32 v4, v1, v2
	s_cmp_lt_u32 s5, 30
	s_cbranch_scc1 .LBB0_567

.LBB0_570:
	s_add_i32 s12, s5, 1
	s_add_i32 s13, s12, s10
	s_cmp_lt_i32 s13, s4
	s_cselect_b64 s[38:39], -1, 0
	s_cmp_ge_i32 s13, s7
	s_cselect_b64 s[42:43], -1, 0
	s_or_b64 s[38:39], s[38:39], s[42:43]
	v_mov_b32_e32 v5, 0
	s_and_b64 vcc, exec, s[38:39]
	s_cbranch_vccnz .LBB0_572
	s_add_i32 s13, s13, s11
	v_mad_u64_u32 v[80:81], s[38:39], s13, v233, v[48:49]
	v_add_co_u32_e32 v82, vcc, 0x1000, v80
	s_nop 1
	v_addc_co_u32_e32 v83, vcc, 0, v81, vcc
	v_mov_b32_e32 v1, v147
	v_mov_b32_e32 v2, v178
	s_waitcnt vmcnt(1)
	v_lshlrev_b32_e32 v1, 16, v1
	s_waitcnt vmcnt(0)
	v_lshlrev_b32_e32 v2, 16, v2
	v_mul_f32_e32 v5, v1, v2

.LBB0_574:
	s_cmpk_gt_u32 s5, 0x5b
	s_cbranch_scc1 .LBB0_579
	s_add_i32 s12, s5, 2
	s_add_i32 s13, s12, s10
	s_cmp_lt_i32 s13, s4
	s_cselect_b64 s[38:39], -1, 0
	s_cmp_ge_i32 s13, s7
	s_cselect_b64 s[42:43], -1, 0
	s_or_b64 s[38:39], s[38:39], s[42:43]
	v_mov_b32_e32 v6, 0
	s_and_b64 vcc, exec, s[38:39]
	s_cbranch_vccnz .LBB0_577
	s_add_i32 s13, s13, s11
	v_mad_u64_u32 v[80:81], s[38:39], s13, v233, v[48:49]
	v_add_co_u32_e32 v82, vcc, 0x1000, v80
	s_nop 1
	v_addc_co_u32_e32 v83, vcc, 0, v81, vcc
	v_mov_b32_e32 v1, v148
	v_mov_b32_e32 v2, v179
	s_waitcnt vmcnt(1)
	v_lshlrev_b32_e32 v1, 16, v1
	s_waitcnt vmcnt(0)
	v_lshlrev_b32_e32 v2, 16, v2
	v_mul_f32_e32 v6, v1, v2

.LBB0_579:
	s_cmpk_gt_u32 s5, 0x5a
	s_cbranch_scc1 .LBB0_584
	s_add_i32 s12, s5, 3
	s_add_i32 s13, s12, s10
	s_cmp_lt_i32 s13, s4
	s_cselect_b64 s[38:39], -1, 0
	s_cmp_ge_i32 s13, s7
	s_cselect_b64 s[42:43], -1, 0
	s_or_b64 s[38:39], s[38:39], s[42:43]
	v_mov_b32_e32 v7, 0
	s_and_b64 vcc, exec, s[38:39]
	s_cbranch_vccnz .LBB0_582
	s_add_i32 s13, s13, s11
	v_mad_u64_u32 v[80:81], s[38:39], s13, v233, v[48:49]
	v_add_co_u32_e32 v82, vcc, 0x1000, v80
	s_nop 1
	v_addc_co_u32_e32 v83, vcc, 0, v81, vcc
	v_mov_b32_e32 v1, v149
	v_mov_b32_e32 v2, v180
	s_waitcnt vmcnt(1)
	v_lshlrev_b32_e32 v1, 16, v1
	s_waitcnt vmcnt(0)
	v_lshlrev_b32_e32 v2, 16, v2
	v_mul_f32_e32 v7, v1, v2

.LBB0_584:
	s_cmpk_gt_u32 s5, 0x59
	s_cbranch_scc1 .LBB0_589
	s_add_i32 s12, s5, 4
	s_add_i32 s13, s12, s10
	s_cmp_lt_i32 s13, s4
	s_cselect_b64 s[38:39], -1, 0
	s_cmp_ge_i32 s13, s7
	s_cselect_b64 s[42:43], -1, 0
	s_or_b64 s[38:39], s[38:39], s[42:43]
	v_mov_b32_e32 v8, 0
	s_and_b64 vcc, exec, s[38:39]
	s_cbranch_vccnz .LBB0_587
	s_add_i32 s13, s13, s11
	v_mad_u64_u32 v[80:81], s[38:39], s13, v233, v[48:49]
	v_add_co_u32_e32 v82, vcc, 0x1000, v80
	s_nop 1
	v_addc_co_u32_e32 v83, vcc, 0, v81, vcc
	v_mov_b32_e32 v1, v150
	v_mov_b32_e32 v2, v181
	s_waitcnt vmcnt(1)
	v_lshlrev_b32_e32 v1, 16, v1
	s_waitcnt vmcnt(0)
	v_lshlrev_b32_e32 v2, 16, v2
	v_mul_f32_e32 v8, v1, v2

.LBB0_589:
	s_cmpk_gt_u32 s5, 0x58
	s_cbranch_scc1 .LBB0_594
	s_add_i32 s12, s5, 5
	s_add_i32 s13, s12, s10
	s_cmp_lt_i32 s13, s4
	s_cselect_b64 s[38:39], -1, 0
	s_cmp_ge_i32 s13, s7
	s_cselect_b64 s[42:43], -1, 0
	s_or_b64 s[38:39], s[38:39], s[42:43]
	v_mov_b32_e32 v9, 0
	s_and_b64 vcc, exec, s[38:39]
	s_cbranch_vccnz .LBB0_592
	s_add_i32 s13, s13, s11
	v_mad_u64_u32 v[80:81], s[38:39], s13, v233, v[48:49]
	v_add_co_u32_e32 v82, vcc, 0x1000, v80
	s_nop 1
	v_addc_co_u32_e32 v83, vcc, 0, v81, vcc
	v_mov_b32_e32 v1, v151
	v_mov_b32_e32 v2, v182
	s_waitcnt vmcnt(1)
	v_lshlrev_b32_e32 v1, 16, v1
	s_waitcnt vmcnt(0)
	v_lshlrev_b32_e32 v2, 16, v2
	v_mul_f32_e32 v9, v1, v2

.LBB0_594:
	s_cmpk_gt_u32 s5, 0x57
	s_cbranch_scc1 .LBB0_599
	s_add_i32 s12, s5, 6
	s_add_i32 s13, s12, s10
	s_cmp_lt_i32 s13, s4
	s_cselect_b64 s[38:39], -1, 0
	s_cmp_ge_i32 s13, s7
	s_cselect_b64 s[42:43], -1, 0
	s_or_b64 s[38:39], s[38:39], s[42:43]
	v_mov_b32_e32 v10, 0
	s_and_b64 vcc, exec, s[38:39]
	s_cbranch_vccnz .LBB0_597
	s_add_i32 s13, s13, s11
	v_mad_u64_u32 v[80:81], s[38:39], s13, v233, v[48:49]
	v_add_co_u32_e32 v82, vcc, 0x1000, v80
	s_nop 1
	v_addc_co_u32_e32 v83, vcc, 0, v81, vcc
	v_mov_b32_e32 v1, v152
	v_mov_b32_e32 v2, v183
	s_waitcnt vmcnt(1)
	v_lshlrev_b32_e32 v1, 16, v1
	s_waitcnt vmcnt(0)
	v_lshlrev_b32_e32 v2, 16, v2
	v_mul_f32_e32 v10, v1, v2

.LBB0_599:
	s_cmpk_gt_u32 s5, 0x56
	s_cbranch_scc1 .LBB0_604
	s_add_i32 s12, s5, 7
	s_add_i32 s13, s12, s10
	s_cmp_lt_i32 s13, s4
	s_cselect_b64 s[38:39], -1, 0
	s_cmp_ge_i32 s13, s7
	s_cselect_b64 s[42:43], -1, 0
	s_or_b64 s[38:39], s[38:39], s[42:43]
	v_mov_b32_e32 v11, 0
	s_and_b64 vcc, exec, s[38:39]
	s_cbranch_vccnz .LBB0_602
	s_add_i32 s13, s13, s11
	v_mad_u64_u32 v[80:81], s[38:39], s13, v233, v[48:49]
	v_add_co_u32_e32 v82, vcc, 0x1000, v80
	s_nop 1
	v_addc_co_u32_e32 v83, vcc, 0, v81, vcc
	v_mov_b32_e32 v1, v153
	v_mov_b32_e32 v2, v184
	s_waitcnt vmcnt(1)
	v_lshlrev_b32_e32 v1, 16, v1
	s_waitcnt vmcnt(0)
	v_lshlrev_b32_e32 v2, 16, v2
	v_mul_f32_e32 v11, v1, v2

.LBB0_604:
	s_cmpk_gt_u32 s5, 0x55
	s_cbranch_scc1 .LBB0_609
	s_add_i32 s12, s5, 8
	s_add_i32 s13, s12, s10
	s_cmp_lt_i32 s13, s4
	s_cselect_b64 s[38:39], -1, 0
	s_cmp_ge_i32 s13, s7
	s_cselect_b64 s[42:43], -1, 0
	s_or_b64 s[38:39], s[38:39], s[42:43]
	v_mov_b32_e32 v12, 0
	s_and_b64 vcc, exec, s[38:39]
	s_cbranch_vccnz .LBB0_607
	s_add_i32 s13, s13, s11
	v_mad_u64_u32 v[80:81], s[38:39], s13, v233, v[48:49]
	v_add_co_u32_e32 v82, vcc, 0x1000, v80
	s_nop 1
	v_addc_co_u32_e32 v83, vcc, 0, v81, vcc
	v_mov_b32_e32 v1, v154
	v_mov_b32_e32 v2, v185
	s_waitcnt vmcnt(1)
	v_lshlrev_b32_e32 v1, 16, v1
	s_waitcnt vmcnt(0)
	v_lshlrev_b32_e32 v2, 16, v2
	v_mul_f32_e32 v12, v1, v2

.LBB0_609:
	s_cmpk_gt_u32 s5, 0x54
	s_cbranch_scc1 .LBB0_614
	s_add_i32 s12, s5, 9
	s_add_i32 s13, s12, s10
	s_cmp_lt_i32 s13, s4
	s_cselect_b64 s[38:39], -1, 0
	s_cmp_ge_i32 s13, s7
	s_cselect_b64 s[42:43], -1, 0
	s_or_b64 s[38:39], s[38:39], s[42:43]
	v_mov_b32_e32 v13, 0
	s_and_b64 vcc, exec, s[38:39]
	s_cbranch_vccnz .LBB0_612
	s_add_i32 s13, s13, s11
	v_mad_u64_u32 v[80:81], s[38:39], s13, v233, v[48:49]
	v_add_co_u32_e32 v82, vcc, 0x1000, v80
	s_nop 1
	v_addc_co_u32_e32 v83, vcc, 0, v81, vcc
	v_mov_b32_e32 v1, v155
	v_mov_b32_e32 v2, v186
	s_waitcnt vmcnt(1)
	v_lshlrev_b32_e32 v1, 16, v1
	s_waitcnt vmcnt(0)
	v_lshlrev_b32_e32 v2, 16, v2
	v_mul_f32_e32 v13, v1, v2

.LBB0_614:
	s_cmpk_gt_u32 s5, 0x53
	s_cbranch_scc1 .LBB0_619
	s_add_i32 s12, s5, 10
	s_add_i32 s13, s12, s10
	s_cmp_lt_i32 s13, s4
	s_cselect_b64 s[38:39], -1, 0
	s_cmp_ge_i32 s13, s7
	s_cselect_b64 s[42:43], -1, 0
	s_or_b64 s[38:39], s[38:39], s[42:43]
	v_mov_b32_e32 v14, 0
	s_and_b64 vcc, exec, s[38:39]
	s_cbranch_vccnz .LBB0_617
	s_add_i32 s13, s13, s11
	v_mad_u64_u32 v[80:81], s[38:39], s13, v233, v[48:49]
	v_add_co_u32_e32 v82, vcc, 0x1000, v80
	s_nop 1
	v_addc_co_u32_e32 v83, vcc, 0, v81, vcc
	v_mov_b32_e32 v1, v156
	v_mov_b32_e32 v2, v187
	s_waitcnt vmcnt(1)
	v_lshlrev_b32_e32 v1, 16, v1
	s_waitcnt vmcnt(0)
	v_lshlrev_b32_e32 v2, 16, v2
	v_mul_f32_e32 v14, v1, v2

.LBB0_619:
	s_cmpk_gt_u32 s5, 0x52
	s_cbranch_scc1 .LBB0_624
	s_add_i32 s12, s5, 11
	s_add_i32 s13, s12, s10
	s_cmp_lt_i32 s13, s4
	s_cselect_b64 s[38:39], -1, 0
	s_cmp_ge_i32 s13, s7
	s_cselect_b64 s[42:43], -1, 0
	s_or_b64 s[38:39], s[38:39], s[42:43]
	v_mov_b32_e32 v15, 0
	s_and_b64 vcc, exec, s[38:39]
	s_cbranch_vccnz .LBB0_622
	s_add_i32 s13, s13, s11
	v_mad_u64_u32 v[80:81], s[38:39], s13, v233, v[48:49]
	v_add_co_u32_e32 v82, vcc, 0x1000, v80
	s_nop 1
	v_addc_co_u32_e32 v83, vcc, 0, v81, vcc
	v_mov_b32_e32 v1, v157
	v_mov_b32_e32 v2, v188
	s_waitcnt vmcnt(1)
	v_lshlrev_b32_e32 v1, 16, v1
	s_waitcnt vmcnt(0)
	v_lshlrev_b32_e32 v2, 16, v2
	v_mul_f32_e32 v15, v1, v2

.LBB0_624:
	s_cmpk_gt_u32 s5, 0x51
	s_cbranch_scc1 .LBB0_629
	s_add_i32 s12, s5, 12
	s_add_i32 s13, s12, s10
	s_cmp_lt_i32 s13, s4
	s_cselect_b64 s[38:39], -1, 0
	s_cmp_ge_i32 s13, s7
	s_cselect_b64 s[42:43], -1, 0
	s_or_b64 s[38:39], s[38:39], s[42:43]
	v_mov_b32_e32 v16, 0
	s_and_b64 vcc, exec, s[38:39]
	s_cbranch_vccnz .LBB0_627
	s_add_i32 s13, s13, s11
	v_mad_u64_u32 v[80:81], s[38:39], s13, v233, v[48:49]
	v_add_co_u32_e32 v82, vcc, 0x1000, v80
	s_nop 1
	v_addc_co_u32_e32 v83, vcc, 0, v81, vcc
	v_mov_b32_e32 v1, v158
	v_mov_b32_e32 v2, v189
	s_waitcnt vmcnt(1)
	v_lshlrev_b32_e32 v1, 16, v1
	s_waitcnt vmcnt(0)
	v_lshlrev_b32_e32 v2, 16, v2
	v_mul_f32_e32 v16, v1, v2

.LBB0_629:
	s_cmpk_gt_u32 s5, 0x50
	s_cbranch_scc1 .LBB0_634
	s_add_i32 s12, s5, 13
	s_add_i32 s13, s12, s10
	s_cmp_lt_i32 s13, s4
	s_cselect_b64 s[38:39], -1, 0
	s_cmp_ge_i32 s13, s7
	s_cselect_b64 s[42:43], -1, 0
	s_or_b64 s[38:39], s[38:39], s[42:43]
	v_mov_b32_e32 v17, 0
	s_and_b64 vcc, exec, s[38:39]
	s_cbranch_vccnz .LBB0_632
	s_add_i32 s13, s13, s11
	v_mad_u64_u32 v[80:81], s[38:39], s13, v233, v[48:49]
	v_add_co_u32_e32 v82, vcc, 0x1000, v80
	s_nop 1
	v_addc_co_u32_e32 v83, vcc, 0, v81, vcc
	v_mov_b32_e32 v1, v159
	v_mov_b32_e32 v2, v190
	s_waitcnt vmcnt(1)
	v_lshlrev_b32_e32 v1, 16, v1
	s_waitcnt vmcnt(0)
	v_lshlrev_b32_e32 v2, 16, v2
	v_mul_f32_e32 v17, v1, v2

.LBB0_634:
	s_cmpk_gt_u32 s5, 0x4f
	s_cbranch_scc1 .LBB0_639
	s_add_i32 s12, s5, 14
	s_add_i32 s13, s12, s10
	s_cmp_lt_i32 s13, s4
	s_cselect_b64 s[38:39], -1, 0
	s_cmp_ge_i32 s13, s7
	s_cselect_b64 s[42:43], -1, 0
	s_or_b64 s[38:39], s[38:39], s[42:43]
	v_mov_b32_e32 v18, 0
	s_and_b64 vcc, exec, s[38:39]
	s_cbranch_vccnz .LBB0_637
	s_add_i32 s13, s13, s11
	v_mad_u64_u32 v[80:81], s[38:39], s13, v233, v[48:49]
	v_add_co_u32_e32 v82, vcc, 0x1000, v80
	s_nop 1
	v_addc_co_u32_e32 v83, vcc, 0, v81, vcc
	v_mov_b32_e32 v1, v160
	v_mov_b32_e32 v2, v191
	s_waitcnt vmcnt(1)
	v_lshlrev_b32_e32 v1, 16, v1
	s_waitcnt vmcnt(0)
	v_lshlrev_b32_e32 v2, 16, v2
	v_mul_f32_e32 v18, v1, v2

.LBB0_639:
	s_cmpk_gt_u32 s5, 0x4e
	s_cbranch_scc1 .LBB0_644
	s_add_i32 s12, s5, s1
	s_cmp_lt_u32 s12, s4
	s_cselect_b64 s[38:39], -1, 0
	s_cmp_ge_u32 s12, s7
	s_cselect_b64 s[42:43], -1, 0
	s_or_b64 s[38:39], s[38:39], s[42:43]
	v_mov_b32_e32 v19, 0
	s_and_b64 vcc, exec, s[38:39]
	s_cbranch_vccnz .LBB0_642
	s_add_i32 s12, s12, s11
	v_mad_u64_u32 v[80:81], s[12:13], s12, v233, v[48:49]
	v_add_co_u32_e32 v82, vcc, 0x1000, v80
	s_nop 1
	v_addc_co_u32_e32 v83, vcc, 0, v81, vcc
	v_mov_b32_e32 v1, v161
	v_mov_b32_e32 v2, v192
	s_waitcnt vmcnt(1)
	v_lshlrev_b32_e32 v1, 16, v1
	s_waitcnt vmcnt(0)
	v_lshlrev_b32_e32 v2, 16, v2
	v_mul_f32_e32 v19, v1, v2

.LBB0_644:
	s_cmpk_gt_u32 s5, 0x4d
	s_cbranch_scc1 .LBB0_649
	s_add_i32 s12, s5, 16
	s_add_i32 s13, s12, s10
	s_cmp_lt_u32 s13, s4
	s_cselect_b64 s[38:39], -1, 0
	s_cmp_ge_u32 s13, s7
	s_cselect_b64 s[42:43], -1, 0
	s_or_b64 s[38:39], s[38:39], s[42:43]
	v_mov_b32_e32 v20, 0
	s_and_b64 vcc, exec, s[38:39]
	s_cbranch_vccnz .LBB0_647
	s_add_i32 s13, s13, s11
	v_mad_u64_u32 v[80:81], s[38:39], s13, v233, v[48:49]
	v_add_co_u32_e32 v82, vcc, 0x1000, v80
	s_nop 1
	v_addc_co_u32_e32 v83, vcc, 0, v81, vcc
	v_mov_b32_e32 v1, v162
	v_mov_b32_e32 v2, v193
	s_waitcnt vmcnt(1)
	v_lshlrev_b32_e32 v1, 16, v1
	s_waitcnt vmcnt(0)
	v_lshlrev_b32_e32 v2, 16, v2
	v_mul_f32_e32 v20, v1, v2

.LBB0_649:
	s_cmpk_gt_u32 s5, 0x4c
	s_cbranch_scc1 .LBB0_654
	s_add_i32 s12, s5, 17
	s_add_i32 s13, s12, s10
	s_cmp_lt_u32 s13, s4
	s_cselect_b64 s[38:39], -1, 0
	s_cmp_ge_u32 s13, s7
	s_cselect_b64 s[42:43], -1, 0
	s_or_b64 s[38:39], s[38:39], s[42:43]
	v_mov_b32_e32 v21, 0
	s_and_b64 vcc, exec, s[38:39]
	s_cbranch_vccnz .LBB0_652
	s_add_i32 s13, s13, s11
	v_mad_u64_u32 v[80:81], s[38:39], s13, v233, v[48:49]
	v_add_co_u32_e32 v82, vcc, 0x1000, v80
	s_nop 1
	v_addc_co_u32_e32 v83, vcc, 0, v81, vcc
	v_mov_b32_e32 v1, v163
	v_mov_b32_e32 v2, v194
	s_waitcnt vmcnt(1)
	v_lshlrev_b32_e32 v1, 16, v1
	s_waitcnt vmcnt(0)
	v_lshlrev_b32_e32 v2, 16, v2
	v_mul_f32_e32 v21, v1, v2

.LBB0_654:
	s_cmpk_gt_u32 s5, 0x4b
	s_cbranch_scc1 .LBB0_659
	s_add_i32 s12, s5, 18
	s_add_i32 s13, s12, s10
	s_cmp_lt_u32 s13, s4
	s_cselect_b64 s[38:39], -1, 0
	s_cmp_ge_u32 s13, s7
	s_cselect_b64 s[42:43], -1, 0
	s_or_b64 s[38:39], s[38:39], s[42:43]
	v_mov_b32_e32 v22, 0
	s_and_b64 vcc, exec, s[38:39]
	s_cbranch_vccnz .LBB0_657
	s_add_i32 s13, s13, s11
	v_mad_u64_u32 v[80:81], s[38:39], s13, v233, v[48:49]
	v_add_co_u32_e32 v82, vcc, 0x1000, v80
	s_nop 1
	v_addc_co_u32_e32 v83, vcc, 0, v81, vcc
	v_mov_b32_e32 v1, v164
	v_mov_b32_e32 v2, v195
	s_waitcnt vmcnt(1)
	v_lshlrev_b32_e32 v1, 16, v1
	s_waitcnt vmcnt(0)
	v_lshlrev_b32_e32 v2, 16, v2
	v_mul_f32_e32 v22, v1, v2

.LBB0_659:
	s_cmpk_gt_u32 s5, 0x4a
	s_cbranch_scc1 .LBB0_664
	s_add_i32 s12, s5, 19
	s_add_i32 s13, s12, s10
	s_cmp_lt_u32 s13, s4
	s_cselect_b64 s[38:39], -1, 0
	s_cmp_ge_u32 s13, s7
	s_cselect_b64 s[42:43], -1, 0
	s_or_b64 s[38:39], s[38:39], s[42:43]
	v_mov_b32_e32 v23, 0
	s_and_b64 vcc, exec, s[38:39]
	s_cbranch_vccnz .LBB0_662
	s_add_i32 s13, s13, s11
	v_mad_u64_u32 v[80:81], s[38:39], s13, v233, v[48:49]
	v_add_co_u32_e32 v82, vcc, 0x1000, v80
	s_nop 1
	v_addc_co_u32_e32 v83, vcc, 0, v81, vcc
	v_mov_b32_e32 v1, v165
	v_mov_b32_e32 v2, v196
	s_waitcnt vmcnt(1)
	v_lshlrev_b32_e32 v1, 16, v1
	s_waitcnt vmcnt(0)
	v_lshlrev_b32_e32 v2, 16, v2
	v_mul_f32_e32 v23, v1, v2

.LBB0_664:
	s_cmpk_gt_u32 s5, 0x49
	s_cbranch_scc1 .LBB0_669
	s_add_i32 s12, s5, 20
	s_add_i32 s13, s12, s10
	s_cmp_lt_u32 s13, s4
	s_cselect_b64 s[38:39], -1, 0
	s_cmp_ge_u32 s13, s7
	s_cselect_b64 s[42:43], -1, 0
	s_or_b64 s[38:39], s[38:39], s[42:43]
	v_mov_b32_e32 v24, 0
	s_and_b64 vcc, exec, s[38:39]
	s_cbranch_vccnz .LBB0_667
	s_add_i32 s13, s13, s11
	v_mad_u64_u32 v[80:81], s[38:39], s13, v233, v[48:49]
	v_add_co_u32_e32 v82, vcc, 0x1000, v80
	s_nop 1
	v_addc_co_u32_e32 v83, vcc, 0, v81, vcc
	v_mov_b32_e32 v1, v166
	v_mov_b32_e32 v2, v197
	s_waitcnt vmcnt(1)
	v_lshlrev_b32_e32 v1, 16, v1
	s_waitcnt vmcnt(0)
	v_lshlrev_b32_e32 v2, 16, v2
	v_mul_f32_e32 v24, v1, v2

.LBB0_669:
	s_cmpk_gt_u32 s5, 0x48
	s_cbranch_scc1 .LBB0_674
	s_add_i32 s12, s5, 21
	s_add_i32 s13, s12, s10
	s_cmp_lt_u32 s13, s4
	s_cselect_b64 s[38:39], -1, 0
	s_cmp_ge_u32 s13, s7
	s_cselect_b64 s[42:43], -1, 0
	s_or_b64 s[38:39], s[38:39], s[42:43]
	v_mov_b32_e32 v25, 0
	s_and_b64 vcc, exec, s[38:39]
	s_cbranch_vccnz .LBB0_672
	s_add_i32 s13, s13, s11
	v_mad_u64_u32 v[80:81], s[38:39], s13, v233, v[48:49]
	v_add_co_u32_e32 v82, vcc, 0x1000, v80
	s_nop 1
	v_addc_co_u32_e32 v83, vcc, 0, v81, vcc
	v_mov_b32_e32 v1, v167
	v_mov_b32_e32 v2, v198
	s_waitcnt vmcnt(1)
	v_lshlrev_b32_e32 v1, 16, v1
	s_waitcnt vmcnt(0)
	v_lshlrev_b32_e32 v2, 16, v2
	v_mul_f32_e32 v25, v1, v2

.LBB0_674:
	s_cmpk_gt_u32 s5, 0x47
	s_cbranch_scc1 .LBB0_679
	s_add_i32 s12, s5, 22
	s_add_i32 s13, s12, s10
	s_cmp_lt_u32 s13, s4
	s_cselect_b64 s[38:39], -1, 0
	s_cmp_ge_u32 s13, s7
	s_cselect_b64 s[42:43], -1, 0
	s_or_b64 s[38:39], s[38:39], s[42:43]
	v_mov_b32_e32 v26, 0
	s_and_b64 vcc, exec, s[38:39]
	s_cbranch_vccnz .LBB0_677
	s_add_i32 s13, s13, s11
	v_mad_u64_u32 v[80:81], s[38:39], s13, v233, v[48:49]
	v_add_co_u32_e32 v82, vcc, 0x1000, v80
	s_nop 1
	v_addc_co_u32_e32 v83, vcc, 0, v81, vcc
	v_mov_b32_e32 v1, v168
	v_mov_b32_e32 v2, v199
	s_waitcnt vmcnt(1)
	v_lshlrev_b32_e32 v1, 16, v1
	s_waitcnt vmcnt(0)
	v_lshlrev_b32_e32 v2, 16, v2
	v_mul_f32_e32 v26, v1, v2

.LBB0_679:
	s_cmpk_gt_u32 s5, 0x46
	s_cbranch_scc1 .LBB0_684
	s_add_i32 s12, s5, 23
	s_add_i32 s13, s12, s10
	s_cmp_lt_u32 s13, s4
	s_cselect_b64 s[38:39], -1, 0
	s_cmp_ge_u32 s13, s7
	s_cselect_b64 s[42:43], -1, 0
	s_or_b64 s[38:39], s[38:39], s[42:43]
	v_mov_b32_e32 v27, 0
	s_and_b64 vcc, exec, s[38:39]
	s_cbranch_vccnz .LBB0_682
	s_add_i32 s13, s13, s11
	v_mad_u64_u32 v[80:81], s[38:39], s13, v233, v[48:49]
	v_add_co_u32_e32 v82, vcc, 0x1000, v80
	s_nop 1
	v_addc_co_u32_e32 v83, vcc, 0, v81, vcc
	v_mov_b32_e32 v1, v169
	v_mov_b32_e32 v2, v200
	s_waitcnt vmcnt(1)
	v_lshlrev_b32_e32 v1, 16, v1
	s_waitcnt vmcnt(0)
	v_lshlrev_b32_e32 v2, 16, v2
	v_mul_f32_e32 v27, v1, v2

.LBB0_684:
	s_cmpk_gt_u32 s5, 0x45
	s_cbranch_scc1 .LBB0_689
	s_add_i32 s12, s5, 24
	s_add_i32 s13, s12, s10
	s_cmp_lt_u32 s13, s4
	s_cselect_b64 s[38:39], -1, 0
	s_cmp_ge_u32 s13, s7
	s_cselect_b64 s[42:43], -1, 0
	s_or_b64 s[38:39], s[38:39], s[42:43]
	v_mov_b32_e32 v28, 0
	s_and_b64 vcc, exec, s[38:39]
	s_cbranch_vccnz .LBB0_687
	s_add_i32 s13, s13, s11
	v_mad_u64_u32 v[80:81], s[38:39], s13, v233, v[48:49]
	v_add_co_u32_e32 v82, vcc, 0x1000, v80
	s_nop 1
	v_addc_co_u32_e32 v83, vcc, 0, v81, vcc
	v_mov_b32_e32 v1, v170
	v_mov_b32_e32 v2, v201
	s_waitcnt vmcnt(1)
	v_lshlrev_b32_e32 v1, 16, v1
	s_waitcnt vmcnt(0)
	v_lshlrev_b32_e32 v2, 16, v2
	v_mul_f32_e32 v28, v1, v2

.LBB0_689:
	s_cmpk_gt_u32 s5, 0x44
	s_cbranch_scc1 .LBB0_694
	s_add_i32 s12, s5, 25
	s_add_i32 s13, s12, s10
	s_cmp_lt_u32 s13, s4
	s_cselect_b64 s[38:39], -1, 0
	s_cmp_ge_u32 s13, s7
	s_cselect_b64 s[42:43], -1, 0
	s_or_b64 s[38:39], s[38:39], s[42:43]
	v_mov_b32_e32 v29, 0
	s_and_b64 vcc, exec, s[38:39]
	s_cbranch_vccnz .LBB0_692
	s_add_i32 s13, s13, s11
	v_mad_u64_u32 v[80:81], s[38:39], s13, v233, v[48:49]
	v_add_co_u32_e32 v82, vcc, 0x1000, v80
	s_nop 1
	v_addc_co_u32_e32 v83, vcc, 0, v81, vcc
	v_mov_b32_e32 v1, v171
	v_mov_b32_e32 v2, v202
	s_waitcnt vmcnt(1)
	v_lshlrev_b32_e32 v1, 16, v1
	s_waitcnt vmcnt(0)
	v_lshlrev_b32_e32 v2, 16, v2
	v_mul_f32_e32 v29, v1, v2

.LBB0_694:
	s_cmpk_gt_u32 s5, 0x43
	s_cbranch_scc1 .LBB0_699
	s_add_i32 s12, s5, 26
	s_add_i32 s13, s12, s10
	s_cmp_lt_u32 s13, s4
	s_cselect_b64 s[38:39], -1, 0
	s_cmp_ge_u32 s13, s7
	s_cselect_b64 s[42:43], -1, 0
	s_or_b64 s[38:39], s[38:39], s[42:43]
	v_mov_b32_e32 v30, 0
	s_and_b64 vcc, exec, s[38:39]
	s_cbranch_vccnz .LBB0_697
	s_add_i32 s13, s13, s11
	v_mad_u64_u32 v[80:81], s[38:39], s13, v233, v[48:49]
	v_add_co_u32_e32 v82, vcc, 0x1000, v80
	s_nop 1
	v_addc_co_u32_e32 v83, vcc, 0, v81, vcc
	v_mov_b32_e32 v1, v172
	v_mov_b32_e32 v2, v203
	s_waitcnt vmcnt(1)
	v_lshlrev_b32_e32 v1, 16, v1
	s_waitcnt vmcnt(0)
	v_lshlrev_b32_e32 v2, 16, v2
	v_mul_f32_e32 v30, v1, v2

.LBB0_699:
	s_cmpk_gt_u32 s5, 0x42
	s_cbranch_scc1 .LBB0_704
	s_add_i32 s12, s5, 27
	s_add_i32 s13, s12, s10
	s_cmp_lt_u32 s13, s4
	s_cselect_b64 s[38:39], -1, 0
	s_cmp_ge_u32 s13, s7
	s_cselect_b64 s[42:43], -1, 0
	s_or_b64 s[38:39], s[38:39], s[42:43]
	v_mov_b32_e32 v31, 0
	s_and_b64 vcc, exec, s[38:39]
	s_cbranch_vccnz .LBB0_702
	s_add_i32 s13, s13, s11
	v_mad_u64_u32 v[80:81], s[38:39], s13, v233, v[48:49]
	v_add_co_u32_e32 v82, vcc, 0x1000, v80
	s_nop 1
	v_addc_co_u32_e32 v83, vcc, 0, v81, vcc
	v_mov_b32_e32 v1, v173
	v_mov_b32_e32 v2, v204
	s_waitcnt vmcnt(1)
	v_lshlrev_b32_e32 v1, 16, v1
	s_waitcnt vmcnt(0)
	v_lshlrev_b32_e32 v2, 16, v2
	v_mul_f32_e32 v31, v1, v2

.LBB0_704:
	s_cmpk_gt_u32 s5, 0x41
	s_cbranch_scc1 .LBB0_709
	s_add_i32 s12, s5, 28
	s_add_i32 s13, s12, s10
	s_cmp_lt_u32 s13, s4
	s_cselect_b64 s[38:39], -1, 0
	s_cmp_ge_u32 s13, s7
	s_cselect_b64 s[42:43], -1, 0
	s_or_b64 s[38:39], s[38:39], s[42:43]
	v_mov_b32_e32 v32, 0
	s_and_b64 vcc, exec, s[38:39]
	s_cbranch_vccnz .LBB0_707
	s_add_i32 s13, s13, s11
	v_mad_u64_u32 v[80:81], s[38:39], s13, v233, v[48:49]
	v_add_co_u32_e32 v82, vcc, 0x1000, v80
	s_nop 1
	v_addc_co_u32_e32 v83, vcc, 0, v81, vcc
	v_mov_b32_e32 v1, v174
	v_mov_b32_e32 v2, v205
	s_waitcnt vmcnt(1)
	v_lshlrev_b32_e32 v1, 16, v1
	s_waitcnt vmcnt(0)
	v_lshlrev_b32_e32 v2, 16, v2
	v_mul_f32_e32 v32, v1, v2

.LBB0_709:
	s_cmp_gt_u32 s5, 64
	s_cbranch_scc1 .LBB0_714
	s_add_i32 s12, s5, 29
	s_add_i32 s13, s12, s10
	s_cmp_lt_u32 s13, s4
	s_cselect_b64 s[38:39], -1, 0
	s_cmp_ge_u32 s13, s7
	s_cselect_b64 s[42:43], -1, 0
	s_or_b64 s[38:39], s[38:39], s[42:43]
	v_mov_b32_e32 v33, 0
	s_and_b64 vcc, exec, s[38:39]
	s_cbranch_vccnz .LBB0_712
	s_add_i32 s13, s13, s11
	v_mad_u64_u32 v[80:81], s[38:39], s13, v233, v[48:49]
	v_add_co_u32_e32 v82, vcc, 0x1000, v80
	s_nop 1
	v_addc_co_u32_e32 v83, vcc, 0, v81, vcc
	v_mov_b32_e32 v1, v175
	v_mov_b32_e32 v2, v206
	s_waitcnt vmcnt(1)
	v_lshlrev_b32_e32 v1, 16, v1
	s_waitcnt vmcnt(0)
	v_lshlrev_b32_e32 v2, 16, v2
	v_mul_f32_e32 v33, v1, v2

.LBB0_714:
	s_cmp_gt_u32 s5, 63
	s_cbranch_scc1 .LBB0_564
	s_add_i32 s12, s5, 30
	s_add_i32 s13, s12, s10
	s_cmp_lt_u32 s13, s4
	s_cselect_b64 s[38:39], -1, 0
	s_cmp_ge_u32 s13, s7
	s_cselect_b64 s[42:43], -1, 0
	s_or_b64 s[38:39], s[38:39], s[42:43]
	v_mov_b32_e32 v34, 0
	s_and_b64 vcc, exec, s[38:39]
	s_cbranch_vccnz .LBB0_563
	s_add_i32 s13, s13, s11
	v_mad_u64_u32 v[34:35], s[38:39], s13, v233, v[48:49]
	v_add_co_u32_e32 v80, vcc, 0x1000, v34
	s_nop 1
	v_addc_co_u32_e32 v81, vcc, 0, v35, vcc
	v_mov_b32_e32 v1, v176
	v_mov_b32_e32 v2, v207
	s_waitcnt vmcnt(1)
	v_lshlrev_b32_e32 v1, 16, v1
	s_waitcnt vmcnt(0)
	v_lshlrev_b32_e32 v2, 16, v2
	v_mul_f32_e32 v34, v1, v2
	s_branch .LBB0_563

.LBB0_758:
	s_or_b64 exec, exec, s[0:1]
	v_lshl_add_u32 v0, v64, 1, 32
	s_waitcnt vmcnt(0)
	v_lshlrev_b32_e32 v64, 16, v46
	v_and_b32_e32 v65, 0xffff0000, v46
	v_lshlrev_b32_e32 v46, 16, v47
	v_and_b32_e32 v47, 0xffff0000, v47
	v_lshlrev_b32_e32 v68, 16, v37
	v_and_b32_e32 v69, 0xffff0000, v37
	v_pk_fma_f32 v[46:47], v[22:23], v[46:47], v[6:7]
	v_lshlrev_b32_e32 v66, 16, v36
	v_and_b32_e32 v67, 0xffff0000, v36
	v_lshlrev_b32_e32 v70, 16, v60
	v_and_b32_e32 v71, 0xffff0000, v60
	v_lshlrev_b32_e32 v60, 16, v61
	v_and_b32_e32 v61, 0xffff0000, v61
	v_pk_fma_f32 v[36:37], v[20:21], v[64:65], v[4:5]
	v_pk_fma_f32 v[46:47], v[18:19], v[68:69], v[46:47]
	v_lshlrev_b32_e32 v72, 16, v52
	v_and_b32_e32 v73, 0xffff0000, v52
	v_pk_fma_f32 v[36:37], v[16:17], v[66:67], v[36:37]
	v_lshlrev_b32_e32 v52, 16, v53
	v_and_b32_e32 v53, 0xffff0000, v53
	v_pk_fma_f32 v[46:47], v[14:15], v[60:61], v[46:47]
	v_pk_fma_f32 v[66:67], v[20:21], v[66:67], v[4:5]
	v_pk_fma_f32 v[68:69], v[22:23], v[68:69], v[6:7]
	v_pk_fma_f32 v[46:47], v[10:11], v[52:53], v[46:47]
	v_pk_fma_f32 v[66:67], v[16:17], v[70:71], v[66:67]
	v_pk_fma_f32 v[68:69], v[18:19], v[60:61], v[68:69]
	v_pk_fma_f32 v[36:37], v[12:13], v[70:71], v[36:37]
	v_cvt_pk_bf16_f32 v65, v46, v47
	v_lshlrev_b32_e32 v46, 16, v58
	v_and_b32_e32 v47, 0xffff0000, v58
	v_pk_fma_f32 v[66:67], v[12:13], v[72:73], v[66:67]
	v_lshlrev_b32_e32 v58, 16, v59
	v_and_b32_e32 v59, 0xffff0000, v59
	v_pk_fma_f32 v[68:69], v[14:15], v[52:53], v[68:69]
	v_pk_fma_f32 v[36:37], v[8:9], v[72:73], v[36:37]
	s_movk_i32 s9, 0x220
	v_pk_fma_f32 v[66:67], v[8:9], v[46:47], v[66:67]
	v_pk_fma_f32 v[68:69], v[10:11], v[58:59], v[68:69]
	v_cvt_pk_bf16_f32 v64, v36, v37
	v_mad_u64_u32 v[36:37], s[0:1], v63, s9, v[0:1]
	v_cvt_pk_bf16_f32 v66, v66, v67
	v_cvt_pk_bf16_f32 v67, v68, v69
	ds_write2_b64 v36, v[64:65], v[66:67] offset1:68
	v_pk_fma_f32 v[66:67], v[20:21], v[70:71], v[4:5]
	v_pk_fma_f32 v[60:61], v[22:23], v[60:61], v[6:7]
	v_pk_fma_f32 v[66:67], v[16:17], v[72:73], v[66:67]
	v_pk_fma_f32 v[60:61], v[18:19], v[52:53], v[60:61]
	v_lshlrev_b32_e32 v64, 16, v42
	v_and_b32_e32 v65, 0xffff0000, v42
	v_pk_fma_f32 v[66:67], v[12:13], v[46:47], v[66:67]
	v_lshlrev_b32_e32 v42, 16, v43
	v_and_b32_e32 v43, 0xffff0000, v43
	v_pk_fma_f32 v[60:61], v[14:15], v[58:59], v[60:61]
	v_pk_fma_f32 v[68:69], v[20:21], v[72:73], v[4:5]
	v_pk_fma_f32 v[52:53], v[22:23], v[52:53], v[6:7]
	v_pk_fma_f32 v[66:67], v[8:9], v[64:65], v[66:67]
	v_pk_fma_f32 v[60:61], v[10:11], v[42:43], v[60:61]
	v_pk_fma_f32 v[68:69], v[16:17], v[46:47], v[68:69]
	v_pk_fma_f32 v[52:53], v[18:19], v[58:59], v[52:53]
	v_cvt_pk_bf16_f32 v66, v66, v67
	v_cvt_pk_bf16_f32 v67, v60, v61
	v_lshlrev_b32_e32 v60, 16, v56
	v_and_b32_e32 v61, 0xffff0000, v56
	v_pk_fma_f32 v[68:69], v[12:13], v[64:65], v[68:69]
	v_lshlrev_b32_e32 v56, 16, v57
	v_and_b32_e32 v57, 0xffff0000, v57
	v_pk_fma_f32 v[52:53], v[14:15], v[42:43], v[52:53]
	v_pk_fma_f32 v[46:47], v[20:21], v[46:47], v[4:5]
	v_pk_fma_f32 v[58:59], v[22:23], v[58:59], v[6:7]
	v_pk_fma_f32 v[68:69], v[8:9], v[60:61], v[68:69]
	v_pk_fma_f32 v[52:53], v[10:11], v[56:57], v[52:53]
	v_pk_fma_f32 v[46:47], v[16:17], v[64:65], v[46:47]
	v_pk_fma_f32 v[58:59], v[18:19], v[42:43], v[58:59]
	v_cvt_pk_bf16_f32 v68, v68, v69
	v_cvt_pk_bf16_f32 v69, v52, v53
	v_lshlrev_b32_e32 v52, 16, v38
	v_and_b32_e32 v53, 0xffff0000, v38
	v_pk_fma_f32 v[46:47], v[12:13], v[60:61], v[46:47]
	v_lshlrev_b32_e32 v38, 16, v39
	v_and_b32_e32 v39, 0xffff0000, v39
	v_pk_fma_f32 v[58:59], v[14:15], v[56:57], v[58:59]
	v_pk_fma_f32 v[64:65], v[20:21], v[64:65], v[4:5]
	v_pk_fma_f32 v[42:43], v[22:23], v[42:43], v[6:7]
	v_pk_fma_f32 v[46:47], v[8:9], v[52:53], v[46:47]
	v_pk_fma_f32 v[58:59], v[10:11], v[38:39], v[58:59]
	v_pk_fma_f32 v[64:65], v[16:17], v[60:61], v[64:65]
	v_pk_fma_f32 v[42:43], v[18:19], v[56:57], v[42:43]
	v_cvt_pk_bf16_f32 v46, v46, v47
	v_cvt_pk_bf16_f32 v47, v58, v59
	v_lshlrev_b32_e32 v58, 16, v54
	v_and_b32_e32 v59, 0xffff0000, v54
	v_pk_fma_f32 v[64:65], v[12:13], v[52:53], v[64:65]
	v_lshlrev_b32_e32 v54, 16, v55
	v_and_b32_e32 v55, 0xffff0000, v55
	v_pk_fma_f32 v[42:43], v[14:15], v[38:39], v[42:43]
	v_pk_fma_f32 v[64:65], v[8:9], v[58:59], v[64:65]
	v_pk_fma_f32 v[42:43], v[10:11], v[54:55], v[42:43]
	v_cvt_pk_bf16_f32 v64, v64, v65
	v_cvt_pk_bf16_f32 v65, v42, v43
	v_add_u32_e32 v1, 0x800, v36
	ds_write2_b64 v1, v[46:47], v[64:65] offset0:16 offset1:84
	v_pk_fma_f32 v[46:47], v[20:21], v[60:61], v[4:5]
	v_pk_fma_f32 v[56:57], v[22:23], v[56:57], v[6:7]
	v_pk_fma_f32 v[46:47], v[16:17], v[52:53], v[46:47]
	v_pk_fma_f32 v[56:57], v[18:19], v[38:39], v[56:57]
	v_lshlrev_b32_e32 v42, 16, v34
	v_and_b32_e32 v43, 0xffff0000, v34
	v_pk_fma_f32 v[46:47], v[12:13], v[58:59], v[46:47]
	v_lshlrev_b32_e32 v34, 16, v35
	v_and_b32_e32 v35, 0xffff0000, v35
	v_pk_fma_f32 v[56:57], v[14:15], v[54:55], v[56:57]
	v_pk_fma_f32 v[52:53], v[20:21], v[52:53], v[4:5]
	v_pk_fma_f32 v[38:39], v[22:23], v[38:39], v[6:7]
	v_pk_fma_f32 v[46:47], v[8:9], v[42:43], v[46:47]
	v_pk_fma_f32 v[56:57], v[10:11], v[34:35], v[56:57]
	v_pk_fma_f32 v[52:53], v[16:17], v[58:59], v[52:53]
	v_pk_fma_f32 v[38:39], v[18:19], v[54:55], v[38:39]
	v_cvt_pk_bf16_f32 v46, v46, v47
	v_cvt_pk_bf16_f32 v47, v56, v57
	v_lshlrev_b32_e32 v56, 16, v50
	v_and_b32_e32 v57, 0xffff0000, v50
	v_pk_fma_f32 v[52:53], v[12:13], v[42:43], v[52:53]
	v_lshlrev_b32_e32 v50, 16, v51
	v_and_b32_e32 v51, 0xffff0000, v51
	v_pk_fma_f32 v[38:39], v[14:15], v[34:35], v[38:39]
	v_pk_fma_f32 v[52:53], v[8:9], v[56:57], v[52:53]
	v_pk_fma_f32 v[38:39], v[10:11], v[50:51], v[38:39]
	v_cvt_pk_bf16_f32 v52, v52, v53
	v_cvt_pk_bf16_f32 v53, v38, v39
	ds_write2_b64 v1, v[46:47], v[52:53] offset0:152 offset1:220
	v_pk_fma_f32 v[46:47], v[20:21], v[58:59], v[4:5]
	v_pk_fma_f32 v[52:53], v[22:23], v[54:55], v[6:7]
	v_pk_fma_f32 v[46:47], v[16:17], v[42:43], v[46:47]
	v_pk_fma_f32 v[52:53], v[18:19], v[34:35], v[52:53]
	v_lshlrev_b32_e32 v38, 16, v32
	v_and_b32_e32 v39, 0xffff0000, v32
	v_pk_fma_f32 v[46:47], v[12:13], v[56:57], v[46:47]
	v_lshlrev_b32_e32 v32, 16, v33
	v_and_b32_e32 v33, 0xffff0000, v33
	v_pk_fma_f32 v[52:53], v[14:15], v[50:51], v[52:53]
	v_pk_fma_f32 v[42:43], v[20:21], v[42:43], v[4:5]
	v_pk_fma_f32 v[34:35], v[22:23], v[34:35], v[6:7]
	v_pk_fma_f32 v[46:47], v[8:9], v[38:39], v[46:47]
	v_pk_fma_f32 v[52:53], v[10:11], v[32:33], v[52:53]
	v_pk_fma_f32 v[42:43], v[16:17], v[56:57], v[42:43]
	v_pk_fma_f32 v[34:35], v[18:19], v[50:51], v[34:35]
	v_cvt_pk_bf16_f32 v46, v46, v47
	v_cvt_pk_bf16_f32 v47, v52, v53
	v_lshlrev_b32_e32 v52, 16, v48
	v_and_b32_e32 v53, 0xffff0000, v48
	v_pk_fma_f32 v[42:43], v[12:13], v[38:39], v[42:43]
	v_lshlrev_b32_e32 v48, 16, v49
	v_and_b32_e32 v49, 0xffff0000, v49
	v_pk_fma_f32 v[34:35], v[14:15], v[32:33], v[34:35]
	v_pk_fma_f32 v[42:43], v[8:9], v[52:53], v[42:43]
	v_pk_fma_f32 v[34:35], v[10:11], v[48:49], v[34:35]
	v_cvt_pk_bf16_f32 v42, v42, v43
	v_cvt_pk_bf16_f32 v43, v34, v35
	v_add_u32_e32 v1, 0x1000, v36
	ds_write2_b64 v1, v[46:47], v[42:43] offset0:32 offset1:100
	v_pk_fma_f32 v[42:43], v[20:21], v[56:57], v[4:5]
	v_pk_fma_f32 v[46:47], v[22:23], v[50:51], v[6:7]
	v_pk_fma_f32 v[42:43], v[16:17], v[38:39], v[42:43]
	v_pk_fma_f32 v[46:47], v[18:19], v[32:33], v[46:47]
	v_lshlrev_b32_e32 v34, 16, v30
	v_and_b32_e32 v35, 0xffff0000, v30
	v_pk_fma_f32 v[42:43], v[12:13], v[52:53], v[42:43]
	v_lshlrev_b32_e32 v30, 16, v31
	v_and_b32_e32 v31, 0xffff0000, v31
	v_pk_fma_f32 v[46:47], v[14:15], v[48:49], v[46:47]
	v_pk_fma_f32 v[38:39], v[20:21], v[38:39], v[4:5]
	v_pk_fma_f32 v[32:33], v[22:23], v[32:33], v[6:7]
	v_pk_fma_f32 v[42:43], v[8:9], v[34:35], v[42:43]
	v_pk_fma_f32 v[46:47], v[10:11], v[30:31], v[46:47]
	v_pk_fma_f32 v[38:39], v[16:17], v[52:53], v[38:39]
	v_pk_fma_f32 v[32:33], v[18:19], v[48:49], v[32:33]
	v_cvt_pk_bf16_f32 v42, v42, v43
	v_cvt_pk_bf16_f32 v43, v46, v47
	v_lshlrev_b32_e32 v46, 16, v44
	v_and_b32_e32 v47, 0xffff0000, v44
	v_pk_fma_f32 v[38:39], v[12:13], v[34:35], v[38:39]
	v_lshlrev_b32_e32 v44, 16, v45
	v_and_b32_e32 v45, 0xffff0000, v45
	v_pk_fma_f32 v[32:33], v[14:15], v[30:31], v[32:33]
	v_pk_fma_f32 v[38:39], v[8:9], v[46:47], v[38:39]
	v_pk_fma_f32 v[32:33], v[10:11], v[44:45], v[32:33]
	v_cvt_pk_bf16_f32 v38, v38, v39
	v_cvt_pk_bf16_f32 v39, v32, v33
	ds_write2_b64 v1, v[42:43], v[38:39] offset0:168 offset1:236
	v_pk_fma_f32 v[38:39], v[20:21], v[52:53], v[4:5]
	v_pk_fma_f32 v[42:43], v[22:23], v[48:49], v[6:7]
	v_pk_fma_f32 v[38:39], v[16:17], v[34:35], v[38:39]
	v_pk_fma_f32 v[42:43], v[18:19], v[30:31], v[42:43]
	v_lshlrev_b32_e32 v32, 16, v28
	v_and_b32_e32 v33, 0xffff0000, v28
	v_pk_fma_f32 v[38:39], v[12:13], v[46:47], v[38:39]
	v_lshlrev_b32_e32 v28, 16, v29
	v_and_b32_e32 v29, 0xffff0000, v29
	v_pk_fma_f32 v[42:43], v[14:15], v[44:45], v[42:43]
	v_pk_fma_f32 v[34:35], v[20:21], v[34:35], v[4:5]
	v_pk_fma_f32 v[30:31], v[22:23], v[30:31], v[6:7]
	v_pk_fma_f32 v[38:39], v[8:9], v[32:33], v[38:39]
	v_pk_fma_f32 v[42:43], v[10:11], v[28:29], v[42:43]
	v_pk_fma_f32 v[34:35], v[16:17], v[46:47], v[34:35]
	v_pk_fma_f32 v[30:31], v[18:19], v[44:45], v[30:31]
	v_cvt_pk_bf16_f32 v38, v38, v39
	v_cvt_pk_bf16_f32 v39, v42, v43
	v_lshlrev_b32_e32 v42, 16, v40
	v_and_b32_e32 v43, 0xffff0000, v40
	v_pk_fma_f32 v[34:35], v[12:13], v[32:33], v[34:35]
	v_lshlrev_b32_e32 v40, 16, v41
	v_and_b32_e32 v41, 0xffff0000, v41
	v_pk_fma_f32 v[30:31], v[14:15], v[28:29], v[30:31]
	v_pk_fma_f32 v[34:35], v[8:9], v[42:43], v[34:35]
	v_pk_fma_f32 v[30:31], v[10:11], v[40:41], v[30:31]
	v_cvt_pk_bf16_f32 v34, v34, v35
	v_cvt_pk_bf16_f32 v35, v30, v31
	v_add_u32_e32 v1, 0x1800, v36
	ds_write2_b64 v1, v[38:39], v[34:35] offset0:48 offset1:116
	v_pk_fma_f32 v[34:35], v[20:21], v[46:47], v[4:5]
	v_pk_fma_f32 v[38:39], v[22:23], v[44:45], v[6:7]
	v_pk_fma_f32 v[34:35], v[16:17], v[32:33], v[34:35]
	v_pk_fma_f32 v[38:39], v[18:19], v[28:29], v[38:39]
	v_lshlrev_b32_e32 v30, 16, v26
	v_and_b32_e32 v31, 0xffff0000, v26
	v_pk_fma_f32 v[34:35], v[12:13], v[42:43], v[34:35]
	v_lshlrev_b32_e32 v26, 16, v27
	v_and_b32_e32 v27, 0xffff0000, v27
	v_pk_fma_f32 v[38:39], v[14:15], v[40:41], v[38:39]
	v_pk_fma_f32 v[34:35], v[8:9], v[30:31], v[34:35]
	v_pk_fma_f32 v[38:39], v[10:11], v[26:27], v[38:39]
	v_cvt_pk_bf16_f32 v34, v34, v35
	v_cvt_pk_bf16_f32 v35, v38, v39
	ds_write2_b64 v36, v[66:67], v[68:69] offset0:136 offset1:204
	ds_write_b64 v36, v[34:35] offset:7616
	v_mov_b32_e32 v34, v20
	v_mov_b32_e32 v35, v16
	v_mov_b32_e32 v36, v32
	v_mov_b32_e32 v37, v42
	v_mov_b32_e32 v16, v21
	v_mov_b32_e32 v42, v33
	v_mov_b32_e32 v20, v22
	v_mov_b32_e32 v21, v18
	v_mov_b32_e32 v32, v28
	v_mov_b32_e32 v33, v40
	v_mov_b32_e32 v18, v23
	v_mov_b32_e32 v40, v29
	v_lshlrev_b32_e32 v23, 16, v24
	v_mov_b32_e32 v28, v12
	v_mov_b32_e32 v29, v8
	v_mov_b32_e32 v22, v30
	v_pk_mul_f32 v[34:35], v[34:35], v[36:37]
	v_pk_mul_f32 v[16:17], v[16:17], v[42:43]
	v_pk_mul_f32 v[22:23], v[28:29], v[22:23]
	v_and_b32_e32 v29, 0xffff0000, v24
	v_mov_b32_e32 v8, v13
	v_mov_b32_e32 v28, v31
	v_pk_mul_f32 v[8:9], v[8:9], v[28:29]
	v_mov_b32_e32 v28, v14
	v_mov_b32_e32 v29, v10
	v_mov_b32_e32 v10, v15
	v_mov_b32_e32 v14, v34
	v_mov_b32_e32 v15, v16
	v_pk_add_f32 v[4:5], v[4:5], v[14:15]
	v_mov_b32_e32 v16, v35
	v_pk_add_f32 v[4:5], v[4:5], v[16:17]
	v_mov_b32_e32 v14, v22
	v_mov_b32_e32 v15, v8
	v_pk_mul_f32 v[20:21], v[20:21], v[32:33]
	v_pk_mul_f32 v[18:19], v[18:19], v[40:41]
	v_pk_add_f32 v[4:5], v[4:5], v[14:15]
	v_mov_b32_e32 v8, v23
	v_lshlrev_b32_e32 v13, 16, v25
	v_mov_b32_e32 v12, v26
	v_and_b32_e32 v25, 0xffff0000, v25
	v_mov_b32_e32 v24, v27
	v_pk_add_f32 v[4:5], v[4:5], v[8:9]
	v_mov_b32_e32 v8, v20
	v_mov_b32_e32 v9, v18
	v_pk_mul_f32 v[12:13], v[28:29], v[12:13]
	v_pk_mul_f32 v[10:11], v[10:11], v[24:25]
	v_pk_add_f32 v[6:7], v[6:7], v[8:9]
	v_mov_b32_e32 v18, v21
	v_pk_add_f32 v[6:7], v[6:7], v[18:19]
	v_mov_b32_e32 v8, v12
	v_mov_b32_e32 v9, v10
	v_pk_add_f32 v[6:7], v[6:7], v[8:9]
	v_mov_b32_e32 v10, v13
	v_pk_add_f32 v[6:7], v[6:7], v[10:11]
	v_or_b32_e32 v1, 15, v62
	v_cvt_pk_bf16_f32 v4, v4, v5
	v_cvt_pk_bf16_f32 v5, v6, v7
	v_mad_u64_u32 v[0:1], s[0:1], v1, s9, v[0:1]
	ds_write_b64 v0, v[4:5]
	v_mov_b32_e32 v0, v222
	s_waitcnt lgkmcnt(0)
	s_barrier
	v_readlane_b32 s0, v252, 46
	v_ashrrev_i32_e32 v1, 6, v0
	v_bfe_u32 v81, v0, 4, 2
	v_add_u32_e32 v4, s0, v1
	v_readlane_b32 s0, v252, 47
	v_ashrrev_i32_e32 v5, 31, v4
	v_lshlrev_b64 v[4:5], 13, v[4:5]
	v_add_u32_e32 v6, s0, v1
	v_ashrrev_i32_e32 v7, 31, v6
	v_and_b32_e32 v72, 0xffffffc0, v0
	v_and_b32_e32 v80, 15, v0
	v_lshl_add_u64 v[4:5], s[84:85], 0, v[4:5]
	v_lshlrev_b64 v[6:7], 13, v[6:7]
	v_lshlrev_b32_e32 v2, 4, v81
	v_ashrrev_i32_e32 v73, 31, v72
	v_readlane_b32 s0, v252, 48
	v_lshl_add_u64 v[6:7], s[84:85], 0, v[6:7]
	v_lshl_add_u64 v[4:5], v[4:5], 0, v[2:3]
	v_lshlrev_b32_e32 v8, 7, v80
	v_mov_b32_e32 v9, v3
	v_lshlrev_b64 v[74:75], 2, v[72:73]
	v_readlane_b32 s1, v252, 49
	v_lshl_add_u64 v[6:7], v[6:7], 0, v[2:3]
	v_lshl_add_u64 v[10:11], v[4:5], 0, v[8:9]
	v_lshl_add_u64 v[76:77], s[0:1], 0, v[74:75]
	v_readlane_b32 s0, v252, 50
	v_lshl_add_u64 v[12:13], v[6:7], 0, v[8:9]
	global_load_dwordx4 v[56:59], v[10:11], off
	global_load_dwordx4 v[52:55], v[12:13], off
	global_load_dwordx4 v[64:67], v[10:11], off offset:64
	global_load_dwordx4 v[60:63], v[12:13], off offset:64
	global_load_dwordx4 v[40:43], v[10:11], off offset:2048
	global_load_dwordx4 v[36:39], v[12:13], off offset:2048
	global_load_dwordx4 v[48:51], v[10:11], off offset:2112
	global_load_dwordx4 v[44:47], v[12:13], off offset:2112
	v_or_b32_e32 v10, 0x1000, v8
	v_mov_b32_e32 v11, v3
	v_readlane_b32 s1, v252, 51
	v_lshl_add_u64 v[12:13], v[4:5], 0, v[10:11]
	v_or_b32_e32 v8, 0x1800, v8
	v_lshl_add_u64 v[68:69], s[0:1], 0, v[74:75]
	v_lshl_add_u64 v[10:11], v[6:7], 0, v[10:11]
	global_load_dwordx4 v[24:27], v[12:13], off
	global_load_dwordx4 v[20:23], v[10:11], off
	global_load_dwordx4 v[32:35], v[12:13], off offset:64
	global_load_dwordx4 v[28:31], v[10:11], off offset:64
	v_lshl_add_u64 v[12:13], v[4:5], 0, v[8:9]
	v_lshl_add_u64 v[14:15], v[6:7], 0, v[8:9]
	v_lshl_add_u64 v[78:79], v[68:69], 0, v[2:3]
	global_load_dwordx4 v[8:11], v[12:13], off
	global_load_dwordx4 v[4:7], v[14:15], off
	global_load_dwordx4 v[16:19], v[12:13], off offset:64
	s_nop 0
	global_load_dwordx4 v[12:15], v[14:15], off offset:64
	v_readlane_b32 s0, v252, 52
	v_readlane_b32 s1, v252, 53
	s_movk_i32 s10, 0x88
	v_lshl_add_u64 v[152:153], v[76:77], 0, v[2:3]
	v_lshlrev_b32_e32 v82, 3, v81
	v_readlane_b32 s7, v252, 11
	v_readlane_b32 s8, v252, 12
	s_waitcnt vmcnt(0)
	s_lshl_b32 s98, s16, 11
	s_add_u32 s98, s98, 0x8000
	s_add_u32 s98, s30, s98
	s_addc_u32 s99, s31, 0
	v_lshrrev_b32_e32 v172, 4, v222
	v_and_b32_e32 v171, 3, v172
	v_lshrrev_b32_e32 v172, 2, v172
	v_lshlrev_b32_e32 v171, 4, v171
	v_lshl_or_b32 v172, v172, 8, v171
	global_load_dword v1, v172, s[98:99]
	global_load_dword v158, v172, s[98:99] offset:4
	global_load_dword v159, v172, s[98:99] offset:8
	global_load_dword v160, v172, s[98:99] offset:12
	global_load_dword v161, v172, s[98:99] offset:64
	global_load_dword v162, v172, s[98:99] offset:68
	global_load_dword v164, v172, s[98:99] offset:72
	global_load_dword v166, v172, s[98:99] offset:76
	global_load_dword v163, v172, s[98:99] offset:128
	global_load_dword v165, v172, s[98:99] offset:132
	global_load_dword v167, v172, s[98:99] offset:136
	global_load_dword v168, v172, s[98:99] offset:140
	global_load_dword v169, v172, s[98:99] offset:192
	global_load_dword v170, v172, s[98:99] offset:196
	global_load_dword v171, v172, s[98:99] offset:200
	global_load_dword v172, v172, s[98:99] offset:204
	v_lshl_or_b32 v96, v81, 2, v72
	v_lshlrev_b32_e32 v97, 3, v80
	v_lshl_add_u64 v[68:69], s[0:1], 0, v[74:75]
	v_lshl_add_u64 v[154:155], v[68:69], 0, v[2:3]
	v_mul_lo_u32 v69, v0, s10
	v_lshl_add_u32 v68, v72, 1, 32
	v_add_u32_e32 v112, 32, v69
	v_mul_u32_u24_e32 v69, 0x220, v80
	v_add3_u32 v180, v68, v69, v2
	ds_read_b128 v[68:71], v180
	ds_read_b128 v[72:75], v180 offset:64
	global_load_dwordx4 v[190:193], v[154:155], off
	global_load_dwordx4 v[206:209], v[152:153], off
	global_load_dwordx4 v[194:197], v[154:155], off offset:64
	global_load_dwordx4 v[210:213], v[152:153], off offset:64
	global_load_dwordx4 v[198:201], v[154:155], off offset:128
	global_load_dwordx4 v[214:217], v[152:153], off offset:128
	global_load_dwordx4 v[202:205], v[154:155], off offset:192
	global_load_dwordx4 v[240:243], v[152:153], off offset:192
	s_waitcnt vmcnt(0)
	v_mov_b32_e32 v84, v190
	v_mov_b32_e32 v85, v191
	v_mov_b32_e32 v86, v192
	v_mov_b32_e32 v87, v193
	v_mov_b32_e32 v88, v206
	v_mov_b32_e32 v89, v207
	v_mov_b32_e32 v90, v208
	v_mov_b32_e32 v91, v209
	s_waitcnt lgkmcnt(1)
	v_mfma_f32_16x16x32_bf16 v[76:79], v[56:59], v[68:71], 0
	v_sub_u32_e32 v2, v180, v82
	ds_read_b64 v[92:93], v2
	v_add_u32_e32 v173, 0x8800, v112
	s_waitcnt lgkmcnt(1)
	v_mfma_f32_16x16x32_bf16 v[80:83], v[64:67], v[72:75], v[76:79]
	v_add_u32_e32 v185, 0x8810, v112
	v_add_u32_e32 v184, 0x8820, v112
	s_waitcnt lgkmcnt(0)
	v_lshlrev_b32_e32 v95, 16, v92
	v_mfma_f32_16x16x32_bf16 v[76:79], v[52:55], v[68:71], 0
	v_and_b32_e32 v98, 0xffff0000, v92
	v_lshlrev_b32_e32 v99, 16, v93
	v_and_b32_e32 v93, 0xffff0000, v93
	v_mfma_f32_16x16x32_bf16 v[76:79], v[60:63], v[72:75], v[76:79]
	v_add_u32_e32 v175, 0x8860, v112
	v_add_u32_e32 v179, 0x8830, v112
	v_add_u32_e32 v176, 0x8840, v112
	v_add_u32_e32 v178, 0x8850, v112
	v_add_u32_e32 v177, 0x8870, v112
	s_mul_i32 s0, s4, 0x88
	s_add_i32 s0, s0, s5
	s_lshl_b32 s0, s0, 11
	s_add_u32 s4, s7, s0
	s_addc_u32 s5, s8, 0
	v_readlane_b32 s1, v252, 54
	s_add_i32 s0, s0, 0x22000
	s_add_u32 s0, s7, s0
	s_waitcnt vmcnt(1)
	v_add_f32_e32 v80, v80, v84
	v_mul_f32_e32 v80, 0xbfb8aa3b, v80
	v_exp_f32_e32 v80, v80
	s_waitcnt vmcnt(0)
	v_add_f32_e32 v76, v76, v88
	v_mul_f32_e32 v76, 0xbfb8aa3b, v76
	v_exp_f32_e32 v76, v76
	v_add_f32_e32 v80, 1.0, v80
	v_rcp_f32_e32 v80, v80
	v_add_f32_e32 v77, v77, v89
	v_add_f32_e32 v76, 1.0, v76
	v_rcp_f32_e32 v76, v76
	v_mul_f32_e32 v80, 0xc1000000, v80
	s_waitcnt vmcnt(0)
	v_mul_f32_e32 v80, v80, v1
	v_mul_f32_e32 v80, 0x3fb8aa3b, v80
	v_exp_f32_e32 v94, v80
	v_mul_f32_e32 v77, 0xbfb8aa3b, v77
	v_exp_f32_e32 v77, v77
	v_add_f32_e32 v79, v79, v91
	v_sub_f32_e32 v80, 1.0, v94
	v_add_f32_e32 v84, 1.0, v94
	v_mul_f32_e32 v80, v80, v84
	v_max_f32_e32 v80, 0, v80
	v_sqrt_f32_e32 v80, v80
	v_add_f32_e32 v77, 1.0, v77
	v_rcp_f32_e32 v77, v77
	v_mul_f32_e32 v79, 0xbfb8aa3b, v79
	v_mul_f32_e32 v76, v76, v80
	v_mul_f32_e32 v95, v76, v95
	v_mul_lo_u32 v76, v96, s10
	v_add3_u32 v92, 32, v97, v76
	v_add_f32_e32 v76, v81, v85
	v_mul_f32_e32 v76, 0xbfb8aa3b, v76
	v_exp_f32_e32 v76, v76
	v_add_u32_e32 v181, 0x8800, v92
	v_exp_f32_e32 v79, v79
	v_add_u32_e32 v182, 0x9000, v92
	v_add_f32_e32 v76, 1.0, v76
	v_rcp_f32_e32 v76, v76
	v_add_f32_e32 v79, 1.0, v79
	v_rcp_f32_e32 v79, v79
	v_add_u32_e32 v183, 0x9800, v92
	v_mul_f32_e32 v76, 0xc1000000, v76
	v_mul_f32_e32 v76, v76, v158
	v_mul_f32_e32 v76, 0x3fb8aa3b, v76
	v_exp_f32_e32 v76, v76
	v_add_u32_e32 v174, 0xa000, v92
	v_sub_f32_e32 v80, 1.0, v76
	v_add_f32_e32 v81, 1.0, v76
	v_mul_f32_e32 v80, v80, v81
	v_max_f32_e32 v80, 0, v80
	v_sqrt_f32_e32 v80, v80
	s_nop 0
	v_mul_f32_e32 v77, v77, v80
	v_mul_f32_e32 v77, v77, v98
	ds_write2_b64 v181, v[94:95], v[76:77] offset1:17
	v_add_f32_e32 v76, v82, v86
	v_mul_f32_e32 v76, 0xbfb8aa3b, v76
	v_exp_f32_e32 v76, v76
	v_add_f32_e32 v77, v78, v90
	v_mul_f32_e32 v77, 0xbfb8aa3b, v77
	v_exp_f32_e32 v77, v77
	v_add_f32_e32 v76, 1.0, v76
	v_rcp_f32_e32 v76, v76
	v_add_f32_e32 v77, 1.0, v77
	v_rcp_f32_e32 v77, v77
	v_mul_f32_e32 v76, 0xc1000000, v76
	v_mul_f32_e32 v76, v76, v159
	v_mul_f32_e32 v76, 0x3fb8aa3b, v76
	v_exp_f32_e32 v76, v76
	s_nop 0
	v_sub_f32_e32 v78, 1.0, v76
	v_add_f32_e32 v80, 1.0, v76
	v_mul_f32_e32 v78, v78, v80
	v_max_f32_e32 v78, 0, v78
	v_sqrt_f32_e32 v78, v78
	s_nop 0
	v_mul_f32_e32 v77, v77, v78
	v_add_f32_e32 v78, v83, v87
	v_mul_f32_e32 v78, 0xbfb8aa3b, v78
	v_exp_f32_e32 v78, v78
	v_mul_f32_e32 v77, v77, v99
	v_add_f32_e32 v78, 1.0, v78
	v_rcp_f32_e32 v78, v78
	s_nop 0
	v_mul_f32_e32 v78, 0xc1000000, v78
	v_mul_f32_e32 v78, v78, v160
	v_mul_f32_e32 v78, 0x3fb8aa3b, v78
	v_exp_f32_e32 v78, v78
	s_nop 0
	v_sub_f32_e32 v80, 1.0, v78
	v_add_f32_e32 v81, 1.0, v78
	v_mul_f32_e32 v80, v80, v81
	v_max_f32_e32 v80, 0, v80
	v_sqrt_f32_e32 v80, v80
	s_nop 0
	v_mul_f32_e32 v79, v79, v80
	v_mul_f32_e32 v79, v79, v93
	ds_write2_b64 v181, v[76:77], v[78:79] offset0:34 offset1:51
	v_mov_b32_e32 v84, v194
	v_mov_b32_e32 v85, v195
	v_mov_b32_e32 v86, v196
	v_mov_b32_e32 v87, v197
	v_mov_b32_e32 v88, v210
	v_mov_b32_e32 v89, v211
	v_mov_b32_e32 v90, v212
	v_mov_b32_e32 v91, v213
	v_mfma_f32_16x16x32_bf16 v[76:79], v[40:43], v[68:71], 0
	ds_read_b64 v[94:95], v2 offset:32
	s_waitcnt lgkmcnt(0)
	v_lshlrev_b32_e32 v93, 16, v94
	v_mfma_f32_16x16x32_bf16 v[80:83], v[48:51], v[72:75], v[76:79]
	v_and_b32_e32 v96, 0xffff0000, v94
	v_lshlrev_b32_e32 v97, 16, v95
	v_and_b32_e32 v98, 0xffff0000, v95
	v_mfma_f32_16x16x32_bf16 v[76:79], v[36:39], v[68:71], 0
	v_mfma_f32_16x16x32_bf16 v[76:79], v[44:47], v[72:75], v[76:79]
	s_waitcnt vmcnt(1)
	s_nop 1
	v_add_f32_e32 v80, v80, v84
	v_mul_f32_e32 v80, 0xbfb8aa3b, v80
	v_exp_f32_e32 v80, v80
	s_waitcnt vmcnt(0)
	s_nop 0
	v_add_f32_e32 v76, v76, v88
	v_mul_f32_e32 v76, 0xbfb8aa3b, v76
	v_exp_f32_e32 v76, v76
	v_add_f32_e32 v80, 1.0, v80
	v_rcp_f32_e32 v80, v80
	v_add_f32_e32 v77, v77, v89
	v_add_f32_e32 v76, 1.0, v76
	v_rcp_f32_e32 v76, v76
	v_mul_f32_e32 v80, 0xc1000000, v80
	v_mul_f32_e32 v80, v80, v161
	v_mul_f32_e32 v80, 0x3fb8aa3b, v80
	v_exp_f32_e32 v94, v80
	v_mul_f32_e32 v77, 0xbfb8aa3b, v77
	v_exp_f32_e32 v77, v77
	v_add_f32_e32 v79, v79, v91
	v_sub_f32_e32 v80, 1.0, v94
	v_add_f32_e32 v84, 1.0, v94
	v_mul_f32_e32 v80, v80, v84
	v_max_f32_e32 v80, 0, v80
	v_sqrt_f32_e32 v80, v80
	v_add_f32_e32 v77, 1.0, v77
	v_rcp_f32_e32 v77, v77
	v_mul_f32_e32 v79, 0xbfb8aa3b, v79
	v_mul_f32_e32 v76, v76, v80
	v_mul_f32_e32 v95, v76, v93
	v_add_f32_e32 v76, v81, v85
	v_mul_f32_e32 v76, 0xbfb8aa3b, v76
	v_exp_f32_e32 v76, v76
	v_exp_f32_e32 v79, v79
	v_add_f32_e32 v76, 1.0, v76
	v_rcp_f32_e32 v76, v76
	v_add_f32_e32 v79, 1.0, v79
	v_rcp_f32_e32 v79, v79
	v_mul_f32_e32 v76, 0xc1000000, v76
	v_mul_f32_e32 v76, v76, v162
	v_mul_f32_e32 v76, 0x3fb8aa3b, v76
	v_exp_f32_e32 v76, v76
	s_nop 0
	v_sub_f32_e32 v80, 1.0, v76
	v_add_f32_e32 v81, 1.0, v76
	v_mul_f32_e32 v80, v80, v81
	v_max_f32_e32 v80, 0, v80
	v_sqrt_f32_e32 v80, v80
	s_nop 0
	v_mul_f32_e32 v77, v77, v80
	v_mul_f32_e32 v77, v77, v96
	ds_write2_b64 v182, v[94:95], v[76:77] offset0:16 offset1:33
	v_add_f32_e32 v76, v82, v86
	v_mul_f32_e32 v76, 0xbfb8aa3b, v76
	v_exp_f32_e32 v76, v76
	v_add_f32_e32 v77, v78, v90
	v_mul_f32_e32 v77, 0xbfb8aa3b, v77
	v_exp_f32_e32 v77, v77
	v_add_f32_e32 v76, 1.0, v76
	v_rcp_f32_e32 v76, v76
	v_add_f32_e32 v77, 1.0, v77
	v_rcp_f32_e32 v77, v77
	v_mul_f32_e32 v76, 0xc1000000, v76
	v_mul_f32_e32 v76, v76, v164
	v_mul_f32_e32 v76, 0x3fb8aa3b, v76
	v_exp_f32_e32 v76, v76
	s_nop 0
	v_sub_f32_e32 v78, 1.0, v76
	v_add_f32_e32 v80, 1.0, v76
	v_mul_f32_e32 v78, v78, v80
	v_max_f32_e32 v78, 0, v78
	v_sqrt_f32_e32 v78, v78
	s_nop 0
	v_mul_f32_e32 v77, v77, v78
	v_add_f32_e32 v78, v83, v87
	v_mul_f32_e32 v78, 0xbfb8aa3b, v78
	v_exp_f32_e32 v78, v78
	v_mul_f32_e32 v77, v77, v97
	v_add_f32_e32 v78, 1.0, v78
	v_rcp_f32_e32 v78, v78
	s_nop 0
	v_mul_f32_e32 v78, 0xc1000000, v78
	v_mul_f32_e32 v78, v78, v166
	v_mul_f32_e32 v78, 0x3fb8aa3b, v78
	v_exp_f32_e32 v78, v78
	s_nop 0
	v_sub_f32_e32 v80, 1.0, v78
	v_add_f32_e32 v81, 1.0, v78
	v_mul_f32_e32 v80, v80, v81
	v_max_f32_e32 v80, 0, v80
	v_sqrt_f32_e32 v80, v80
	s_nop 0
	v_mul_f32_e32 v79, v79, v80
	v_mul_f32_e32 v79, v79, v98
	ds_write2_b64 v182, v[76:77], v[78:79] offset0:50 offset1:67
	v_mov_b32_e32 v84, v198
	v_mov_b32_e32 v85, v199
	v_mov_b32_e32 v86, v200
	v_mov_b32_e32 v87, v201
	v_mov_b32_e32 v88, v214
	v_mov_b32_e32 v89, v215
	v_mov_b32_e32 v90, v216
	v_mov_b32_e32 v91, v217
	v_mfma_f32_16x16x32_bf16 v[76:79], v[24:27], v[68:71], 0
	ds_read_b64 v[94:95], v2 offset:64
	s_waitcnt lgkmcnt(0)
	v_lshlrev_b32_e32 v93, 16, v94
	v_mfma_f32_16x16x32_bf16 v[80:83], v[32:35], v[72:75], v[76:79]
	v_and_b32_e32 v96, 0xffff0000, v94
	v_lshlrev_b32_e32 v97, 16, v95
	v_and_b32_e32 v98, 0xffff0000, v95
	v_mfma_f32_16x16x32_bf16 v[76:79], v[20:23], v[68:71], 0
	v_mfma_f32_16x16x32_bf16 v[76:79], v[28:31], v[72:75], v[76:79]
	s_waitcnt vmcnt(1)
	s_nop 1
	v_add_f32_e32 v80, v80, v84
	v_mul_f32_e32 v80, 0xbfb8aa3b, v80
	v_exp_f32_e32 v80, v80
	s_waitcnt vmcnt(0)
	s_nop 0
	v_add_f32_e32 v76, v76, v88
	v_mul_f32_e32 v76, 0xbfb8aa3b, v76
	v_exp_f32_e32 v76, v76
	v_add_f32_e32 v80, 1.0, v80
	v_rcp_f32_e32 v80, v80
	v_add_f32_e32 v77, v77, v89
	v_add_f32_e32 v76, 1.0, v76
	v_rcp_f32_e32 v76, v76
	v_mul_f32_e32 v80, 0xc1000000, v80
	v_mul_f32_e32 v80, v80, v163
	v_mul_f32_e32 v80, 0x3fb8aa3b, v80
	v_exp_f32_e32 v94, v80
	v_mul_f32_e32 v77, 0xbfb8aa3b, v77
	v_exp_f32_e32 v77, v77
	v_add_f32_e32 v79, v79, v91
	v_sub_f32_e32 v80, 1.0, v94
	v_add_f32_e32 v84, 1.0, v94
	v_mul_f32_e32 v80, v80, v84
	v_max_f32_e32 v80, 0, v80
	v_sqrt_f32_e32 v80, v80
	v_add_f32_e32 v77, 1.0, v77
	v_rcp_f32_e32 v77, v77
	v_mul_f32_e32 v79, 0xbfb8aa3b, v79
	v_mul_f32_e32 v76, v76, v80
	v_mul_f32_e32 v95, v76, v93
	v_add_f32_e32 v76, v81, v85
	v_mul_f32_e32 v76, 0xbfb8aa3b, v76
	v_exp_f32_e32 v76, v76
	v_exp_f32_e32 v79, v79
	v_add_f32_e32 v76, 1.0, v76
	v_rcp_f32_e32 v76, v76
	v_add_f32_e32 v79, 1.0, v79
	v_rcp_f32_e32 v79, v79
	v_mul_f32_e32 v76, 0xc1000000, v76
	v_mul_f32_e32 v76, v76, v165
	v_mul_f32_e32 v76, 0x3fb8aa3b, v76
	v_exp_f32_e32 v76, v76
	s_nop 0
	v_sub_f32_e32 v80, 1.0, v76
	v_add_f32_e32 v81, 1.0, v76
	v_mul_f32_e32 v80, v80, v81
	v_max_f32_e32 v80, 0, v80
	v_sqrt_f32_e32 v80, v80
	s_nop 0
	v_mul_f32_e32 v77, v77, v80
	v_mul_f32_e32 v77, v77, v96
	ds_write2_b64 v183, v[94:95], v[76:77] offset0:32 offset1:49
	v_add_f32_e32 v76, v82, v86
	v_mul_f32_e32 v76, 0xbfb8aa3b, v76
	v_exp_f32_e32 v76, v76
	v_add_f32_e32 v77, v78, v90
	v_mul_f32_e32 v77, 0xbfb8aa3b, v77
	v_exp_f32_e32 v77, v77
	v_add_f32_e32 v76, 1.0, v76
	v_rcp_f32_e32 v76, v76
	v_add_f32_e32 v77, 1.0, v77
	v_rcp_f32_e32 v77, v77
	v_mul_f32_e32 v76, 0xc1000000, v76
	v_mul_f32_e32 v76, v76, v167
	v_mul_f32_e32 v76, 0x3fb8aa3b, v76
	v_exp_f32_e32 v76, v76
	s_nop 0
	v_sub_f32_e32 v78, 1.0, v76
	v_add_f32_e32 v80, 1.0, v76
	v_mul_f32_e32 v78, v78, v80
	v_max_f32_e32 v78, 0, v78
	v_sqrt_f32_e32 v78, v78
	s_nop 0
	v_mul_f32_e32 v77, v77, v78
	v_add_f32_e32 v78, v83, v87
	v_mul_f32_e32 v78, 0xbfb8aa3b, v78
	v_exp_f32_e32 v78, v78
	v_mul_f32_e32 v77, v77, v97
	v_add_f32_e32 v78, 1.0, v78
	v_rcp_f32_e32 v78, v78
	s_nop 0
	v_mul_f32_e32 v78, 0xc1000000, v78
	v_mul_f32_e32 v78, v78, v168
	v_mul_f32_e32 v78, 0x3fb8aa3b, v78
	v_exp_f32_e32 v78, v78
	s_nop 0
	v_sub_f32_e32 v80, 1.0, v78
	v_add_f32_e32 v81, 1.0, v78
	v_mul_f32_e32 v80, v80, v81
	v_max_f32_e32 v80, 0, v80
	v_sqrt_f32_e32 v80, v80
	s_nop 0
	v_mul_f32_e32 v79, v79, v80
	v_mul_f32_e32 v79, v79, v98
	ds_write2_b64 v183, v[76:77], v[78:79] offset0:66 offset1:83
	v_mfma_f32_16x16x32_bf16 v[76:79], v[8:11], v[68:71], 0
	v_mfma_f32_16x16x32_bf16 v[68:71], v[4:7], v[68:71], 0
	v_mfma_f32_16x16x32_bf16 v[76:79], v[16:19], v[72:75], v[76:79]
	v_mfma_f32_16x16x32_bf16 v[68:71], v[12:15], v[72:75], v[68:71]
	v_mov_b32_e32 v72, v202
	v_mov_b32_e32 v73, v203
	v_mov_b32_e32 v74, v204
	v_mov_b32_e32 v75, v205
	v_mov_b32_e32 v80, v240
	v_mov_b32_e32 v81, v241
	v_mov_b32_e32 v82, v242
	v_mov_b32_e32 v83, v243
	ds_read_b64 v[84:85], v2 offset:96
	s_waitcnt lgkmcnt(0)
	v_lshlrev_b32_e32 v86, 16, v84
	v_and_b32_e32 v87, 0xffff0000, v84
	v_lshlrev_b32_e32 v88, 16, v85
	v_and_b32_e32 v89, 0xffff0000, v85
	s_waitcnt vmcnt(1)
	v_add_f32_e32 v72, v76, v72
	v_mul_f32_e32 v72, 0xbfb8aa3b, v72
	v_exp_f32_e32 v72, v72
	s_waitcnt vmcnt(0)
	v_add_f32_e32 v68, v68, v80
	v_mul_f32_e32 v68, 0xbfb8aa3b, v68
	v_exp_f32_e32 v68, v68
	v_add_f32_e32 v72, 1.0, v72
	v_rcp_f32_e32 v72, v72
	v_add_f32_e32 v69, v69, v81
	v_add_f32_e32 v68, 1.0, v68
	v_rcp_f32_e32 v68, v68
	v_mul_f32_e32 v72, 0xc1000000, v72
	v_mul_f32_e32 v72, v169, v72
	v_mul_f32_e32 v72, 0x3fb8aa3b, v72
	v_exp_f32_e32 v84, v72
	v_mul_f32_e32 v69, 0xbfb8aa3b, v69
	v_exp_f32_e32 v69, v69
	v_add_f32_e32 v71, v71, v83
	v_sub_f32_e32 v72, 1.0, v84
	v_add_f32_e32 v76, 1.0, v84
	v_mul_f32_e32 v72, v72, v76
	v_max_f32_e32 v72, 0, v72
	v_sqrt_f32_e32 v72, v72
	v_add_f32_e32 v69, 1.0, v69
	v_rcp_f32_e32 v69, v69
	v_mul_f32_e32 v71, 0xbfb8aa3b, v71
	v_mul_f32_e32 v68, v68, v72
	v_mul_f32_e32 v85, v68, v86
	v_add_f32_e32 v68, v77, v73
	v_mul_f32_e32 v68, 0xbfb8aa3b, v68
	v_exp_f32_e32 v68, v68
	v_exp_f32_e32 v71, v71
	v_add_f32_e32 v68, 1.0, v68
	v_rcp_f32_e32 v68, v68
	v_add_f32_e32 v71, 1.0, v71
	v_rcp_f32_e32 v71, v71
	v_mul_f32_e32 v68, 0xc1000000, v68
	v_mul_f32_e32 v68, v170, v68
	v_mul_f32_e32 v68, 0x3fb8aa3b, v68
	v_exp_f32_e32 v68, v68
	s_nop 0
	v_sub_f32_e32 v72, 1.0, v68
	v_add_f32_e32 v73, 1.0, v68
	v_mul_f32_e32 v72, v72, v73
	v_max_f32_e32 v72, 0, v72
	v_sqrt_f32_e32 v72, v72
	s_nop 0
	v_mul_f32_e32 v69, v69, v72
	v_mul_f32_e32 v69, v69, v87
	ds_write2_b64 v174, v[84:85], v[68:69] offset0:48 offset1:65
	v_add_f32_e32 v68, v78, v74
	v_mul_f32_e32 v68, 0xbfb8aa3b, v68
	v_exp_f32_e32 v68, v68
	v_add_f32_e32 v69, v70, v82
	v_mul_f32_e32 v69, 0xbfb8aa3b, v69
	v_exp_f32_e32 v69, v69
	v_add_f32_e32 v68, 1.0, v68
	v_rcp_f32_e32 v68, v68
	v_add_f32_e32 v69, 1.0, v69
	v_rcp_f32_e32 v69, v69
	v_mul_f32_e32 v68, 0xc1000000, v68
	v_mul_f32_e32 v68, v171, v68
	v_mul_f32_e32 v68, 0x3fb8aa3b, v68
	v_exp_f32_e32 v68, v68
	s_nop 0
	v_sub_f32_e32 v70, 1.0, v68
	v_add_f32_e32 v72, 1.0, v68
	v_mul_f32_e32 v70, v70, v72
	v_max_f32_e32 v70, 0, v70
	v_sqrt_f32_e32 v70, v70
	s_nop 0
	v_mul_f32_e32 v69, v69, v70
	v_add_f32_e32 v70, v79, v75
	v_mul_f32_e32 v70, 0xbfb8aa3b, v70
	v_exp_f32_e32 v70, v70
	v_mul_f32_e32 v69, v69, v88
	v_add_f32_e32 v70, 1.0, v70
	v_rcp_f32_e32 v70, v70
	s_nop 0
	v_mul_f32_e32 v70, 0xc1000000, v70
	v_mul_f32_e32 v70, v172, v70
	v_mul_f32_e32 v70, 0x3fb8aa3b, v70
	v_exp_f32_e32 v70, v70
	s_nop 0
	v_sub_f32_e32 v72, 1.0, v70
	v_add_f32_e32 v73, 1.0, v70
	v_mul_f32_e32 v72, v72, v73
	v_max_f32_e32 v72, 0, v72
	v_sqrt_f32_e32 v72, v72
	s_nop 0
	v_mul_f32_e32 v71, v71, v72
	v_mul_f32_e32 v71, v71, v89
	ds_write2_b64 v174, v[68:69], v[70:71] offset0:82 offset1:99
	s_waitcnt lgkmcnt(0)
	s_barrier
	ds_read2_b64 v[68:71], v173 offset1:1
	ds_read2_b64 v[108:111], v175 offset1:1
	ds_read2_b64 v[100:103], v185 offset1:1
	ds_read2_b64 v[88:91], v184 offset1:1
	ds_read2_b64 v[92:95], v179 offset1:1
	ds_read2_b64 v[104:107], v178 offset1:1
	s_waitcnt lgkmcnt(5)
	v_fma_f32 v72, 0, v68, v69
	v_pk_mul_f32 v[156:157], v[68:69], v[70:71]
	v_fmac_f32_e32 v71, v70, v72
	s_waitcnt lgkmcnt(3)
	v_fma_f32 v68, v100, v71, v101
	v_fma_f32 v68, v102, v68, v103
	ds_read2_b64 v[96:99], v176 offset1:1
	ds_read2_b64 v[84:87], v177 offset1:1
	s_waitcnt lgkmcnt(4)
	v_fma_f32 v68, v88, v68, v89
	v_fma_f32 v68, v90, v68, v91
	s_waitcnt lgkmcnt(3)
	v_fma_f32 v68, v92, v68, v93
	v_fma_f32 v68, v94, v68, v95
	s_waitcnt lgkmcnt(1)
	v_fma_f32 v68, v96, v68, v97
	v_fma_f32 v68, v98, v68, v99
	v_fma_f32 v68, v104, v68, v105
	v_fma_f32 v68, v106, v68, v107
	v_fma_f32 v68, v108, v68, v109
	v_fma_f32 v68, v110, v68, v111
	s_waitcnt lgkmcnt(0)
	v_fma_f32 v68, v84, v68, v85
	v_fma_f32 v89, v86, v68, v87
	s_barrier
	ds_read_b128 v[68:71], v180 offset:8704
	ds_read_b128 v[72:75], v180 offset:8768
	v_mov_b32_e32 v112, v190
	v_mov_b32_e32 v113, v191
	v_mov_b32_e32 v114, v192
	v_mov_b32_e32 v115, v193
	v_mov_b32_e32 v116, v206
	v_mov_b32_e32 v117, v207
	v_mov_b32_e32 v118, v208
	v_mov_b32_e32 v119, v209
	s_waitcnt lgkmcnt(1)
	v_mfma_f32_16x16x32_bf16 v[76:79], v[56:59], v[68:71], 0
	ds_read_b64 v[120:121], v2 offset:8704
	s_waitcnt lgkmcnt(0)
	v_lshlrev_b32_e32 v97, 16, v120
	v_mfma_f32_16x16x32_bf16 v[76:79], v[64:67], v[72:75], v[76:79]
	v_and_b32_e32 v109, 0xffff0000, v120
	v_lshlrev_b32_e32 v122, 16, v121
	v_and_b32_e32 v123, 0xffff0000, v121
	v_mfma_f32_16x16x32_bf16 v[80:83], v[52:55], v[68:71], 0
	v_mfma_f32_16x16x32_bf16 v[80:83], v[60:63], v[72:75], v[80:83]
	s_waitcnt vmcnt(1)
	s_nop 1
	v_add_f32_e32 v76, v76, v112
	v_mul_f32_e32 v76, 0xbfb8aa3b, v76
	v_exp_f32_e32 v76, v76
	s_waitcnt vmcnt(0)
	s_nop 0
	v_add_f32_e32 v80, v80, v116
	v_mul_f32_e32 v80, 0xbfb8aa3b, v80
	v_exp_f32_e32 v80, v80
	v_add_f32_e32 v76, 1.0, v76
	v_rcp_f32_e32 v76, v76
	v_add_f32_e32 v80, 1.0, v80
	v_rcp_f32_e32 v80, v80
	v_mul_f32_e32 v76, 0xc1000000, v76
	v_mul_f32_e32 v76, v1, v76
	v_mul_f32_e32 v76, 0x3fb8aa3b, v76
	v_exp_f32_e32 v120, v76
	s_nop 0
	v_sub_f32_e32 v76, 1.0, v120
	v_add_f32_e32 v112, 1.0, v120
	v_mul_f32_e32 v76, v76, v112
	v_max_f32_e32 v76, 0, v76
	v_sqrt_f32_e32 v76, v76
	s_nop 0
	v_mul_f32_e32 v76, v80, v76
	v_mul_f32_e32 v121, v76, v97
	v_add_f32_e32 v76, v77, v113
	v_mul_f32_e32 v76, 0xbfb8aa3b, v76
	v_exp_f32_e32 v76, v76
	v_add_f32_e32 v77, v81, v117
	v_mul_f32_e32 v77, 0xbfb8aa3b, v77
	v_exp_f32_e32 v77, v77
	v_add_f32_e32 v76, 1.0, v76
	v_rcp_f32_e32 v76, v76
	v_add_f32_e32 v77, 1.0, v77
	v_rcp_f32_e32 v77, v77
	v_mul_f32_e32 v76, 0xc1000000, v76
	v_mul_f32_e32 v76, v158, v76
	v_mul_f32_e32 v76, 0x3fb8aa3b, v76
	v_exp_f32_e32 v76, v76
	s_nop 0
	v_sub_f32_e32 v80, 1.0, v76
	v_add_f32_e32 v81, 1.0, v76
	v_mul_f32_e32 v80, v80, v81
	v_max_f32_e32 v80, 0, v80
	v_sqrt_f32_e32 v80, v80
	s_nop 0
	v_mul_f32_e32 v77, v77, v80
	v_mul_f32_e32 v77, v77, v109
	ds_write2_b64 v181, v[120:121], v[76:77] offset1:17
	v_add_f32_e32 v76, v78, v114
	v_mul_f32_e32 v76, 0xbfb8aa3b, v76
	v_exp_f32_e32 v76, v76
	v_add_f32_e32 v77, v82, v118
	v_mul_f32_e32 v77, 0xbfb8aa3b, v77
	v_exp_f32_e32 v77, v77
	v_add_f32_e32 v76, 1.0, v76
	v_rcp_f32_e32 v76, v76
	v_add_f32_e32 v77, 1.0, v77
	v_rcp_f32_e32 v77, v77
	v_mul_f32_e32 v76, 0xc1000000, v76
	v_mul_f32_e32 v76, v159, v76
	v_mul_f32_e32 v76, 0x3fb8aa3b, v76
	v_exp_f32_e32 v76, v76
	s_nop 0
	v_sub_f32_e32 v78, 1.0, v76
	v_add_f32_e32 v80, 1.0, v76
	v_mul_f32_e32 v78, v78, v80
	v_max_f32_e32 v78, 0, v78
	v_sqrt_f32_e32 v78, v78
	s_nop 0
	v_mul_f32_e32 v77, v77, v78
	v_add_f32_e32 v78, v79, v115
	v_mul_f32_e32 v78, 0xbfb8aa3b, v78
	v_exp_f32_e32 v78, v78
	v_add_f32_e32 v79, v83, v119
	v_mul_f32_e32 v79, 0xbfb8aa3b, v79
	v_exp_f32_e32 v79, v79
	v_add_f32_e32 v78, 1.0, v78
	v_rcp_f32_e32 v78, v78
	v_mul_f32_e32 v77, v77, v122
	v_add_f32_e32 v79, 1.0, v79
	v_rcp_f32_e32 v79, v79
	v_mul_f32_e32 v78, 0xc1000000, v78
	v_mul_f32_e32 v78, v160, v78
	v_mul_f32_e32 v78, 0x3fb8aa3b, v78
	v_exp_f32_e32 v78, v78
	s_nop 0
	v_sub_f32_e32 v80, 1.0, v78
	v_add_f32_e32 v81, 1.0, v78
	v_mul_f32_e32 v80, v80, v81
	v_max_f32_e32 v80, 0, v80
	v_sqrt_f32_e32 v80, v80
	s_nop 0
	v_mul_f32_e32 v79, v79, v80
	v_mul_f32_e32 v79, v79, v123
	ds_write2_b64 v181, v[76:77], v[78:79] offset0:34 offset1:51
	v_mov_b32_e32 v112, v194
	v_mov_b32_e32 v113, v195
	v_mov_b32_e32 v114, v196
	v_mov_b32_e32 v115, v197
	v_mov_b32_e32 v116, v210
	v_mov_b32_e32 v117, v211
	v_mov_b32_e32 v118, v212
	v_mov_b32_e32 v119, v213
	v_mfma_f32_16x16x32_bf16 v[76:79], v[40:43], v[68:71], 0
	ds_read_b64 v[120:121], v2 offset:8736
	s_waitcnt lgkmcnt(0)
	v_lshlrev_b32_e32 v97, 16, v120
	v_mfma_f32_16x16x32_bf16 v[80:83], v[48:51], v[72:75], v[76:79]
	v_and_b32_e32 v109, 0xffff0000, v120
	v_lshlrev_b32_e32 v122, 16, v121
	v_and_b32_e32 v123, 0xffff0000, v121
	v_mfma_f32_16x16x32_bf16 v[76:79], v[36:39], v[68:71], 0
	v_mfma_f32_16x16x32_bf16 v[76:79], v[44:47], v[72:75], v[76:79]
	s_waitcnt vmcnt(1)
	s_nop 1
	v_add_f32_e32 v80, v80, v112
	v_mul_f32_e32 v80, 0xbfb8aa3b, v80
	v_exp_f32_e32 v80, v80
	s_waitcnt vmcnt(0)
	s_nop 0
	v_add_f32_e32 v76, v76, v116
	v_mul_f32_e32 v76, 0xbfb8aa3b, v76
	v_exp_f32_e32 v76, v76
	v_add_f32_e32 v80, 1.0, v80
	v_rcp_f32_e32 v80, v80
	v_add_f32_e32 v77, v77, v117
	v_add_f32_e32 v76, 1.0, v76
	v_rcp_f32_e32 v76, v76
	v_mul_f32_e32 v80, 0xc1000000, v80
	v_mul_f32_e32 v80, v161, v80
	v_mul_f32_e32 v80, 0x3fb8aa3b, v80
	v_exp_f32_e32 v120, v80
	v_mul_f32_e32 v77, 0xbfb8aa3b, v77
	v_exp_f32_e32 v77, v77
	v_add_f32_e32 v79, v79, v119
	v_sub_f32_e32 v80, 1.0, v120
	v_add_f32_e32 v112, 1.0, v120
	v_mul_f32_e32 v80, v80, v112
	v_max_f32_e32 v80, 0, v80
	v_sqrt_f32_e32 v80, v80
	v_add_f32_e32 v77, 1.0, v77
	v_rcp_f32_e32 v77, v77
	v_mul_f32_e32 v79, 0xbfb8aa3b, v79
	v_mul_f32_e32 v76, v76, v80
	v_mul_f32_e32 v121, v76, v97
	v_add_f32_e32 v76, v81, v113
	v_mul_f32_e32 v76, 0xbfb8aa3b, v76
	v_exp_f32_e32 v76, v76
	v_exp_f32_e32 v79, v79
	v_add_f32_e32 v76, 1.0, v76
	v_rcp_f32_e32 v76, v76
	v_add_f32_e32 v79, 1.0, v79
	v_rcp_f32_e32 v79, v79
	v_mul_f32_e32 v76, 0xc1000000, v76
	v_mul_f32_e32 v76, v162, v76
	v_mul_f32_e32 v76, 0x3fb8aa3b, v76
	v_exp_f32_e32 v76, v76
	s_nop 0
	v_sub_f32_e32 v80, 1.0, v76
	v_add_f32_e32 v81, 1.0, v76
	v_mul_f32_e32 v80, v80, v81
	v_max_f32_e32 v80, 0, v80
	v_sqrt_f32_e32 v80, v80
	s_nop 0
	v_mul_f32_e32 v77, v77, v80
	v_mul_f32_e32 v77, v77, v109
	ds_write2_b64 v182, v[120:121], v[76:77] offset0:16 offset1:33
	v_add_f32_e32 v76, v82, v114
	v_mul_f32_e32 v76, 0xbfb8aa3b, v76
	v_exp_f32_e32 v76, v76
	v_add_f32_e32 v77, v78, v118
	v_mul_f32_e32 v77, 0xbfb8aa3b, v77
	v_exp_f32_e32 v77, v77
	v_add_f32_e32 v76, 1.0, v76
	v_rcp_f32_e32 v76, v76
	v_add_f32_e32 v77, 1.0, v77
	v_rcp_f32_e32 v77, v77
	v_mul_f32_e32 v76, 0xc1000000, v76
	v_mul_f32_e32 v76, v164, v76
	v_mul_f32_e32 v76, 0x3fb8aa3b, v76
	v_exp_f32_e32 v76, v76
	s_nop 0
	v_sub_f32_e32 v78, 1.0, v76
	v_add_f32_e32 v80, 1.0, v76
	v_mul_f32_e32 v78, v78, v80
	v_max_f32_e32 v78, 0, v78
	v_sqrt_f32_e32 v78, v78
	s_nop 0
	v_mul_f32_e32 v77, v77, v78
	v_add_f32_e32 v78, v83, v115
	v_mul_f32_e32 v78, 0xbfb8aa3b, v78
	v_exp_f32_e32 v78, v78
	v_mul_f32_e32 v77, v77, v122
	v_add_f32_e32 v78, 1.0, v78
	v_rcp_f32_e32 v78, v78
	s_nop 0
	v_mul_f32_e32 v78, 0xc1000000, v78
	v_mul_f32_e32 v78, v166, v78
	v_mul_f32_e32 v78, 0x3fb8aa3b, v78
	v_exp_f32_e32 v78, v78
	s_nop 0
	v_sub_f32_e32 v80, 1.0, v78
	v_add_f32_e32 v81, 1.0, v78
	v_mul_f32_e32 v80, v80, v81
	v_max_f32_e32 v80, 0, v80
	v_sqrt_f32_e32 v80, v80
	s_nop 0
	v_mul_f32_e32 v79, v79, v80
	v_mul_f32_e32 v79, v79, v123
	ds_write2_b64 v182, v[76:77], v[78:79] offset0:50 offset1:67
	v_mov_b32_e32 v112, v198
	v_mov_b32_e32 v113, v199
	v_mov_b32_e32 v114, v200
	v_mov_b32_e32 v115, v201
	v_mov_b32_e32 v116, v214
	v_mov_b32_e32 v117, v215
	v_mov_b32_e32 v118, v216
	v_mov_b32_e32 v119, v217
	v_mfma_f32_16x16x32_bf16 v[76:79], v[24:27], v[68:71], 0
	ds_read_b64 v[120:121], v2 offset:8768
	s_waitcnt lgkmcnt(0)
	v_lshlrev_b32_e32 v97, 16, v120
	v_mfma_f32_16x16x32_bf16 v[80:83], v[32:35], v[72:75], v[76:79]
	v_and_b32_e32 v109, 0xffff0000, v120
	v_lshlrev_b32_e32 v122, 16, v121
	v_and_b32_e32 v123, 0xffff0000, v121
	v_mfma_f32_16x16x32_bf16 v[76:79], v[20:23], v[68:71], 0
	v_mfma_f32_16x16x32_bf16 v[76:79], v[28:31], v[72:75], v[76:79]
	s_waitcnt vmcnt(1)
	s_nop 1
	v_add_f32_e32 v80, v80, v112
	v_mul_f32_e32 v80, 0xbfb8aa3b, v80
	v_exp_f32_e32 v80, v80
	s_waitcnt vmcnt(0)
	s_nop 0
	v_add_f32_e32 v76, v76, v116
	v_mul_f32_e32 v76, 0xbfb8aa3b, v76
	v_exp_f32_e32 v76, v76
	v_add_f32_e32 v80, 1.0, v80
	v_rcp_f32_e32 v80, v80
	v_add_f32_e32 v77, v77, v117
	v_add_f32_e32 v76, 1.0, v76
	v_rcp_f32_e32 v76, v76
	v_mul_f32_e32 v80, 0xc1000000, v80
	v_mul_f32_e32 v80, v163, v80
	v_mul_f32_e32 v80, 0x3fb8aa3b, v80
	v_exp_f32_e32 v120, v80
	v_mul_f32_e32 v77, 0xbfb8aa3b, v77
	v_exp_f32_e32 v77, v77
	v_add_f32_e32 v79, v79, v119
	v_sub_f32_e32 v80, 1.0, v120
	v_add_f32_e32 v112, 1.0, v120
	v_mul_f32_e32 v80, v80, v112
	v_max_f32_e32 v80, 0, v80
	v_sqrt_f32_e32 v80, v80
	v_add_f32_e32 v77, 1.0, v77
	v_rcp_f32_e32 v77, v77
	v_mul_f32_e32 v79, 0xbfb8aa3b, v79
	v_mul_f32_e32 v76, v76, v80
	v_mul_f32_e32 v121, v76, v97
	v_add_f32_e32 v76, v81, v113
	v_mul_f32_e32 v76, 0xbfb8aa3b, v76
	v_exp_f32_e32 v76, v76
	v_exp_f32_e32 v79, v79
	v_add_f32_e32 v76, 1.0, v76
	v_rcp_f32_e32 v76, v76
	v_add_f32_e32 v79, 1.0, v79
	v_rcp_f32_e32 v79, v79
	v_mul_f32_e32 v76, 0xc1000000, v76
	v_mul_f32_e32 v76, v165, v76
	v_mul_f32_e32 v76, 0x3fb8aa3b, v76
	v_exp_f32_e32 v76, v76
	s_nop 0
	v_sub_f32_e32 v80, 1.0, v76
	v_add_f32_e32 v81, 1.0, v76
	v_mul_f32_e32 v80, v80, v81
	v_max_f32_e32 v80, 0, v80
	v_sqrt_f32_e32 v80, v80
	s_nop 0
	v_mul_f32_e32 v77, v77, v80
	v_mul_f32_e32 v77, v77, v109
	ds_write2_b64 v183, v[120:121], v[76:77] offset0:32 offset1:49
	v_add_f32_e32 v76, v82, v114
	v_mul_f32_e32 v76, 0xbfb8aa3b, v76
	v_exp_f32_e32 v76, v76
	v_add_f32_e32 v77, v78, v118
	v_mul_f32_e32 v77, 0xbfb8aa3b, v77
	v_exp_f32_e32 v77, v77
	v_add_f32_e32 v76, 1.0, v76
	v_rcp_f32_e32 v76, v76
	v_add_f32_e32 v77, 1.0, v77
	v_rcp_f32_e32 v77, v77
	v_mul_f32_e32 v76, 0xc1000000, v76
	v_mul_f32_e32 v76, v167, v76
	v_mul_f32_e32 v76, 0x3fb8aa3b, v76
	v_exp_f32_e32 v76, v76
	s_nop 0
	v_sub_f32_e32 v78, 1.0, v76
	v_add_f32_e32 v80, 1.0, v76
	v_mul_f32_e32 v78, v78, v80
	v_max_f32_e32 v78, 0, v78
	v_sqrt_f32_e32 v78, v78
	s_nop 0
	v_mul_f32_e32 v77, v77, v78
	v_add_f32_e32 v78, v83, v115
	v_mul_f32_e32 v78, 0xbfb8aa3b, v78
	v_exp_f32_e32 v78, v78
	v_mul_f32_e32 v77, v77, v122
	v_add_f32_e32 v78, 1.0, v78
	v_rcp_f32_e32 v78, v78
	s_nop 0
	v_mul_f32_e32 v78, 0xc1000000, v78
	v_mul_f32_e32 v78, v168, v78
	v_mul_f32_e32 v78, 0x3fb8aa3b, v78
	v_exp_f32_e32 v78, v78
	s_nop 0
	v_sub_f32_e32 v80, 1.0, v78
	v_add_f32_e32 v81, 1.0, v78
	v_mul_f32_e32 v80, v80, v81
	v_max_f32_e32 v80, 0, v80
	v_sqrt_f32_e32 v80, v80
	s_nop 0
	v_mul_f32_e32 v79, v79, v80
	v_mul_f32_e32 v79, v79, v123
	ds_write2_b64 v183, v[76:77], v[78:79] offset0:66 offset1:83
	v_mfma_f32_16x16x32_bf16 v[76:79], v[8:11], v[68:71], 0
	v_mfma_f32_16x16x32_bf16 v[68:71], v[4:7], v[68:71], 0
	v_mfma_f32_16x16x32_bf16 v[76:79], v[16:19], v[72:75], v[76:79]
	v_mfma_f32_16x16x32_bf16 v[68:71], v[12:15], v[72:75], v[68:71]
	v_mov_b32_e32 v72, v202
	v_mov_b32_e32 v73, v203
	v_mov_b32_e32 v74, v204
	v_mov_b32_e32 v75, v205
	v_mov_b32_e32 v80, v240
	v_mov_b32_e32 v81, v241
	v_mov_b32_e32 v82, v242
	v_mov_b32_e32 v83, v243
	ds_read_b64 v[112:113], v2 offset:8800
	s_waitcnt lgkmcnt(0)
	v_lshlrev_b32_e32 v97, 16, v112
	v_and_b32_e32 v109, 0xffff0000, v112
	v_lshlrev_b32_e32 v114, 16, v113
	v_and_b32_e32 v115, 0xffff0000, v113
	s_waitcnt vmcnt(1)
	v_add_f32_e32 v72, v76, v72
	v_mul_f32_e32 v72, 0xbfb8aa3b, v72
	v_exp_f32_e32 v72, v72
	s_waitcnt vmcnt(0)
	v_add_f32_e32 v68, v68, v80
	v_mul_f32_e32 v68, 0xbfb8aa3b, v68
	v_exp_f32_e32 v68, v68
	v_add_f32_e32 v72, 1.0, v72
	v_rcp_f32_e32 v72, v72
	v_add_f32_e32 v69, v69, v81
	v_add_f32_e32 v68, 1.0, v68
	v_rcp_f32_e32 v68, v68
	v_mul_f32_e32 v72, 0xc1000000, v72
	v_mul_f32_e32 v72, v169, v72
	v_mul_f32_e32 v72, 0x3fb8aa3b, v72
	v_exp_f32_e32 v112, v72
	v_mul_f32_e32 v69, 0xbfb8aa3b, v69
	v_exp_f32_e32 v69, v69
	v_add_f32_e32 v71, v71, v83
	v_sub_f32_e32 v72, 1.0, v112
	v_add_f32_e32 v76, 1.0, v112
	v_mul_f32_e32 v72, v72, v76
	v_max_f32_e32 v72, 0, v72
	v_sqrt_f32_e32 v72, v72
	v_add_f32_e32 v69, 1.0, v69
	v_rcp_f32_e32 v69, v69
	v_mul_f32_e32 v71, 0xbfb8aa3b, v71
	v_mul_f32_e32 v68, v68, v72
	v_mul_f32_e32 v113, v68, v97
	v_add_f32_e32 v68, v77, v73
	v_mul_f32_e32 v68, 0xbfb8aa3b, v68
	v_exp_f32_e32 v68, v68
	v_exp_f32_e32 v71, v71
	v_add_f32_e32 v68, 1.0, v68
	v_rcp_f32_e32 v68, v68
	v_add_f32_e32 v71, 1.0, v71
	v_rcp_f32_e32 v71, v71
	v_mul_f32_e32 v68, 0xc1000000, v68
	v_mul_f32_e32 v68, v170, v68
	v_mul_f32_e32 v68, 0x3fb8aa3b, v68
	v_exp_f32_e32 v68, v68
	s_nop 0
	v_sub_f32_e32 v72, 1.0, v68
	v_add_f32_e32 v73, 1.0, v68
	v_mul_f32_e32 v72, v72, v73
	v_max_f32_e32 v72, 0, v72
	v_sqrt_f32_e32 v72, v72
	s_nop 0
	v_mul_f32_e32 v69, v69, v72
	v_mul_f32_e32 v69, v69, v109
	ds_write2_b64 v174, v[112:113], v[68:69] offset0:48 offset1:65
	v_add_f32_e32 v68, v78, v74
	v_mul_f32_e32 v68, 0xbfb8aa3b, v68
	v_exp_f32_e32 v68, v68
	v_add_f32_e32 v69, v70, v82
	v_mul_f32_e32 v69, 0xbfb8aa3b, v69
	v_exp_f32_e32 v69, v69
	v_add_f32_e32 v68, 1.0, v68
	v_rcp_f32_e32 v68, v68
	v_add_f32_e32 v69, 1.0, v69
	v_rcp_f32_e32 v69, v69
	v_mul_f32_e32 v68, 0xc1000000, v68
	v_mul_f32_e32 v68, v171, v68
	v_mul_f32_e32 v68, 0x3fb8aa3b, v68
	v_exp_f32_e32 v68, v68
	s_nop 0
	v_sub_f32_e32 v70, 1.0, v68
	v_add_f32_e32 v72, 1.0, v68
	v_mul_f32_e32 v70, v70, v72
	v_max_f32_e32 v70, 0, v70
	v_sqrt_f32_e32 v70, v70
	s_nop 0
	v_mul_f32_e32 v69, v69, v70
	v_add_f32_e32 v70, v79, v75
	v_mul_f32_e32 v70, 0xbfb8aa3b, v70
	v_exp_f32_e32 v70, v70
	v_mul_f32_e32 v69, v69, v114
	v_add_f32_e32 v70, 1.0, v70
	v_rcp_f32_e32 v70, v70
	s_nop 0
	v_mul_f32_e32 v70, 0xc1000000, v70
	v_mul_f32_e32 v70, v172, v70
	v_mul_f32_e32 v70, 0x3fb8aa3b, v70
	v_exp_f32_e32 v70, v70
	s_nop 0
	v_sub_f32_e32 v72, 1.0, v70
	v_add_f32_e32 v73, 1.0, v70
	v_mul_f32_e32 v72, v72, v73
	v_max_f32_e32 v72, 0, v72
	v_sqrt_f32_e32 v72, v72
	s_nop 0
	v_mul_f32_e32 v71, v71, v72
	v_mul_f32_e32 v71, v71, v115
	ds_write2_b64 v174, v[68:69], v[70:71] offset0:82 offset1:99
	s_waitcnt lgkmcnt(0)
	s_barrier
	ds_read2_b64 v[124:127], v173 offset1:1
	ds_read2_b64 v[76:79], v175 offset1:1
	ds_read2_b64 v[128:131], v185 offset1:1
	ds_read2_b64 v[132:135], v184 offset1:1
	ds_read2_b64 v[136:139], v179 offset1:1
	s_waitcnt lgkmcnt(4)
	v_fma_f32 v68, v89, v124, v125
	v_fma_f32 v68, v126, v68, v127
	s_waitcnt lgkmcnt(2)
	v_fma_f32 v68, v128, v68, v129
	v_fma_f32 v68, v130, v68, v131
	s_waitcnt lgkmcnt(1)
	v_fma_f32 v68, v132, v68, v133
	v_fma_f32 v68, v134, v68, v135
	s_waitcnt lgkmcnt(0)
	v_fma_f32 v68, v136, v68, v137
	v_fma_f32 v72, v138, v68, v139
	ds_read2_b64 v[68:71], v176 offset1:1
	ds_read2_b64 v[80:83], v177 offset1:1
	s_waitcnt lgkmcnt(1)
	v_fma_f32 v69, v68, v72, v69
	ds_read2_b64 v[72:75], v178 offset1:1
	s_waitcnt lgkmcnt(0)
	s_barrier
	ds_read_b128 v[112:115], v180 offset:17408
	ds_read_b128 v[116:119], v180 offset:17472
	v_mov_b32_e32 v144, v190
	v_mov_b32_e32 v145, v191
	v_mov_b32_e32 v146, v192
	v_mov_b32_e32 v147, v193
	v_mov_b32_e32 v148, v206
	v_mov_b32_e32 v149, v207
	v_mov_b32_e32 v150, v208
	v_mov_b32_e32 v151, v209
	s_waitcnt lgkmcnt(1)
	v_mfma_f32_16x16x32_bf16 v[120:123], v[56:59], v[112:115], 0
	ds_read_b64 v[186:187], v2 offset:17408
	v_fma_f32 v69, v70, v69, v71
	v_fma_f32 v69, v72, v69, v73
	s_waitcnt lgkmcnt(1)
	v_mfma_f32_16x16x32_bf16 v[120:123], v[64:67], v[116:119], v[120:123]
	v_fma_f32 v69, v74, v69, v75
	v_fma_f32 v69, v76, v69, v77
	s_waitcnt lgkmcnt(0)
	v_lshlrev_b32_e32 v77, 16, v186
	v_mfma_f32_16x16x32_bf16 v[140:143], v[52:55], v[112:115], 0
	v_and_b32_e32 v89, 0xffff0000, v186
	v_lshlrev_b32_e32 v97, 16, v187
	v_and_b32_e32 v109, 0xffff0000, v187
	v_mfma_f32_16x16x32_bf16 v[140:143], v[60:63], v[116:119], v[140:143]
	v_fma_f32 v69, v78, v69, v79
	v_fma_f32 v69, v80, v69, v81
	v_fma_f32 v69, v82, v69, v83
	s_waitcnt vmcnt(1)
	v_add_f32_e32 v120, v120, v144
	v_mul_f32_e32 v120, 0xbfb8aa3b, v120
	v_exp_f32_e32 v120, v120
	s_waitcnt vmcnt(0)
	v_add_f32_e32 v125, v140, v148
	v_mul_f32_e32 v125, 0xbfb8aa3b, v125
	v_exp_f32_e32 v125, v125
	v_add_f32_e32 v120, 1.0, v120
	v_rcp_f32_e32 v120, v120
	v_add_f32_e32 v125, 1.0, v125
	v_rcp_f32_e32 v125, v125
	v_mul_f32_e32 v120, 0xc1000000, v120
	v_mul_f32_e32 v120, v1, v120
	v_mul_f32_e32 v120, 0x3fb8aa3b, v120
	v_exp_f32_e32 v186, v120
	s_nop 0
	v_sub_f32_e32 v120, 1.0, v186
	v_add_f32_e32 v133, 1.0, v186
	v_mul_f32_e32 v120, v120, v133
	v_max_f32_e32 v120, 0, v120
	v_sqrt_f32_e32 v120, v120
	s_nop 0
	v_mul_f32_e32 v120, v125, v120
	v_mul_f32_e32 v187, v120, v77
	v_add_f32_e32 v77, v121, v145
	v_mul_f32_e32 v77, 0xbfb8aa3b, v77
	v_exp_f32_e32 v77, v77
	v_add_f32_e32 v120, v141, v149
	v_mul_f32_e32 v120, 0xbfb8aa3b, v120
	v_exp_f32_e32 v120, v120
	v_add_f32_e32 v77, 1.0, v77
	v_rcp_f32_e32 v77, v77
	v_add_f32_e32 v120, 1.0, v120
	v_rcp_f32_e32 v121, v120
	v_mul_f32_e32 v77, 0xc1000000, v77
	v_mul_f32_e32 v77, v158, v77
	v_mul_f32_e32 v77, 0x3fb8aa3b, v77
	v_exp_f32_e32 v120, v77
	s_nop 0
	v_sub_f32_e32 v77, 1.0, v120
	v_add_f32_e32 v125, 1.0, v120
	v_mul_f32_e32 v77, v77, v125
	v_max_f32_e32 v77, 0, v77
	v_sqrt_f32_e32 v77, v77
	s_nop 0
	v_mul_f32_e32 v77, v121, v77
	v_mul_f32_e32 v121, v77, v89
	v_add_f32_e32 v77, v122, v146
	v_mul_f32_e32 v77, 0xbfb8aa3b, v77
	v_exp_f32_e32 v77, v77
	ds_write2_b64 v181, v[186:187], v[120:121] offset1:17
	v_add_f32_e32 v89, v142, v150
	v_mul_f32_e32 v89, 0xbfb8aa3b, v89
	v_add_f32_e32 v77, 1.0, v77
	v_rcp_f32_e32 v77, v77
	v_exp_f32_e32 v89, v89
	v_mul_f32_e32 v77, 0xc1000000, v77
	v_mul_f32_e32 v77, v159, v77
	v_mul_f32_e32 v77, 0x3fb8aa3b, v77
	v_exp_f32_e32 v120, v77
	v_add_f32_e32 v89, 1.0, v89
	v_rcp_f32_e32 v89, v89
	v_sub_f32_e32 v77, 1.0, v120
	v_add_f32_e32 v121, 1.0, v120
	v_mul_f32_e32 v77, v77, v121
	v_max_f32_e32 v77, 0, v77
	v_sqrt_f32_e32 v77, v77
	s_nop 0
	v_mul_f32_e32 v77, v89, v77
	v_mul_f32_e32 v121, v77, v97
	v_add_f32_e32 v77, v123, v147
	v_mul_f32_e32 v77, 0xbfb8aa3b, v77
	v_exp_f32_e32 v77, v77
	v_add_f32_e32 v89, v143, v151
	v_mul_f32_e32 v89, 0xbfb8aa3b, v89
	v_exp_f32_e32 v89, v89
	v_add_f32_e32 v77, 1.0, v77
	v_rcp_f32_e32 v77, v77
	v_add_f32_e32 v89, 1.0, v89
	v_rcp_f32_e32 v89, v89
	v_mul_f32_e32 v77, 0xc1000000, v77
	v_mul_f32_e32 v77, v160, v77
	v_mul_f32_e32 v77, 0x3fb8aa3b, v77
	v_exp_f32_e32 v122, v77
	s_nop 0
	v_sub_f32_e32 v77, 1.0, v122
	v_add_f32_e32 v97, 1.0, v122
	v_mul_f32_e32 v77, v77, v97
	v_max_f32_e32 v77, 0, v77
	v_sqrt_f32_e32 v77, v77
	s_nop 0
	v_mul_f32_e32 v77, v89, v77
	v_mul_f32_e32 v123, v77, v109
	ds_write2_b64 v181, v[120:121], v[122:123] offset0:34 offset1:51
	v_mov_b32_e32 v144, v194
	v_mov_b32_e32 v145, v195
	v_mov_b32_e32 v146, v196
	v_mov_b32_e32 v147, v197
	v_mov_b32_e32 v148, v210
	v_mov_b32_e32 v149, v211
	v_mov_b32_e32 v150, v212
	v_mov_b32_e32 v151, v213
	v_mfma_f32_16x16x32_bf16 v[120:123], v[40:43], v[112:115], 0
	ds_read_b64 v[186:187], v2 offset:17440
	s_waitcnt lgkmcnt(0)
	v_lshlrev_b32_e32 v77, 16, v186
	v_mfma_f32_16x16x32_bf16 v[140:143], v[48:51], v[116:119], v[120:123]
	v_and_b32_e32 v89, 0xffff0000, v186
	v_lshlrev_b32_e32 v97, 16, v187
	v_and_b32_e32 v109, 0xffff0000, v187
	v_mfma_f32_16x16x32_bf16 v[120:123], v[36:39], v[112:115], 0
	v_mfma_f32_16x16x32_bf16 v[120:123], v[44:47], v[116:119], v[120:123]
	s_waitcnt vmcnt(1)
	s_nop 1
	v_add_f32_e32 v125, v140, v144
	v_mul_f32_e32 v125, 0xbfb8aa3b, v125
	v_exp_f32_e32 v125, v125
	s_waitcnt vmcnt(0)
	s_nop 0
	v_add_f32_e32 v120, v120, v148
	v_mul_f32_e32 v120, 0xbfb8aa3b, v120
	v_exp_f32_e32 v120, v120
	v_add_f32_e32 v125, 1.0, v125
	v_rcp_f32_e32 v125, v125
	v_add_f32_e32 v120, 1.0, v120
	v_rcp_f32_e32 v120, v120
	v_mul_f32_e32 v125, 0xc1000000, v125
	v_mul_f32_e32 v125, v161, v125
	v_mul_f32_e32 v125, 0x3fb8aa3b, v125
	v_exp_f32_e32 v186, v125
	s_nop 0
	v_sub_f32_e32 v125, 1.0, v186
	v_add_f32_e32 v133, 1.0, v186
	v_mul_f32_e32 v125, v125, v133
	v_max_f32_e32 v125, 0, v125
	v_sqrt_f32_e32 v125, v125
	s_nop 0
	v_mul_f32_e32 v120, v120, v125
	v_mul_f32_e32 v187, v120, v77
	v_add_f32_e32 v77, v141, v145
	v_mul_f32_e32 v77, 0xbfb8aa3b, v77
	v_exp_f32_e32 v77, v77
	v_add_f32_e32 v120, v121, v149
	v_mul_f32_e32 v120, 0xbfb8aa3b, v120
	v_exp_f32_e32 v120, v120
	v_add_f32_e32 v77, 1.0, v77
	v_rcp_f32_e32 v77, v77
	v_add_f32_e32 v120, 1.0, v120
	v_rcp_f32_e32 v121, v120
	v_mul_f32_e32 v77, 0xc1000000, v77
	v_mul_f32_e32 v77, v162, v77
	v_mul_f32_e32 v77, 0x3fb8aa3b, v77
	v_exp_f32_e32 v120, v77
	s_nop 0
	v_sub_f32_e32 v77, 1.0, v120
	v_add_f32_e32 v125, 1.0, v120
	v_mul_f32_e32 v77, v77, v125
	v_max_f32_e32 v77, 0, v77
	v_sqrt_f32_e32 v77, v77
	s_nop 0
	v_mul_f32_e32 v77, v121, v77
	v_mul_f32_e32 v121, v77, v89
	v_add_f32_e32 v77, v142, v146
	v_mul_f32_e32 v77, 0xbfb8aa3b, v77
	v_exp_f32_e32 v77, v77
	ds_write2_b64 v182, v[186:187], v[120:121] offset0:16 offset1:33
	v_add_f32_e32 v89, v122, v150
	v_mul_f32_e32 v89, 0xbfb8aa3b, v89
	v_add_f32_e32 v77, 1.0, v77
	v_rcp_f32_e32 v77, v77
	v_exp_f32_e32 v89, v89
	v_mul_f32_e32 v77, 0xc1000000, v77
	v_mul_f32_e32 v77, v164, v77
	v_mul_f32_e32 v77, 0x3fb8aa3b, v77
	v_exp_f32_e32 v120, v77
	v_add_f32_e32 v89, 1.0, v89
	v_rcp_f32_e32 v89, v89
	v_sub_f32_e32 v77, 1.0, v120
	v_add_f32_e32 v121, 1.0, v120
	v_mul_f32_e32 v77, v77, v121
	v_max_f32_e32 v77, 0, v77
	v_sqrt_f32_e32 v77, v77
	s_nop 0
	v_mul_f32_e32 v77, v89, v77
	v_mul_f32_e32 v121, v77, v97
	v_add_f32_e32 v77, v143, v147
	v_mul_f32_e32 v77, 0xbfb8aa3b, v77
	v_exp_f32_e32 v77, v77
	v_add_f32_e32 v89, v123, v151
	v_mul_f32_e32 v89, 0xbfb8aa3b, v89
	v_exp_f32_e32 v89, v89
	v_add_f32_e32 v77, 1.0, v77
	v_rcp_f32_e32 v77, v77
	v_add_f32_e32 v89, 1.0, v89
	v_rcp_f32_e32 v89, v89
	v_mul_f32_e32 v77, 0xc1000000, v77
	v_mul_f32_e32 v77, v166, v77
	v_mul_f32_e32 v77, 0x3fb8aa3b, v77
	v_exp_f32_e32 v122, v77
	s_nop 0
	v_sub_f32_e32 v77, 1.0, v122
	v_add_f32_e32 v97, 1.0, v122
	v_mul_f32_e32 v77, v77, v97
	v_max_f32_e32 v77, 0, v77
	v_sqrt_f32_e32 v77, v77
	s_nop 0
	v_mul_f32_e32 v77, v89, v77
	v_mul_f32_e32 v123, v77, v109
	ds_write2_b64 v182, v[120:121], v[122:123] offset0:50 offset1:67
	v_mov_b32_e32 v144, v198
	v_mov_b32_e32 v145, v199
	v_mov_b32_e32 v146, v200
	v_mov_b32_e32 v147, v201
	v_mov_b32_e32 v148, v214
	v_mov_b32_e32 v149, v215
	v_mov_b32_e32 v150, v216
	v_mov_b32_e32 v151, v217
	v_mfma_f32_16x16x32_bf16 v[120:123], v[24:27], v[112:115], 0
	ds_read_b64 v[186:187], v2 offset:17472
	s_waitcnt lgkmcnt(0)
	v_lshlrev_b32_e32 v77, 16, v186
	v_mfma_f32_16x16x32_bf16 v[140:143], v[32:35], v[116:119], v[120:123]
	v_and_b32_e32 v89, 0xffff0000, v186
	v_lshlrev_b32_e32 v97, 16, v187
	v_and_b32_e32 v109, 0xffff0000, v187
	v_mfma_f32_16x16x32_bf16 v[120:123], v[20:23], v[112:115], 0
	v_mfma_f32_16x16x32_bf16 v[120:123], v[28:31], v[116:119], v[120:123]
	s_waitcnt vmcnt(1)
	s_nop 1
	v_add_f32_e32 v125, v140, v144
	v_mul_f32_e32 v125, 0xbfb8aa3b, v125
	v_exp_f32_e32 v125, v125
	s_waitcnt vmcnt(0)
	s_nop 0
	v_add_f32_e32 v120, v120, v148
	v_mul_f32_e32 v120, 0xbfb8aa3b, v120
	v_exp_f32_e32 v120, v120
	v_add_f32_e32 v125, 1.0, v125
	v_rcp_f32_e32 v125, v125
	v_add_f32_e32 v120, 1.0, v120
	v_rcp_f32_e32 v120, v120
	v_mul_f32_e32 v125, 0xc1000000, v125
	v_mul_f32_e32 v125, v163, v125
	v_mul_f32_e32 v125, 0x3fb8aa3b, v125
	v_exp_f32_e32 v186, v125
	s_nop 0
	v_sub_f32_e32 v125, 1.0, v186
	v_add_f32_e32 v133, 1.0, v186
	v_mul_f32_e32 v125, v125, v133
	v_max_f32_e32 v125, 0, v125
	v_sqrt_f32_e32 v125, v125
	s_nop 0
	v_mul_f32_e32 v120, v120, v125
	v_mul_f32_e32 v187, v120, v77
	v_add_f32_e32 v77, v141, v145
	v_mul_f32_e32 v77, 0xbfb8aa3b, v77
	v_exp_f32_e32 v77, v77
	v_add_f32_e32 v120, v121, v149
	v_mul_f32_e32 v120, 0xbfb8aa3b, v120
	v_exp_f32_e32 v120, v120
	v_add_f32_e32 v77, 1.0, v77
	v_rcp_f32_e32 v77, v77
	v_add_f32_e32 v120, 1.0, v120
	v_rcp_f32_e32 v121, v120
	v_mul_f32_e32 v77, 0xc1000000, v77
	v_mul_f32_e32 v77, v165, v77
	v_mul_f32_e32 v77, 0x3fb8aa3b, v77
	v_exp_f32_e32 v120, v77
	s_nop 0
	v_sub_f32_e32 v77, 1.0, v120
	v_add_f32_e32 v125, 1.0, v120
	v_mul_f32_e32 v77, v77, v125
	v_max_f32_e32 v77, 0, v77
	v_sqrt_f32_e32 v77, v77
	s_nop 0
	v_mul_f32_e32 v77, v121, v77
	v_mul_f32_e32 v121, v77, v89
	v_add_f32_e32 v77, v142, v146
	v_mul_f32_e32 v77, 0xbfb8aa3b, v77
	v_exp_f32_e32 v77, v77
	ds_write2_b64 v183, v[186:187], v[120:121] offset0:32 offset1:49
	v_add_f32_e32 v89, v122, v150
	v_mul_f32_e32 v89, 0xbfb8aa3b, v89
	v_add_f32_e32 v77, 1.0, v77
	v_rcp_f32_e32 v77, v77
	v_exp_f32_e32 v89, v89
	v_mul_f32_e32 v77, 0xc1000000, v77
	v_mul_f32_e32 v77, v167, v77
	v_mul_f32_e32 v77, 0x3fb8aa3b, v77
	v_exp_f32_e32 v120, v77
	v_add_f32_e32 v89, 1.0, v89
	v_rcp_f32_e32 v89, v89
	v_sub_f32_e32 v77, 1.0, v120
	v_add_f32_e32 v121, 1.0, v120
	v_mul_f32_e32 v77, v77, v121
	v_max_f32_e32 v77, 0, v77
	v_sqrt_f32_e32 v77, v77
	s_nop 0
	v_mul_f32_e32 v77, v89, v77
	v_mul_f32_e32 v121, v77, v97
	v_add_f32_e32 v77, v143, v147
	v_mul_f32_e32 v77, 0xbfb8aa3b, v77
	v_exp_f32_e32 v77, v77
	v_add_f32_e32 v89, v123, v151
	v_mul_f32_e32 v89, 0xbfb8aa3b, v89
	v_exp_f32_e32 v89, v89
	v_add_f32_e32 v77, 1.0, v77
	v_rcp_f32_e32 v77, v77
	v_add_f32_e32 v89, 1.0, v89
	v_rcp_f32_e32 v89, v89
	v_mul_f32_e32 v77, 0xc1000000, v77
	v_mul_f32_e32 v77, v168, v77
	v_mul_f32_e32 v77, 0x3fb8aa3b, v77
	v_exp_f32_e32 v122, v77
	s_nop 0
	v_sub_f32_e32 v77, 1.0, v122
	v_add_f32_e32 v97, 1.0, v122
	v_mul_f32_e32 v77, v77, v97
	v_max_f32_e32 v77, 0, v77
	v_sqrt_f32_e32 v77, v77
	s_nop 0
	v_mul_f32_e32 v77, v89, v77
	v_mul_f32_e32 v123, v77, v109
	ds_write2_b64 v183, v[120:121], v[122:123] offset0:66 offset1:83
	v_mfma_f32_16x16x32_bf16 v[120:123], v[8:11], v[112:115], 0
	v_mfma_f32_16x16x32_bf16 v[112:115], v[4:7], v[112:115], 0
	v_mfma_f32_16x16x32_bf16 v[120:123], v[16:19], v[116:119], v[120:123]
	v_mfma_f32_16x16x32_bf16 v[112:115], v[12:15], v[116:119], v[112:115]
	v_mov_b32_e32 v116, v202
	v_mov_b32_e32 v117, v203
	v_mov_b32_e32 v118, v204
	v_mov_b32_e32 v119, v205
	v_mov_b32_e32 v140, v240
	v_mov_b32_e32 v141, v241
	v_mov_b32_e32 v142, v242
	v_mov_b32_e32 v143, v243
	ds_read_b64 v[144:145], v2 offset:17504
	s_waitcnt lgkmcnt(0)
	v_lshlrev_b32_e32 v77, 16, v144
	v_and_b32_e32 v89, 0xffff0000, v144
	v_lshlrev_b32_e32 v97, 16, v145
	v_and_b32_e32 v109, 0xffff0000, v145
	s_waitcnt vmcnt(1)
	v_add_f32_e32 v116, v120, v116
	v_mul_f32_e32 v116, 0xbfb8aa3b, v116
	v_exp_f32_e32 v116, v116
	s_waitcnt vmcnt(0)
	v_add_f32_e32 v112, v112, v140
	v_mul_f32_e32 v112, 0xbfb8aa3b, v112
	v_exp_f32_e32 v112, v112
	v_add_f32_e32 v116, 1.0, v116
	v_rcp_f32_e32 v116, v116
	v_add_f32_e32 v112, 1.0, v112
	v_rcp_f32_e32 v112, v112
	v_mul_f32_e32 v116, 0xc1000000, v116
	v_mul_f32_e32 v116, v169, v116
	v_mul_f32_e32 v116, 0x3fb8aa3b, v116
	v_exp_f32_e32 v144, v116
	s_nop 0
	v_sub_f32_e32 v116, 1.0, v144
	v_add_f32_e32 v120, 1.0, v144
	v_mul_f32_e32 v116, v116, v120
	v_max_f32_e32 v116, 0, v116
	v_sqrt_f32_e32 v116, v116
	s_nop 0
	v_mul_f32_e32 v112, v112, v116
	v_mul_f32_e32 v145, v112, v77
	v_add_f32_e32 v77, v121, v117
	v_mul_f32_e32 v77, 0xbfb8aa3b, v77
	v_exp_f32_e32 v77, v77
	v_add_f32_e32 v112, v113, v141
	v_mul_f32_e32 v112, 0xbfb8aa3b, v112
	v_exp_f32_e32 v112, v112
	v_add_f32_e32 v77, 1.0, v77
	v_rcp_f32_e32 v77, v77
	v_add_f32_e32 v112, 1.0, v112
	v_rcp_f32_e32 v113, v112
	v_mul_f32_e32 v77, 0xc1000000, v77
	v_mul_f32_e32 v77, v170, v77
	v_mul_f32_e32 v77, 0x3fb8aa3b, v77
	v_exp_f32_e32 v112, v77
	s_nop 0
	v_sub_f32_e32 v77, 1.0, v112
	v_add_f32_e32 v116, 1.0, v112
	v_mul_f32_e32 v77, v77, v116
	v_max_f32_e32 v77, 0, v77
	v_sqrt_f32_e32 v77, v77
	s_nop 0
	v_mul_f32_e32 v77, v113, v77
	v_mul_f32_e32 v113, v77, v89
	v_add_f32_e32 v77, v122, v118
	v_mul_f32_e32 v77, 0xbfb8aa3b, v77
	v_exp_f32_e32 v77, v77
	ds_write2_b64 v174, v[144:145], v[112:113] offset0:48 offset1:65
	v_add_f32_e32 v89, v114, v142
	v_mul_f32_e32 v89, 0xbfb8aa3b, v89
	v_add_f32_e32 v77, 1.0, v77
	v_rcp_f32_e32 v77, v77
	v_exp_f32_e32 v89, v89
	v_mul_f32_e32 v77, 0xc1000000, v77
	v_mul_f32_e32 v77, v171, v77
	v_mul_f32_e32 v77, 0x3fb8aa3b, v77
	v_exp_f32_e32 v112, v77
	v_add_f32_e32 v89, 1.0, v89
	v_rcp_f32_e32 v89, v89
	v_sub_f32_e32 v77, 1.0, v112
	v_add_f32_e32 v113, 1.0, v112
	v_mul_f32_e32 v77, v77, v113
	v_max_f32_e32 v77, 0, v77
	v_sqrt_f32_e32 v77, v77
	s_nop 0
	v_mul_f32_e32 v77, v89, v77
	v_mul_f32_e32 v113, v77, v97
	v_add_f32_e32 v77, v123, v119
	v_mul_f32_e32 v77, 0xbfb8aa3b, v77
	v_exp_f32_e32 v77, v77
	v_add_f32_e32 v89, v115, v143
	v_mul_f32_e32 v89, 0xbfb8aa3b, v89
	v_exp_f32_e32 v89, v89
	v_add_f32_e32 v77, 1.0, v77
	v_rcp_f32_e32 v77, v77
	v_add_f32_e32 v89, 1.0, v89
	v_rcp_f32_e32 v89, v89
	v_mul_f32_e32 v77, 0xc1000000, v77
	v_mul_f32_e32 v77, v172, v77
	v_mul_f32_e32 v77, 0x3fb8aa3b, v77
	v_exp_f32_e32 v114, v77
	s_nop 0
	v_sub_f32_e32 v77, 1.0, v114
	v_add_f32_e32 v97, 1.0, v114
	v_mul_f32_e32 v77, v77, v97
	v_max_f32_e32 v77, 0, v77
	v_sqrt_f32_e32 v77, v77
	s_nop 0
	v_mul_f32_e32 v77, v89, v77
	v_mul_f32_e32 v115, v77, v109
	ds_write2_b64 v174, v[112:113], v[114:115] offset0:82 offset1:99
	s_waitcnt lgkmcnt(0)
	s_barrier
	ds_read2_b64 v[116:119], v173 offset1:1
	v_mov_b32_e32 v112, v156
	v_mov_b32_e32 v114, v100
	v_pk_mul_f32 v[100:101], v[156:157], v[100:101]
	s_waitcnt lgkmcnt(0)
	v_fma_f32 v113, v69, v116, v117
	v_mov_b32_e32 v115, v118
	v_pk_mul_f32 v[140:141], v[100:101], v[102:103]
	v_pk_fma_f32 v[100:101], v[112:113], v[114:115], v[118:119]
	s_nop 0
	v_mov_b32_e32 v141, v101
	ds_read2_b64 v[120:123], v185 offset1:1
	ds_read2_b64 v[112:115], v184 offset1:1
	ds_read2_b64 v[100:103], v179 offset1:1
	s_waitcnt lgkmcnt(2)
	v_mov_b32_e32 v89, v120
	v_pk_mul_f32 v[142:143], v[140:141], v[88:89]
	v_pk_fma_f32 v[88:89], v[140:141], v[88:89], v[120:121]
	v_pk_mul_f32 v[90:91], v[142:143], v[90:91]
	v_mov_b32_e32 v140, v92
	v_mov_b32_e32 v88, v90
	v_mov_b32_e32 v141, v122
	v_pk_mul_f32 v[90:91], v[90:91], v[92:93]
	v_pk_fma_f32 v[88:89], v[88:89], v[140:141], v[122:123]
	v_pk_mul_f32 v[90:91], v[90:91], v[94:95]
	s_waitcnt lgkmcnt(1)
	v_mov_b32_e32 v97, v112
	v_mov_b32_e32 v91, v89
	v_pk_mul_f32 v[88:89], v[90:91], v[96:97]
	v_pk_fma_f32 v[90:91], v[90:91], v[96:97], v[112:113]
	v_pk_mul_f32 v[88:89], v[88:89], v[98:99]
	v_mov_b32_e32 v92, v104
	v_mov_b32_e32 v90, v88
	v_mov_b32_e32 v93, v114
	v_pk_mul_f32 v[88:89], v[88:89], v[104:105]
	v_pk_fma_f32 v[90:91], v[90:91], v[92:93], v[114:115]
	v_pk_mul_f32 v[88:89], v[88:89], v[106:107]
	s_waitcnt lgkmcnt(0)
	v_mov_b32_e32 v109, v100
	v_mov_b32_e32 v89, v91
	v_pk_mul_f32 v[90:91], v[88:89], v[108:109]
	v_pk_fma_f32 v[98:99], v[88:89], v[108:109], v[100:101]
	v_pk_mul_f32 v[96:97], v[90:91], v[110:111]
	ds_read2_b64 v[92:95], v176 offset1:1
	ds_read2_b64 v[88:91], v178 offset1:1
	v_mov_b32_e32 v98, v96
	v_mov_b32_e32 v104, v84
	v_mov_b32_e32 v105, v102
	v_pk_mul_f32 v[84:85], v[96:97], v[84:85]
	s_waitcnt lgkmcnt(1)
	v_mov_b32_e32 v125, v92
	v_pk_mul_f32 v[84:85], v[84:85], v[86:87]
	v_pk_fma_f32 v[86:87], v[98:99], v[104:105], v[102:103]
	v_mov_b32_e32 v96, v128
	v_mov_b32_e32 v85, v87
	v_pk_mul_f32 v[86:87], v[84:85], v[124:125]
	v_pk_fma_f32 v[84:85], v[84:85], v[124:125], v[92:93]
	v_pk_mul_f32 v[86:87], v[86:87], v[126:127]
	v_mov_b32_e32 v97, v94
	v_mov_b32_e32 v84, v86
	v_pk_mul_f32 v[86:87], v[86:87], v[128:129]
	v_pk_fma_f32 v[84:85], v[84:85], v[96:97], v[94:95]
	v_pk_mul_f32 v[86:87], v[86:87], v[130:131]
	s_waitcnt lgkmcnt(0)
	v_mov_b32_e32 v133, v88
	v_mov_b32_e32 v87, v85
	v_pk_mul_f32 v[84:85], v[86:87], v[132:133]
	v_pk_fma_f32 v[86:87], v[86:87], v[132:133], v[88:89]
	v_pk_mul_f32 v[84:85], v[84:85], v[134:135]
	v_mov_b32_e32 v96, v136
	v_mov_b32_e32 v86, v84
	v_mov_b32_e32 v97, v90
	v_pk_mul_f32 v[84:85], v[84:85], v[136:137]
	s_nop 0
	v_pk_mul_f32 v[124:125], v[84:85], v[138:139]
	v_pk_fma_f32 v[84:85], v[86:87], v[96:97], v[90:91]
	s_nop 0
	v_mov_b32_e32 v125, v85
	ds_read2_b64 v[96:99], v175 offset1:1
	ds_read2_b64 v[84:87], v177 offset1:1
	s_waitcnt lgkmcnt(0)
	s_barrier
	ds_read_b128 v[104:107], v180 offset:26112
	ds_read_b128 v[108:111], v180 offset:26176
	s_waitcnt lgkmcnt(1)
	v_mfma_f32_16x16x32_bf16 v[56:59], v[56:59], v[104:107], 0
	v_mfma_f32_16x16x32_bf16 v[52:55], v[52:55], v[104:107], 0
	s_waitcnt lgkmcnt(0)
	v_mfma_f32_16x16x32_bf16 v[56:59], v[64:67], v[108:111], v[56:59]
	v_mfma_f32_16x16x32_bf16 v[52:55], v[60:63], v[108:111], v[52:55]
	v_mov_b32_e32 v60, v190
	v_mov_b32_e32 v61, v191
	v_mov_b32_e32 v62, v192
	v_mov_b32_e32 v63, v193
	v_mov_b32_e32 v64, v206
	v_mov_b32_e32 v65, v207
	v_mov_b32_e32 v66, v208
	v_mov_b32_e32 v67, v209
	ds_read_b64 v[126:127], v2 offset:26112
	s_waitcnt lgkmcnt(0)
	v_lshlrev_b32_e32 v69, 16, v126
	v_and_b32_e32 v77, 0xffff0000, v126
	v_lshlrev_b32_e32 v93, 16, v127
	v_and_b32_e32 v113, 0xffff0000, v127
	v_mfma_f32_16x16x32_bf16 v[40:43], v[40:43], v[104:107], 0
	s_waitcnt vmcnt(1)
	v_add_f32_e32 v56, v56, v60
	v_mul_f32_e32 v56, 0xbfb8aa3b, v56
	v_exp_f32_e32 v56, v56
	s_waitcnt vmcnt(0)
	v_add_f32_e32 v52, v52, v64
	v_mul_f32_e32 v52, 0xbfb8aa3b, v52
	v_exp_f32_e32 v52, v52
	v_add_f32_e32 v56, 1.0, v56
	v_rcp_f32_e32 v56, v56
	v_mfma_f32_16x16x32_bf16 v[36:39], v[36:39], v[104:107], 0
	v_add_f32_e32 v52, 1.0, v52
	v_rcp_f32_e32 v52, v52
	v_mul_f32_e32 v56, 0xc1000000, v56
	v_mul_f32_e32 v1, v1, v56
	v_mul_f32_e32 v1, 0x3fb8aa3b, v1
	v_exp_f32_e32 v126, v1
	v_mfma_f32_16x16x32_bf16 v[40:43], v[48:51], v[108:111], v[40:43]
	v_sub_f32_e32 v1, 1.0, v126
	v_add_f32_e32 v56, 1.0, v126
	v_mul_f32_e32 v1, v1, v56
	v_max_f32_e32 v1, 0, v1
	v_sqrt_f32_e32 v1, v1
	v_mfma_f32_16x16x32_bf16 v[36:39], v[44:47], v[108:111], v[36:39]
	v_mul_f32_e32 v1, v52, v1
	v_mul_f32_e32 v127, v1, v69
	v_add_f32_e32 v1, v57, v61
	v_mul_f32_e32 v1, 0xbfb8aa3b, v1
	v_exp_f32_e32 v1, v1
	v_add_f32_e32 v52, v53, v65
	v_mul_f32_e32 v52, 0xbfb8aa3b, v52
	v_exp_f32_e32 v52, v52
	v_add_f32_e32 v1, 1.0, v1
	v_rcp_f32_e32 v1, v1
	v_mfma_f32_16x16x32_bf16 v[24:27], v[24:27], v[104:107], 0
	v_add_f32_e32 v52, 1.0, v52
	v_rcp_f32_e32 v53, v52
	v_mul_f32_e32 v1, 0xc1000000, v1
	v_mul_f32_e32 v1, v158, v1
	v_mul_f32_e32 v1, 0x3fb8aa3b, v1
	v_exp_f32_e32 v52, v1
	v_mfma_f32_16x16x32_bf16 v[20:23], v[20:23], v[104:107], 0
	v_mov_b32_e32 v69, v96
	v_sub_f32_e32 v1, 1.0, v52
	v_add_f32_e32 v56, 1.0, v52
	v_mul_f32_e32 v1, v1, v56
	v_max_f32_e32 v1, 0, v1
	v_sqrt_f32_e32 v1, v1
	v_mfma_f32_16x16x32_bf16 v[24:27], v[32:35], v[108:111], v[24:27]
	v_mul_f32_e32 v1, v53, v1
	v_mul_f32_e32 v53, v1, v77
	v_add_f32_e32 v1, v58, v62
	v_mul_f32_e32 v1, 0xbfb8aa3b, v1
	v_exp_f32_e32 v1, v1
	ds_write2_b64 v181, v[126:127], v[52:53] offset1:17
	v_add_f32_e32 v52, v54, v66
	v_mul_f32_e32 v52, 0xbfb8aa3b, v52
	v_add_f32_e32 v1, 1.0, v1
	v_rcp_f32_e32 v1, v1
	v_exp_f32_e32 v52, v52
	v_mfma_f32_16x16x32_bf16 v[20:23], v[28:31], v[108:111], v[20:23]
	v_mov_b32_e32 v77, v84
	v_mul_f32_e32 v1, 0xc1000000, v1
	v_mul_f32_e32 v1, v159, v1
	v_add_f32_e32 v52, 1.0, v52
	v_mul_f32_e32 v1, 0x3fb8aa3b, v1
	v_rcp_f32_e32 v53, v52
	v_exp_f32_e32 v52, v1
	v_mfma_f32_16x16x32_bf16 v[8:11], v[8:11], v[104:107], 0
	v_sub_f32_e32 v1, 1.0, v52
	v_add_f32_e32 v54, 1.0, v52
	v_mul_f32_e32 v1, v1, v54
	v_max_f32_e32 v1, 0, v1
	v_sqrt_f32_e32 v1, v1
	v_add_f32_e32 v54, v55, v67
	v_mul_f32_e32 v54, 0xbfb8aa3b, v54
	v_exp_f32_e32 v54, v54
	v_mul_f32_e32 v1, v53, v1
	v_mul_f32_e32 v53, v1, v93
	v_add_f32_e32 v1, v59, v63
	v_mul_f32_e32 v1, 0xbfb8aa3b, v1
	v_exp_f32_e32 v1, v1
	v_add_f32_e32 v54, 1.0, v54
	v_rcp_f32_e32 v55, v54
	v_mfma_f32_16x16x32_bf16 v[4:7], v[4:7], v[104:107], 0
	v_add_f32_e32 v1, 1.0, v1
	v_rcp_f32_e32 v1, v1
	v_mfma_f32_16x16x32_bf16 v[8:11], v[16:19], v[108:111], v[8:11]
	v_mul_f32_e32 v1, 0xc1000000, v1
	v_mul_f32_e32 v1, v160, v1
	v_mul_f32_e32 v1, 0x3fb8aa3b, v1
	v_exp_f32_e32 v54, v1
	v_mfma_f32_16x16x32_bf16 v[4:7], v[12:15], v[108:111], v[4:7]
	v_sub_f32_e32 v1, 1.0, v54
	v_add_f32_e32 v56, 1.0, v54
	v_mul_f32_e32 v1, v1, v56
	v_max_f32_e32 v1, 0, v1
	v_sqrt_f32_e32 v1, v1
	s_nop 0
	v_mul_f32_e32 v1, v55, v1
	v_mul_f32_e32 v55, v1, v113
	ds_write2_b64 v181, v[52:53], v[54:55] offset0:34 offset1:51
	v_mov_b32_e32 v44, v194
	v_mov_b32_e32 v45, v195
	v_mov_b32_e32 v46, v196
	v_mov_b32_e32 v47, v197
	v_mov_b32_e32 v48, v210
	v_mov_b32_e32 v49, v211
	v_mov_b32_e32 v50, v212
	v_mov_b32_e32 v51, v213
	ds_read_b64 v[52:53], v2 offset:26144
	s_waitcnt lgkmcnt(0)
	v_lshlrev_b32_e32 v1, 16, v52
	v_and_b32_e32 v54, 0xffff0000, v52
	v_lshlrev_b32_e32 v55, 16, v53
	v_and_b32_e32 v56, 0xffff0000, v53
	s_waitcnt vmcnt(1)
	v_add_f32_e32 v40, v40, v44
	v_mul_f32_e32 v40, 0xbfb8aa3b, v40
	v_exp_f32_e32 v40, v40
	s_waitcnt vmcnt(0)
	v_add_f32_e32 v36, v36, v48
	v_mul_f32_e32 v36, 0xbfb8aa3b, v36
	v_exp_f32_e32 v36, v36
	v_add_f32_e32 v40, 1.0, v40
	v_rcp_f32_e32 v40, v40
	v_add_f32_e32 v36, 1.0, v36
	v_rcp_f32_e32 v36, v36
	v_mul_f32_e32 v40, 0xc1000000, v40
	v_mul_f32_e32 v40, v161, v40
	v_mul_f32_e32 v40, 0x3fb8aa3b, v40
	v_exp_f32_e32 v52, v40
	s_nop 0
	v_sub_f32_e32 v40, 1.0, v52
	v_add_f32_e32 v44, 1.0, v52
	v_mul_f32_e32 v40, v40, v44
	v_max_f32_e32 v40, 0, v40
	v_sqrt_f32_e32 v40, v40
	s_nop 0
	v_mul_f32_e32 v36, v36, v40
	v_mul_f32_e32 v53, v36, v1
	v_add_f32_e32 v1, v41, v45
	v_mul_f32_e32 v1, 0xbfb8aa3b, v1
	v_exp_f32_e32 v1, v1
	v_add_f32_e32 v36, v37, v49
	v_mul_f32_e32 v36, 0xbfb8aa3b, v36
	v_exp_f32_e32 v36, v36
	v_add_f32_e32 v1, 1.0, v1
	v_rcp_f32_e32 v1, v1
	v_add_f32_e32 v36, 1.0, v36
	v_rcp_f32_e32 v37, v36
	v_mul_f32_e32 v1, 0xc1000000, v1
	v_mul_f32_e32 v1, v162, v1
	v_mul_f32_e32 v1, 0x3fb8aa3b, v1
	v_exp_f32_e32 v36, v1
	s_nop 0
	v_sub_f32_e32 v1, 1.0, v36
	v_add_f32_e32 v40, 1.0, v36
	v_mul_f32_e32 v1, v1, v40
	v_max_f32_e32 v1, 0, v1
	v_sqrt_f32_e32 v1, v1
	s_nop 0
	v_mul_f32_e32 v1, v37, v1
	v_mul_f32_e32 v37, v1, v54
	v_add_f32_e32 v1, v42, v46
	v_mul_f32_e32 v1, 0xbfb8aa3b, v1
	v_exp_f32_e32 v1, v1
	ds_write2_b64 v182, v[52:53], v[36:37] offset0:16 offset1:33
	v_add_f32_e32 v36, v38, v50
	v_mul_f32_e32 v36, 0xbfb8aa3b, v36
	v_add_f32_e32 v1, 1.0, v1
	v_rcp_f32_e32 v1, v1
	v_exp_f32_e32 v36, v36
	v_mul_f32_e32 v1, 0xc1000000, v1
	v_mul_f32_e32 v1, v164, v1
	v_add_f32_e32 v36, 1.0, v36
	v_mul_f32_e32 v1, 0x3fb8aa3b, v1
	v_rcp_f32_e32 v37, v36
	v_exp_f32_e32 v36, v1
	s_nop 0
	v_sub_f32_e32 v1, 1.0, v36
	v_add_f32_e32 v38, 1.0, v36
	v_mul_f32_e32 v1, v1, v38
	v_max_f32_e32 v1, 0, v1
	v_sqrt_f32_e32 v1, v1
	v_add_f32_e32 v38, v39, v51
	v_mul_f32_e32 v38, 0xbfb8aa3b, v38
	v_exp_f32_e32 v38, v38
	v_mul_f32_e32 v1, v37, v1
	v_mul_f32_e32 v37, v1, v55
	v_add_f32_e32 v1, v43, v47
	v_mul_f32_e32 v1, 0xbfb8aa3b, v1
	v_exp_f32_e32 v1, v1
	v_add_f32_e32 v38, 1.0, v38
	v_rcp_f32_e32 v39, v38
	v_add_f32_e32 v1, 1.0, v1
	v_rcp_f32_e32 v1, v1
	s_nop 0
	v_mul_f32_e32 v1, 0xc1000000, v1
	v_mul_f32_e32 v1, v166, v1
	v_mul_f32_e32 v1, 0x3fb8aa3b, v1
	v_exp_f32_e32 v38, v1
	s_nop 0
	v_sub_f32_e32 v1, 1.0, v38
	v_add_f32_e32 v40, 1.0, v38
	v_mul_f32_e32 v1, v1, v40
	v_max_f32_e32 v1, 0, v1
	v_sqrt_f32_e32 v1, v1
	s_nop 0
	v_mul_f32_e32 v1, v39, v1
	v_mul_f32_e32 v39, v1, v56
	ds_write2_b64 v182, v[36:37], v[38:39] offset0:50 offset1:67
	v_mov_b32_e32 v28, v198
	v_mov_b32_e32 v29, v199
	v_mov_b32_e32 v30, v200
	v_mov_b32_e32 v31, v201
	v_mov_b32_e32 v32, v214
	v_mov_b32_e32 v33, v215
	v_mov_b32_e32 v34, v216
	v_mov_b32_e32 v35, v217
	ds_read_b64 v[36:37], v2 offset:26176
	s_waitcnt lgkmcnt(0)
	v_lshlrev_b32_e32 v1, 16, v36
	v_and_b32_e32 v38, 0xffff0000, v36
	v_lshlrev_b32_e32 v39, 16, v37
	v_and_b32_e32 v40, 0xffff0000, v37
	s_waitcnt vmcnt(1)
	v_add_f32_e32 v24, v24, v28
	v_mul_f32_e32 v24, 0xbfb8aa3b, v24
	v_exp_f32_e32 v24, v24
	s_waitcnt vmcnt(0)
	v_add_f32_e32 v20, v20, v32
	v_mul_f32_e32 v20, 0xbfb8aa3b, v20
	v_exp_f32_e32 v20, v20
	v_add_f32_e32 v24, 1.0, v24
	v_rcp_f32_e32 v24, v24
	v_mov_b32_e32 v32, v84
	v_add_f32_e32 v20, 1.0, v20
	v_rcp_f32_e32 v20, v20
	v_mul_f32_e32 v24, 0xc1000000, v24
	v_mul_f32_e32 v24, v163, v24
	v_mul_f32_e32 v24, 0x3fb8aa3b, v24
	v_exp_f32_e32 v36, v24
	s_nop 0
	v_sub_f32_e32 v24, 1.0, v36
	v_add_f32_e32 v28, 1.0, v36
	v_mul_f32_e32 v24, v24, v28
	v_max_f32_e32 v24, 0, v24
	v_sqrt_f32_e32 v24, v24
	s_nop 0
	v_mul_f32_e32 v20, v20, v24
	v_mul_f32_e32 v37, v20, v1
	v_add_f32_e32 v1, v25, v29
	v_mul_f32_e32 v1, 0xbfb8aa3b, v1
	v_exp_f32_e32 v1, v1
	v_add_f32_e32 v20, v21, v33
	v_mul_f32_e32 v20, 0xbfb8aa3b, v20
	v_exp_f32_e32 v20, v20
	v_add_f32_e32 v1, 1.0, v1
	v_rcp_f32_e32 v1, v1
	v_add_f32_e32 v20, 1.0, v20
	v_rcp_f32_e32 v21, v20
	v_mul_f32_e32 v1, 0xc1000000, v1
	v_mul_f32_e32 v1, v165, v1
	v_mul_f32_e32 v1, 0x3fb8aa3b, v1
	v_exp_f32_e32 v20, v1
	s_nop 0
	v_sub_f32_e32 v1, 1.0, v20
	v_add_f32_e32 v24, 1.0, v20
	v_mul_f32_e32 v1, v1, v24
	v_max_f32_e32 v1, 0, v1
	v_sqrt_f32_e32 v1, v1
	s_nop 0
	v_mul_f32_e32 v1, v21, v1
	v_mul_f32_e32 v21, v1, v38
	v_add_f32_e32 v1, v26, v30
	v_mul_f32_e32 v1, 0xbfb8aa3b, v1
	v_exp_f32_e32 v1, v1
	ds_write2_b64 v183, v[36:37], v[20:21] offset0:32 offset1:49
	v_add_f32_e32 v20, v22, v34
	v_mul_f32_e32 v20, 0xbfb8aa3b, v20
	v_add_f32_e32 v1, 1.0, v1
	v_rcp_f32_e32 v1, v1
	v_exp_f32_e32 v20, v20
	v_mul_f32_e32 v1, 0xc1000000, v1
	v_mul_f32_e32 v1, v167, v1
	v_add_f32_e32 v20, 1.0, v20
	v_mul_f32_e32 v1, 0x3fb8aa3b, v1
	v_rcp_f32_e32 v21, v20
	v_exp_f32_e32 v20, v1
	s_nop 0
	v_sub_f32_e32 v1, 1.0, v20
	v_add_f32_e32 v22, 1.0, v20
	v_mul_f32_e32 v1, v1, v22
	v_max_f32_e32 v1, 0, v1
	v_sqrt_f32_e32 v1, v1
	v_add_f32_e32 v22, v23, v35
	v_mul_f32_e32 v22, 0xbfb8aa3b, v22
	v_exp_f32_e32 v22, v22
	v_mul_f32_e32 v1, v21, v1
	v_mul_f32_e32 v21, v1, v39
	v_add_f32_e32 v1, v27, v31
	v_mul_f32_e32 v1, 0xbfb8aa3b, v1
	v_exp_f32_e32 v1, v1
	v_add_f32_e32 v22, 1.0, v22
	v_rcp_f32_e32 v23, v22
	v_add_f32_e32 v1, 1.0, v1
	v_rcp_f32_e32 v1, v1
	s_nop 0
	v_mul_f32_e32 v1, 0xc1000000, v1
	v_mul_f32_e32 v1, v168, v1
	v_mul_f32_e32 v1, 0x3fb8aa3b, v1
	v_exp_f32_e32 v22, v1
	s_nop 0
	v_sub_f32_e32 v1, 1.0, v22
	v_add_f32_e32 v24, 1.0, v22
	v_mul_f32_e32 v1, v1, v24
	v_max_f32_e32 v1, 0, v1
	v_sqrt_f32_e32 v1, v1
	s_nop 0
	v_mul_f32_e32 v1, v23, v1
	v_mul_f32_e32 v23, v1, v40
	ds_write2_b64 v183, v[20:21], v[22:23] offset0:66 offset1:83
	v_mov_b32_e32 v12, v202
	v_mov_b32_e32 v13, v203
	v_mov_b32_e32 v14, v204
	v_mov_b32_e32 v15, v205
	v_mov_b32_e32 v16, v240
	v_mov_b32_e32 v17, v241
	v_mov_b32_e32 v18, v242
	v_mov_b32_e32 v19, v243
	ds_read_b64 v[20:21], v2 offset:26208
	s_waitcnt lgkmcnt(0)
	v_lshlrev_b32_e32 v1, 16, v20
	v_and_b32_e32 v2, 0xffff0000, v20
	v_lshlrev_b32_e32 v22, 16, v21
	v_and_b32_e32 v23, 0xffff0000, v21
	s_waitcnt vmcnt(1)
	v_add_f32_e32 v8, v8, v12
	v_mul_f32_e32 v8, 0xbfb8aa3b, v8
	v_exp_f32_e32 v8, v8
	s_waitcnt vmcnt(0)
	v_add_f32_e32 v4, v4, v16
	v_mul_f32_e32 v4, 0xbfb8aa3b, v4
	v_exp_f32_e32 v4, v4
	v_add_f32_e32 v8, 1.0, v8
	v_rcp_f32_e32 v8, v8
	v_add_f32_e32 v4, 1.0, v4
	v_rcp_f32_e32 v4, v4
	v_mul_f32_e32 v8, 0xc1000000, v8
	v_mul_f32_e32 v8, v169, v8
	v_mul_f32_e32 v8, 0x3fb8aa3b, v8
	v_exp_f32_e32 v20, v8
	s_nop 0
	v_sub_f32_e32 v8, 1.0, v20
	v_add_f32_e32 v12, 1.0, v20
	v_mul_f32_e32 v8, v8, v12
	v_max_f32_e32 v8, 0, v8
	v_sqrt_f32_e32 v8, v8
	v_mov_b32_e32 v12, v72
	v_mul_f32_e32 v4, v4, v8
	v_mul_f32_e32 v21, v4, v1
	v_add_f32_e32 v1, v9, v13
	v_mul_f32_e32 v1, 0xbfb8aa3b, v1
	v_exp_f32_e32 v1, v1
	v_add_f32_e32 v4, v5, v17
	v_mul_f32_e32 v4, 0xbfb8aa3b, v4
	v_exp_f32_e32 v4, v4
	v_add_f32_e32 v1, 1.0, v1
	v_rcp_f32_e32 v1, v1
	v_mov_b32_e32 v13, v98
	v_add_f32_e32 v4, 1.0, v4
	v_rcp_f32_e32 v5, v4
	v_mul_f32_e32 v1, 0xc1000000, v1
	v_mul_f32_e32 v1, v170, v1
	v_mul_f32_e32 v1, 0x3fb8aa3b, v1
	v_exp_f32_e32 v4, v1
	s_nop 0
	v_sub_f32_e32 v1, 1.0, v4
	v_add_f32_e32 v8, 1.0, v4
	v_mul_f32_e32 v1, v1, v8
	v_max_f32_e32 v1, 0, v1
	v_sqrt_f32_e32 v1, v1
	v_pk_mul_f32 v[8:9], v[124:125], v[68:69]
	v_mul_f32_e32 v1, v5, v1
	v_mul_f32_e32 v5, v1, v2
	v_add_f32_e32 v1, v10, v14
	v_mul_f32_e32 v1, 0xbfb8aa3b, v1
	v_exp_f32_e32 v1, v1
	ds_write2_b64 v174, v[20:21], v[4:5] offset0:48 offset1:65
	v_add_f32_e32 v2, v6, v18
	v_mul_f32_e32 v2, 0xbfb8aa3b, v2
	v_add_f32_e32 v1, 1.0, v1
	v_rcp_f32_e32 v1, v1
	v_exp_f32_e32 v2, v2
	v_pk_mul_f32 v[8:9], v[8:9], v[70:71]
	v_mov_b32_e32 v20, v120
	v_mul_f32_e32 v1, 0xc1000000, v1
	v_mul_f32_e32 v1, v171, v1
	v_mul_f32_e32 v1, 0x3fb8aa3b, v1
	v_exp_f32_e32 v4, v1
	v_add_f32_e32 v2, 1.0, v2
	v_rcp_f32_e32 v2, v2
	v_sub_f32_e32 v1, 1.0, v4
	v_add_f32_e32 v5, 1.0, v4
	v_mul_f32_e32 v1, v1, v5
	v_max_f32_e32 v1, 0, v1
	v_sqrt_f32_e32 v1, v1
	s_nop 0
	v_mul_f32_e32 v1, v2, v1
	v_mul_f32_e32 v5, v1, v22
	v_add_f32_e32 v1, v11, v15
	v_mul_f32_e32 v1, 0xbfb8aa3b, v1
	v_exp_f32_e32 v1, v1
	v_add_f32_e32 v2, v7, v19
	v_mul_f32_e32 v2, 0xbfb8aa3b, v2
	v_exp_f32_e32 v2, v2
	v_add_f32_e32 v1, 1.0, v1
	v_rcp_f32_e32 v1, v1
	v_pk_fma_f32 v[10:11], v[124:125], v[68:69], v[96:97]
	v_add_f32_e32 v2, 1.0, v2
	v_rcp_f32_e32 v2, v2
	v_mul_f32_e32 v1, 0xc1000000, v1
	v_mul_f32_e32 v1, v172, v1
	v_mul_f32_e32 v1, 0x3fb8aa3b, v1
	v_exp_f32_e32 v6, v1
	v_mov_b32_e32 v10, v8
	v_pk_mul_f32 v[8:9], v[8:9], v[72:73]
	v_pk_fma_f32 v[10:11], v[10:11], v[12:13], v[98:99]
	v_sub_f32_e32 v1, 1.0, v6
	v_add_f32_e32 v7, 1.0, v6
	v_mul_f32_e32 v1, v1, v7
	v_max_f32_e32 v1, 0, v1
	v_sqrt_f32_e32 v1, v1
	v_pk_mul_f32 v[8:9], v[8:9], v[74:75]
	v_mov_b32_e32 v12, v80
	v_mov_b32_e32 v9, v11
	v_mul_f32_e32 v1, v2, v1
	v_mul_f32_e32 v7, v1, v23
	ds_write2_b64 v174, v[4:5], v[6:7] offset0:82 offset1:99
	s_waitcnt lgkmcnt(0)
	s_barrier
	ds_read2_b64 v[4:7], v173 offset1:1
	v_pk_mul_f32 v[10:11], v[8:9], v[76:77]
	v_pk_fma_f32 v[8:9], v[8:9], v[76:77], v[84:85]
	v_pk_mul_f32 v[10:11], v[10:11], v[78:79]
	v_mov_b32_e32 v13, v86
	v_mov_b32_e32 v8, v10
	v_pk_mul_f32 v[10:11], v[10:11], v[80:81]
	v_pk_fma_f32 v[8:9], v[8:9], v[12:13], v[86:87]
	v_pk_mul_f32 v[10:11], v[10:11], v[82:83]
	s_waitcnt lgkmcnt(0)
	v_mov_b32_e32 v117, v4
	v_mov_b32_e32 v11, v9
	v_pk_mul_f32 v[8:9], v[10:11], v[116:117]
	v_pk_fma_f32 v[18:19], v[10:11], v[116:117], v[4:5]
	v_pk_mul_f32 v[16:17], v[8:9], v[118:119]
	ds_read2_b64 v[8:11], v185 offset1:1
	ds_read2_b64 v[12:15], v184 offset1:1
	v_mov_b32_e32 v18, v16
	v_mov_b32_e32 v21, v6
	v_pk_mul_f32 v[16:17], v[16:17], v[120:121]
	v_pk_fma_f32 v[18:19], v[18:19], v[20:21], v[6:7]
	v_pk_mul_f32 v[16:17], v[16:17], v[122:123]
	s_waitcnt lgkmcnt(1)
	v_mov_b32_e32 v113, v8
	v_mov_b32_e32 v17, v19
	v_pk_mul_f32 v[18:19], v[16:17], v[112:113]
	v_pk_fma_f32 v[16:17], v[16:17], v[112:113], v[8:9]
	v_pk_mul_f32 v[18:19], v[18:19], v[114:115]
	v_mov_b32_e32 v20, v100
	v_mov_b32_e32 v16, v18
	v_mov_b32_e32 v21, v10
	v_pk_mul_f32 v[18:19], v[18:19], v[100:101]
	v_pk_fma_f32 v[16:17], v[16:17], v[20:21], v[10:11]
	v_pk_mul_f32 v[18:19], v[18:19], v[102:103]
	s_waitcnt lgkmcnt(0)
	v_mov_b32_e32 v93, v12
	v_mov_b32_e32 v19, v17
	v_pk_mul_f32 v[16:17], v[18:19], v[92:93]
	v_pk_fma_f32 v[18:19], v[18:19], v[92:93], v[12:13]
	v_pk_mul_f32 v[16:17], v[16:17], v[94:95]
	v_mov_b32_e32 v20, v88
	v_mov_b32_e32 v18, v16
	v_mov_b32_e32 v21, v14
	v_pk_mul_f32 v[16:17], v[16:17], v[88:89]
	v_ashrrev_i32_e32 v1, 31, v0
	v_pk_mul_f32 v[28:29], v[16:17], v[90:91]
	v_pk_fma_f32 v[16:17], v[18:19], v[20:21], v[14:15]
	v_lshl_add_u64 v[0:1], v[0:1], 3, s[4:5]
	v_mov_b32_e32 v29, v17
	ds_read2_b64 v[16:19], v179 offset1:1
	ds_read2_b64 v[20:23], v176 offset1:1
	ds_read2_b64 v[24:27], v178 offset1:1
	v_readlane_b32 s4, v252, 56
	v_readlane_b32 s5, v252, 57
	s_waitcnt lgkmcnt(2)
	v_mov_b32_e32 v97, v16
	v_pk_mul_f32 v[30:31], v[28:29], v[96:97]
	v_pk_fma_f32 v[28:29], v[28:29], v[96:97], v[16:17]
	v_pk_mul_f32 v[30:31], v[30:31], v[98:99]
	v_mov_b32_e32 v33, v18
	v_mov_b32_e32 v28, v30
	v_pk_mul_f32 v[30:31], v[30:31], v[84:85]
	v_pk_fma_f32 v[28:29], v[28:29], v[32:33], v[18:19]
	v_pk_mul_f32 v[30:31], v[30:31], v[86:87]
	s_waitcnt lgkmcnt(1)
	v_mov_b32_e32 v5, v20
	v_mov_b32_e32 v31, v29
	v_pk_mul_f32 v[28:29], v[30:31], v[4:5]
	v_pk_fma_f32 v[4:5], v[30:31], v[4:5], v[20:21]
	v_pk_mul_f32 v[6:7], v[28:29], v[6:7]
	v_mov_b32_e32 v28, v8
	v_mov_b32_e32 v4, v6
	v_mov_b32_e32 v29, v22
	v_pk_mul_f32 v[6:7], v[6:7], v[8:9]
	v_pk_fma_f32 v[4:5], v[4:5], v[28:29], v[22:23]
	v_pk_mul_f32 v[6:7], v[6:7], v[10:11]
	s_waitcnt lgkmcnt(0)
	v_mov_b32_e32 v13, v24
	v_mov_b32_e32 v7, v5
	v_pk_mul_f32 v[4:5], v[6:7], v[12:13]
	v_pk_fma_f32 v[12:13], v[6:7], v[12:13], v[24:25]
	v_pk_mul_f32 v[14:15], v[4:5], v[14:15]
	ds_read2_b64 v[4:7], v175 offset1:1
	ds_read2_b64 v[8:11], v177 offset1:1
	v_mov_b32_e32 v12, v14
	v_mov_b32_e32 v28, v16
	v_mov_b32_e32 v29, v26
	v_pk_mul_f32 v[14:15], v[14:15], v[16:17]
	v_pk_fma_f32 v[12:13], v[12:13], v[28:29], v[26:27]
	v_pk_mul_f32 v[14:15], v[14:15], v[18:19]
	s_waitcnt lgkmcnt(1)
	v_mov_b32_e32 v21, v4
	v_mov_b32_e32 v15, v13
	v_pk_mul_f32 v[12:13], v[14:15], v[20:21]
	v_pk_fma_f32 v[14:15], v[14:15], v[20:21], v[4:5]
	v_pk_mul_f32 v[12:13], v[12:13], v[22:23]
	v_mov_b32_e32 v16, v24
	v_mov_b32_e32 v14, v12
	v_mov_b32_e32 v17, v6
	v_pk_mul_f32 v[12:13], v[12:13], v[24:25]
	v_pk_fma_f32 v[14:15], v[14:15], v[16:17], v[6:7]
	v_pk_mul_f32 v[12:13], v[12:13], v[26:27]
	s_waitcnt lgkmcnt(0)
	v_mov_b32_e32 v5, v8
	v_mov_b32_e32 v13, v15
	v_pk_mul_f32 v[14:15], v[12:13], v[4:5]
	v_pk_fma_f32 v[4:5], v[12:13], v[4:5], v[8:9]
	v_pk_mul_f32 v[6:7], v[14:15], v[6:7]
	v_mov_b32_e32 v12, v8
	v_mov_b32_e32 v4, v6
	v_mov_b32_e32 v13, v10
	v_pk_mul_f32 v[6:7], v[6:7], v[8:9]
	v_pk_fma_f32 v[4:5], v[4:5], v[12:13], v[10:11]
	v_pk_mul_f32 v[6:7], v[6:7], v[10:11]
	s_nop 0
	v_mov_b32_e32 v7, v5
	s_barrier
	global_store_dwordx2 v[0:1], v[6:7], off
	v_mov_b32_e32 v0, v222
	v_mov_b32_e32 v9, v3
	v_ashrrev_i32_e32 v1, 6, v0
	v_add_u32_e32 v4, s1, v1
	v_readlane_b32 s1, v252, 55
	v_ashrrev_i32_e32 v5, 31, v4
	v_bfe_u32 v81, v0, 4, 2
	v_add_u32_e32 v6, s1, v1
	v_lshlrev_b64 v[4:5], 13, v[4:5]
	v_ashrrev_i32_e32 v7, 31, v6
	v_and_b32_e32 v72, 0xffffffc0, v0
	v_and_b32_e32 v80, 15, v0
	v_lshl_add_u64 v[4:5], s[84:85], 0, v[4:5]
	v_lshlrev_b64 v[6:7], 13, v[6:7]
	v_lshlrev_b32_e32 v2, 4, v81
	v_ashrrev_i32_e32 v73, 31, v72
	v_lshl_add_u64 v[6:7], s[84:85], 0, v[6:7]
	v_lshl_add_u64 v[4:5], v[4:5], 0, v[2:3]
	v_lshlrev_b32_e32 v8, 7, v80
	v_lshlrev_b64 v[74:75], 2, v[72:73]
	v_lshl_add_u64 v[6:7], v[6:7], 0, v[2:3]
	v_lshl_add_u64 v[10:11], v[4:5], 0, v[8:9]
	v_lshl_add_u64 v[76:77], s[4:5], 0, v[74:75]
	v_readlane_b32 s4, v252, 58
	v_lshl_add_u64 v[12:13], v[6:7], 0, v[8:9]
	global_load_dwordx4 v[56:59], v[10:11], off
	global_load_dwordx4 v[52:55], v[12:13], off
	global_load_dwordx4 v[64:67], v[10:11], off offset:64
	global_load_dwordx4 v[60:63], v[12:13], off offset:64
	global_load_dwordx4 v[40:43], v[10:11], off offset:2048
	global_load_dwordx4 v[36:39], v[12:13], off offset:2048
	global_load_dwordx4 v[48:51], v[10:11], off offset:2112
	global_load_dwordx4 v[44:47], v[12:13], off offset:2112
	v_or_b32_e32 v10, 0x1000, v8
	v_mov_b32_e32 v11, v3
	v_readlane_b32 s5, v252, 59
	v_lshl_add_u64 v[12:13], v[4:5], 0, v[10:11]
	v_or_b32_e32 v8, 0x1800, v8
	v_lshl_add_u64 v[68:69], s[4:5], 0, v[74:75]
	v_lshl_add_u64 v[10:11], v[6:7], 0, v[10:11]
	global_load_dwordx4 v[24:27], v[12:13], off
	global_load_dwordx4 v[20:23], v[10:11], off
	global_load_dwordx4 v[32:35], v[12:13], off offset:64
	global_load_dwordx4 v[28:31], v[10:11], off offset:64
	v_lshl_add_u64 v[12:13], v[4:5], 0, v[8:9]
	v_lshl_add_u64 v[14:15], v[6:7], 0, v[8:9]
	v_lshl_add_u64 v[78:79], v[68:69], 0, v[2:3]
	global_load_dwordx4 v[8:11], v[12:13], off
	global_load_dwordx4 v[4:7], v[14:15], off
	global_load_dwordx4 v[16:19], v[12:13], off offset:64
	s_nop 0
	global_load_dwordx4 v[12:15], v[14:15], off offset:64
	v_readlane_b32 s4, v252, 60
	v_readlane_b32 s5, v252, 61
	s_movk_i32 s1, 0x218
	v_lshlrev_b32_e32 v113, 1, v72
	v_lshl_add_u64 v[152:153], v[76:77], 0, v[2:3]
	v_lshlrev_b32_e32 v112, 3, v81
	s_waitcnt vmcnt(0)
	s_lshl_b32 s98, s16, 11
	s_add_u32 s98, s98, 0x8400
	s_add_u32 s98, s30, s98
	s_addc_u32 s99, s31, 0
	v_lshrrev_b32_e32 v173, 4, v222
	v_and_b32_e32 v172, 3, v173
	v_lshrrev_b32_e32 v173, 2, v173
	v_lshlrev_b32_e32 v172, 4, v172
	v_lshl_or_b32 v173, v173, 8, v172
	global_load_dword v1, v173, s[98:99]
	global_load_dword v158, v173, s[98:99] offset:4
	global_load_dword v159, v173, s[98:99] offset:8
	global_load_dword v160, v173, s[98:99] offset:12
	global_load_dword v161, v173, s[98:99] offset:64
	global_load_dword v162, v173, s[98:99] offset:68
	global_load_dword v164, v173, s[98:99] offset:72
	global_load_dword v166, v173, s[98:99] offset:76
	global_load_dword v163, v173, s[98:99] offset:128
	global_load_dword v165, v173, s[98:99] offset:132
	global_load_dword v167, v173, s[98:99] offset:136
	global_load_dword v168, v173, s[98:99] offset:140
	global_load_dword v169, v173, s[98:99] offset:192
	global_load_dword v170, v173, s[98:99] offset:196
	global_load_dword v172, v173, s[98:99] offset:200
	global_load_dword v173, v173, s[98:99] offset:204
	v_lshl_add_u32 v92, v80, 3, 32
	v_lshl_or_b32 v93, v81, 2, v72
	v_lshl_add_u64 v[68:69], s[4:5], 0, v[74:75]
	v_lshl_add_u64 v[154:155], v[68:69], 0, v[2:3]
	v_mul_lo_u32 v68, v0, s10
	v_add_u32_e32 v108, 32, v68
	v_mad_u32_u24 v68, v80, s1, v92
	v_add3_u32 v176, v68, v113, v2
	ds_read_b128 v[68:71], v176 offset:26112
	ds_read_b128 v[72:75], v176 offset:26176
	global_load_dwordx4 v[190:193], v[154:155], off
	global_load_dwordx4 v[206:209], v[152:153], off
	global_load_dwordx4 v[194:197], v[154:155], off offset:64
	global_load_dwordx4 v[210:213], v[152:153], off offset:64
	global_load_dwordx4 v[198:201], v[154:155], off offset:128
	global_load_dwordx4 v[214:217], v[152:153], off offset:128
	global_load_dwordx4 v[202:205], v[154:155], off offset:192
	global_load_dwordx4 v[240:243], v[152:153], off offset:192
	s_waitcnt vmcnt(0)
	v_mov_b32_e32 v84, v190
	v_mov_b32_e32 v85, v191
	v_mov_b32_e32 v86, v192
	v_mov_b32_e32 v87, v193
	v_mov_b32_e32 v88, v206
	v_mov_b32_e32 v89, v207
	v_mov_b32_e32 v90, v208
	v_mov_b32_e32 v91, v209
	s_waitcnt lgkmcnt(1)
	v_mfma_f32_16x16x32_bf16 v[76:79], v[56:59], v[68:71], 0
	v_sub_u32_e32 v174, v176, v112
	ds_read_b64 v[94:95], v174 offset:26112
	v_mad_u64_u32 v[92:93], s[4:5], v93, s10, v[92:93]
	s_waitcnt lgkmcnt(1)
	v_mfma_f32_16x16x32_bf16 v[80:83], v[64:67], v[72:75], v[76:79]
	v_add_u32_e32 v177, 0x8800, v92
	s_waitcnt lgkmcnt(0)
	v_lshlrev_b32_e32 v96, 16, v94
	v_and_b32_e32 v97, 0xffff0000, v94
	v_mfma_f32_16x16x32_bf16 v[76:79], v[52:55], v[68:71], 0
	v_lshlrev_b32_e32 v98, 16, v95
	v_and_b32_e32 v99, 0xffff0000, v95
	v_add_u32_e32 v178, 0x9000, v92
	v_mfma_f32_16x16x32_bf16 v[76:79], v[60:63], v[72:75], v[76:79]
	v_add_u32_e32 v179, 0x9800, v92
	v_add_u32_e32 v175, 0xa000, v92
	v_add_u32_e32 v183, 0x8870, v108
	v_add_u32_e32 v180, 0x8860, v108
	v_add_u32_e32 v182, 0x8850, v108
	v_add_u32_e32 v184, 0x8830, v108
	v_add_u32_e32 v181, 0x8840, v108
	v_add_u32_e32 v171, 0x8800, v108
	v_add_u32_e32 v186, 0x8820, v108
	v_add_u32_e32 v185, 0x8810, v108
	s_addc_u32 s1, s8, 0
	s_waitcnt vmcnt(1)
	v_add_f32_e32 v80, v80, v84
	v_mul_f32_e32 v80, 0xbfb8aa3b, v80
	v_exp_f32_e32 v80, v80
	s_waitcnt vmcnt(0)
	v_add_f32_e32 v76, v76, v88
	v_mul_f32_e32 v76, 0xbfb8aa3b, v76
	v_exp_f32_e32 v76, v76
	v_add_f32_e32 v80, 1.0, v80
	v_rcp_f32_e32 v80, v80
	v_add_f32_e32 v77, v77, v89
	v_add_f32_e32 v76, 1.0, v76
	v_rcp_f32_e32 v76, v76
	v_mul_f32_e32 v80, 0xc1000000, v80
	s_waitcnt vmcnt(0)
	v_mul_f32_e32 v80, v80, v1
	v_mul_f32_e32 v80, 0x3fb8aa3b, v80
	v_exp_f32_e32 v94, v80
	v_mul_f32_e32 v77, 0xbfb8aa3b, v77
	v_exp_f32_e32 v77, v77
	v_add_f32_e32 v79, v79, v91
	v_sub_f32_e32 v80, 1.0, v94
	v_add_f32_e32 v84, 1.0, v94
	v_mul_f32_e32 v80, v80, v84
	v_max_f32_e32 v80, 0, v80
	v_sqrt_f32_e32 v80, v80
	v_add_f32_e32 v77, 1.0, v77
	v_rcp_f32_e32 v77, v77
	v_mul_f32_e32 v79, 0xbfb8aa3b, v79
	v_mul_f32_e32 v76, v76, v80
	v_mul_f32_e32 v95, v76, v96
	v_add_f32_e32 v76, v81, v85
	v_mul_f32_e32 v76, 0xbfb8aa3b, v76
	v_exp_f32_e32 v76, v76
	v_exp_f32_e32 v79, v79
	v_add_f32_e32 v76, 1.0, v76
	v_rcp_f32_e32 v76, v76
	v_add_f32_e32 v79, 1.0, v79
	v_rcp_f32_e32 v79, v79
	v_mul_f32_e32 v76, 0xc1000000, v76
	v_mul_f32_e32 v76, v76, v158
	v_mul_f32_e32 v76, 0x3fb8aa3b, v76
	v_exp_f32_e32 v76, v76
	s_nop 0
	v_sub_f32_e32 v80, 1.0, v76
	v_add_f32_e32 v81, 1.0, v76
	v_mul_f32_e32 v80, v80, v81
	v_max_f32_e32 v80, 0, v80
	v_sqrt_f32_e32 v80, v80
	s_nop 0
	v_mul_f32_e32 v77, v77, v80
	v_mul_f32_e32 v77, v77, v97
	ds_write2_b64 v177, v[94:95], v[76:77] offset1:17
	v_add_f32_e32 v76, v82, v86
	v_mul_f32_e32 v76, 0xbfb8aa3b, v76
	v_exp_f32_e32 v76, v76
	v_add_f32_e32 v77, v78, v90
	v_mul_f32_e32 v77, 0xbfb8aa3b, v77
	v_exp_f32_e32 v77, v77
	v_add_f32_e32 v76, 1.0, v76
	v_rcp_f32_e32 v76, v76
	v_add_f32_e32 v77, 1.0, v77
	v_rcp_f32_e32 v77, v77
	v_mul_f32_e32 v76, 0xc1000000, v76
	v_mul_f32_e32 v76, v76, v159
	v_mul_f32_e32 v76, 0x3fb8aa3b, v76
	v_exp_f32_e32 v76, v76
	s_nop 0
	v_sub_f32_e32 v78, 1.0, v76
	v_add_f32_e32 v80, 1.0, v76
	v_mul_f32_e32 v78, v78, v80
	v_max_f32_e32 v78, 0, v78
	v_sqrt_f32_e32 v78, v78
	s_nop 0
	v_mul_f32_e32 v77, v77, v78
	v_add_f32_e32 v78, v83, v87
	v_mul_f32_e32 v78, 0xbfb8aa3b, v78
	v_exp_f32_e32 v78, v78
	v_mul_f32_e32 v77, v77, v98
	v_add_f32_e32 v78, 1.0, v78
	v_rcp_f32_e32 v78, v78
	s_nop 0
	v_mul_f32_e32 v78, 0xc1000000, v78
	v_mul_f32_e32 v78, v78, v160
	v_mul_f32_e32 v78, 0x3fb8aa3b, v78
	v_exp_f32_e32 v78, v78
	s_nop 0
	v_sub_f32_e32 v80, 1.0, v78
	v_add_f32_e32 v81, 1.0, v78
	v_mul_f32_e32 v80, v80, v81
	v_max_f32_e32 v80, 0, v80
	v_sqrt_f32_e32 v80, v80
	s_nop 0
	v_mul_f32_e32 v79, v79, v80
	v_mul_f32_e32 v79, v79, v99
	ds_write2_b64 v177, v[76:77], v[78:79] offset0:34 offset1:51
	v_mov_b32_e32 v84, v194
	v_mov_b32_e32 v85, v195
	v_mov_b32_e32 v86, v196
	v_mov_b32_e32 v87, v197
	v_mov_b32_e32 v88, v210
	v_mov_b32_e32 v89, v211
	v_mov_b32_e32 v90, v212
	v_mov_b32_e32 v91, v213
	v_mfma_f32_16x16x32_bf16 v[76:79], v[40:43], v[68:71], 0
	ds_read_b64 v[94:95], v174 offset:26144
	s_waitcnt lgkmcnt(0)
	v_lshlrev_b32_e32 v93, 16, v94
	v_mfma_f32_16x16x32_bf16 v[80:83], v[48:51], v[72:75], v[76:79]
	v_and_b32_e32 v96, 0xffff0000, v94
	v_lshlrev_b32_e32 v97, 16, v95
	v_and_b32_e32 v98, 0xffff0000, v95
	v_mfma_f32_16x16x32_bf16 v[76:79], v[36:39], v[68:71], 0
	v_mfma_f32_16x16x32_bf16 v[76:79], v[44:47], v[72:75], v[76:79]
	s_waitcnt vmcnt(1)
	s_nop 1
	v_add_f32_e32 v80, v80, v84
	v_mul_f32_e32 v80, 0xbfb8aa3b, v80
	v_exp_f32_e32 v80, v80
	s_waitcnt vmcnt(0)
	s_nop 0
	v_add_f32_e32 v76, v76, v88
	v_mul_f32_e32 v76, 0xbfb8aa3b, v76
	v_exp_f32_e32 v76, v76
	v_add_f32_e32 v80, 1.0, v80
	v_rcp_f32_e32 v80, v80
	v_add_f32_e32 v77, v77, v89
	v_add_f32_e32 v76, 1.0, v76
	v_rcp_f32_e32 v76, v76
	v_mul_f32_e32 v80, 0xc1000000, v80
	v_mul_f32_e32 v80, v80, v161
	v_mul_f32_e32 v80, 0x3fb8aa3b, v80
	v_exp_f32_e32 v94, v80
	v_mul_f32_e32 v77, 0xbfb8aa3b, v77
	v_exp_f32_e32 v77, v77
	v_add_f32_e32 v79, v79, v91
	v_sub_f32_e32 v80, 1.0, v94
	v_add_f32_e32 v84, 1.0, v94
	v_mul_f32_e32 v80, v80, v84
	v_max_f32_e32 v80, 0, v80
	v_sqrt_f32_e32 v80, v80
	v_add_f32_e32 v77, 1.0, v77
	v_rcp_f32_e32 v77, v77
	v_mul_f32_e32 v79, 0xbfb8aa3b, v79
	v_mul_f32_e32 v76, v76, v80
	v_mul_f32_e32 v95, v76, v93
	v_add_f32_e32 v76, v81, v85
	v_mul_f32_e32 v76, 0xbfb8aa3b, v76
	v_exp_f32_e32 v76, v76
	v_exp_f32_e32 v79, v79
	v_add_f32_e32 v76, 1.0, v76
	v_rcp_f32_e32 v76, v76
	v_add_f32_e32 v79, 1.0, v79
	v_rcp_f32_e32 v79, v79
	v_mul_f32_e32 v76, 0xc1000000, v76
	v_mul_f32_e32 v76, v76, v162
	v_mul_f32_e32 v76, 0x3fb8aa3b, v76
	v_exp_f32_e32 v76, v76
	s_nop 0
	v_sub_f32_e32 v80, 1.0, v76
	v_add_f32_e32 v81, 1.0, v76
	v_mul_f32_e32 v80, v80, v81
	v_max_f32_e32 v80, 0, v80
	v_sqrt_f32_e32 v80, v80
	s_nop 0
	v_mul_f32_e32 v77, v77, v80
	v_mul_f32_e32 v77, v77, v96
	ds_write2_b64 v178, v[94:95], v[76:77] offset0:16 offset1:33
	v_add_f32_e32 v76, v82, v86
	v_mul_f32_e32 v76, 0xbfb8aa3b, v76
	v_exp_f32_e32 v76, v76
	v_add_f32_e32 v77, v78, v90
	v_mul_f32_e32 v77, 0xbfb8aa3b, v77
	v_exp_f32_e32 v77, v77
	v_add_f32_e32 v76, 1.0, v76
	v_rcp_f32_e32 v76, v76
	v_add_f32_e32 v77, 1.0, v77
	v_rcp_f32_e32 v77, v77
	v_mul_f32_e32 v76, 0xc1000000, v76
	v_mul_f32_e32 v76, v76, v164
	v_mul_f32_e32 v76, 0x3fb8aa3b, v76
	v_exp_f32_e32 v76, v76
	s_nop 0
	v_sub_f32_e32 v78, 1.0, v76
	v_add_f32_e32 v80, 1.0, v76
	v_mul_f32_e32 v78, v78, v80
	v_max_f32_e32 v78, 0, v78
	v_sqrt_f32_e32 v78, v78
	s_nop 0
	v_mul_f32_e32 v77, v77, v78
	v_add_f32_e32 v78, v83, v87
	v_mul_f32_e32 v78, 0xbfb8aa3b, v78
	v_exp_f32_e32 v78, v78
	v_mul_f32_e32 v77, v77, v97
	v_add_f32_e32 v78, 1.0, v78
	v_rcp_f32_e32 v78, v78
	s_nop 0
	v_mul_f32_e32 v78, 0xc1000000, v78
	v_mul_f32_e32 v78, v78, v166
	v_mul_f32_e32 v78, 0x3fb8aa3b, v78
	v_exp_f32_e32 v78, v78
	s_nop 0
	v_sub_f32_e32 v80, 1.0, v78
	v_add_f32_e32 v81, 1.0, v78
	v_mul_f32_e32 v80, v80, v81
	v_max_f32_e32 v80, 0, v80
	v_sqrt_f32_e32 v80, v80
	s_nop 0
	v_mul_f32_e32 v79, v79, v80
	v_mul_f32_e32 v79, v79, v98
	ds_write2_b64 v178, v[76:77], v[78:79] offset0:50 offset1:67
	v_mov_b32_e32 v84, v198
	v_mov_b32_e32 v85, v199
	v_mov_b32_e32 v86, v200
	v_mov_b32_e32 v87, v201
	v_mov_b32_e32 v88, v214
	v_mov_b32_e32 v89, v215
	v_mov_b32_e32 v90, v216
	v_mov_b32_e32 v91, v217
	v_mfma_f32_16x16x32_bf16 v[76:79], v[24:27], v[68:71], 0
	ds_read_b64 v[94:95], v174 offset:26176
	s_waitcnt lgkmcnt(0)
	v_lshlrev_b32_e32 v93, 16, v94
	v_mfma_f32_16x16x32_bf16 v[80:83], v[32:35], v[72:75], v[76:79]
	v_and_b32_e32 v96, 0xffff0000, v94
	v_lshlrev_b32_e32 v97, 16, v95
	v_and_b32_e32 v98, 0xffff0000, v95
	v_mfma_f32_16x16x32_bf16 v[76:79], v[20:23], v[68:71], 0
	v_mfma_f32_16x16x32_bf16 v[76:79], v[28:31], v[72:75], v[76:79]
	s_waitcnt vmcnt(1)
	s_nop 1
	v_add_f32_e32 v80, v80, v84
	v_mul_f32_e32 v80, 0xbfb8aa3b, v80
	v_exp_f32_e32 v80, v80
	s_waitcnt vmcnt(0)
	s_nop 0
	v_add_f32_e32 v76, v76, v88
	v_mul_f32_e32 v76, 0xbfb8aa3b, v76
	v_exp_f32_e32 v76, v76
	v_add_f32_e32 v80, 1.0, v80
	v_rcp_f32_e32 v80, v80
	v_add_f32_e32 v77, v77, v89
	v_add_f32_e32 v76, 1.0, v76
	v_rcp_f32_e32 v76, v76
	v_mul_f32_e32 v80, 0xc1000000, v80
	v_mul_f32_e32 v80, v80, v163
	v_mul_f32_e32 v80, 0x3fb8aa3b, v80
	v_exp_f32_e32 v94, v80
	v_mul_f32_e32 v77, 0xbfb8aa3b, v77
	v_exp_f32_e32 v77, v77
	v_add_f32_e32 v79, v79, v91
	v_sub_f32_e32 v80, 1.0, v94
	v_add_f32_e32 v84, 1.0, v94
	v_mul_f32_e32 v80, v80, v84
	v_max_f32_e32 v80, 0, v80
	v_sqrt_f32_e32 v80, v80
	v_add_f32_e32 v77, 1.0, v77
	v_rcp_f32_e32 v77, v77
	v_mul_f32_e32 v79, 0xbfb8aa3b, v79
	v_mul_f32_e32 v76, v76, v80
	v_mul_f32_e32 v95, v76, v93
	v_add_f32_e32 v76, v81, v85
	v_mul_f32_e32 v76, 0xbfb8aa3b, v76
	v_exp_f32_e32 v76, v76
	v_exp_f32_e32 v79, v79
	v_add_f32_e32 v76, 1.0, v76
	v_rcp_f32_e32 v76, v76
	v_add_f32_e32 v79, 1.0, v79
	v_rcp_f32_e32 v79, v79
	v_mul_f32_e32 v76, 0xc1000000, v76
	v_mul_f32_e32 v76, v76, v165
	v_mul_f32_e32 v76, 0x3fb8aa3b, v76
	v_exp_f32_e32 v76, v76
	s_nop 0
	v_sub_f32_e32 v80, 1.0, v76
	v_add_f32_e32 v81, 1.0, v76
	v_mul_f32_e32 v80, v80, v81
	v_max_f32_e32 v80, 0, v80
	v_sqrt_f32_e32 v80, v80
	s_nop 0
	v_mul_f32_e32 v77, v77, v80
	v_mul_f32_e32 v77, v77, v96
	ds_write2_b64 v179, v[94:95], v[76:77] offset0:32 offset1:49
	v_add_f32_e32 v76, v82, v86
	v_mul_f32_e32 v76, 0xbfb8aa3b, v76
	v_exp_f32_e32 v76, v76
	v_add_f32_e32 v77, v78, v90
	v_mul_f32_e32 v77, 0xbfb8aa3b, v77
	v_exp_f32_e32 v77, v77
	v_add_f32_e32 v76, 1.0, v76
	v_rcp_f32_e32 v76, v76
	v_add_f32_e32 v77, 1.0, v77
	v_rcp_f32_e32 v77, v77
	v_mul_f32_e32 v76, 0xc1000000, v76
	v_mul_f32_e32 v76, v76, v167
	v_mul_f32_e32 v76, 0x3fb8aa3b, v76
	v_exp_f32_e32 v76, v76
	s_nop 0
	v_sub_f32_e32 v78, 1.0, v76
	v_add_f32_e32 v80, 1.0, v76
	v_mul_f32_e32 v78, v78, v80
	v_max_f32_e32 v78, 0, v78
	v_sqrt_f32_e32 v78, v78
	s_nop 0
	v_mul_f32_e32 v77, v77, v78
	v_add_f32_e32 v78, v83, v87
	v_mul_f32_e32 v78, 0xbfb8aa3b, v78
	v_exp_f32_e32 v78, v78
	v_mul_f32_e32 v77, v77, v97
	v_add_f32_e32 v78, 1.0, v78
	v_rcp_f32_e32 v78, v78
	s_nop 0
	v_mul_f32_e32 v78, 0xc1000000, v78
	v_mul_f32_e32 v78, v78, v168
	v_mul_f32_e32 v78, 0x3fb8aa3b, v78
	v_exp_f32_e32 v78, v78
	s_nop 0
	v_sub_f32_e32 v80, 1.0, v78
	v_add_f32_e32 v81, 1.0, v78
	v_mul_f32_e32 v80, v80, v81
	v_max_f32_e32 v80, 0, v80
	v_sqrt_f32_e32 v80, v80
	s_nop 0
	v_mul_f32_e32 v79, v79, v80
	v_mul_f32_e32 v79, v79, v98
	ds_write2_b64 v179, v[76:77], v[78:79] offset0:66 offset1:83
	v_mfma_f32_16x16x32_bf16 v[76:79], v[8:11], v[68:71], 0
	v_mfma_f32_16x16x32_bf16 v[68:71], v[4:7], v[68:71], 0
	v_mfma_f32_16x16x32_bf16 v[76:79], v[16:19], v[72:75], v[76:79]
	v_mfma_f32_16x16x32_bf16 v[68:71], v[12:15], v[72:75], v[68:71]
	v_mov_b32_e32 v72, v202
	v_mov_b32_e32 v73, v203
	v_mov_b32_e32 v74, v204
	v_mov_b32_e32 v75, v205
	v_mov_b32_e32 v80, v240
	v_mov_b32_e32 v81, v241
	v_mov_b32_e32 v82, v242
	v_mov_b32_e32 v83, v243
	ds_read_b64 v[84:85], v174 offset:26208
	s_waitcnt lgkmcnt(0)
	v_lshlrev_b32_e32 v86, 16, v84
	v_and_b32_e32 v87, 0xffff0000, v84
	v_lshlrev_b32_e32 v88, 16, v85
	v_and_b32_e32 v89, 0xffff0000, v85
	s_waitcnt vmcnt(1)
	v_add_f32_e32 v72, v76, v72
	v_mul_f32_e32 v72, 0xbfb8aa3b, v72
	v_exp_f32_e32 v72, v72
	s_waitcnt vmcnt(0)
	v_add_f32_e32 v68, v68, v80
	v_mul_f32_e32 v68, 0xbfb8aa3b, v68
	v_exp_f32_e32 v68, v68
	v_add_f32_e32 v72, 1.0, v72
	v_rcp_f32_e32 v72, v72
	v_add_f32_e32 v69, v69, v81
	v_add_f32_e32 v68, 1.0, v68
	v_rcp_f32_e32 v68, v68
	v_mul_f32_e32 v72, 0xc1000000, v72
	v_mul_f32_e32 v72, v169, v72
	v_mul_f32_e32 v72, 0x3fb8aa3b, v72
	v_exp_f32_e32 v84, v72
	v_mul_f32_e32 v69, 0xbfb8aa3b, v69
	v_exp_f32_e32 v69, v69
	v_add_f32_e32 v71, v71, v83
	v_sub_f32_e32 v72, 1.0, v84
	v_add_f32_e32 v76, 1.0, v84
	v_mul_f32_e32 v72, v72, v76
	v_max_f32_e32 v72, 0, v72
	v_sqrt_f32_e32 v72, v72
	v_add_f32_e32 v69, 1.0, v69
	v_rcp_f32_e32 v69, v69
	v_mul_f32_e32 v71, 0xbfb8aa3b, v71
	v_mul_f32_e32 v68, v68, v72
	v_mul_f32_e32 v85, v68, v86
	v_add_f32_e32 v68, v77, v73
	v_mul_f32_e32 v68, 0xbfb8aa3b, v68
	v_exp_f32_e32 v68, v68
	v_exp_f32_e32 v71, v71
	v_add_f32_e32 v68, 1.0, v68
	v_rcp_f32_e32 v68, v68
	v_add_f32_e32 v71, 1.0, v71
	v_rcp_f32_e32 v71, v71
	v_mul_f32_e32 v68, 0xc1000000, v68
	v_mul_f32_e32 v68, v170, v68
	v_mul_f32_e32 v68, 0x3fb8aa3b, v68
	v_exp_f32_e32 v68, v68
	s_nop 0
	v_sub_f32_e32 v72, 1.0, v68
	v_add_f32_e32 v73, 1.0, v68
	v_mul_f32_e32 v72, v72, v73
	v_max_f32_e32 v72, 0, v72
	v_sqrt_f32_e32 v72, v72
	s_nop 0
	v_mul_f32_e32 v69, v69, v72
	v_mul_f32_e32 v69, v69, v87
	ds_write2_b64 v175, v[84:85], v[68:69] offset0:48 offset1:65
	v_add_f32_e32 v68, v78, v74
	v_mul_f32_e32 v68, 0xbfb8aa3b, v68
	v_exp_f32_e32 v68, v68
	v_add_f32_e32 v69, v70, v82
	v_mul_f32_e32 v69, 0xbfb8aa3b, v69
	v_exp_f32_e32 v69, v69
	v_add_f32_e32 v68, 1.0, v68
	v_rcp_f32_e32 v68, v68
	v_add_f32_e32 v69, 1.0, v69
	v_rcp_f32_e32 v69, v69
	v_mul_f32_e32 v68, 0xc1000000, v68
	v_mul_f32_e32 v68, v172, v68
	v_mul_f32_e32 v68, 0x3fb8aa3b, v68
	v_exp_f32_e32 v68, v68
	s_nop 0
	v_sub_f32_e32 v70, 1.0, v68
	v_add_f32_e32 v72, 1.0, v68
	v_mul_f32_e32 v70, v70, v72
	v_max_f32_e32 v70, 0, v70
	v_sqrt_f32_e32 v70, v70
	s_nop 0
	v_mul_f32_e32 v69, v69, v70
	v_add_f32_e32 v70, v79, v75
	v_mul_f32_e32 v70, 0xbfb8aa3b, v70
	v_exp_f32_e32 v70, v70
	v_mul_f32_e32 v69, v69, v88
	v_add_f32_e32 v70, 1.0, v70
	v_rcp_f32_e32 v70, v70
	s_nop 0
	v_mul_f32_e32 v70, 0xc1000000, v70
	v_mul_f32_e32 v70, v173, v70
	v_mul_f32_e32 v70, 0x3fb8aa3b, v70
	v_exp_f32_e32 v70, v70
	s_nop 0
	v_sub_f32_e32 v72, 1.0, v70
	v_add_f32_e32 v73, 1.0, v70
	v_mul_f32_e32 v72, v72, v73
	v_max_f32_e32 v72, 0, v72
	v_sqrt_f32_e32 v72, v72
	s_nop 0
	v_mul_f32_e32 v71, v71, v72
	v_mul_f32_e32 v71, v71, v89
	ds_write2_b64 v175, v[68:69], v[70:71] offset0:82 offset1:99
	s_waitcnt lgkmcnt(0)
	s_barrier
	ds_read2_b64 v[68:71], v183 offset1:1
	ds_read2_b64 v[96:99], v184 offset1:1
	ds_read2_b64 v[104:107], v180 offset1:1
	ds_read2_b64 v[84:87], v171 offset1:1
	ds_read2_b64 v[88:91], v182 offset1:1
	ds_read2_b64 v[92:95], v181 offset1:1
	s_waitcnt lgkmcnt(5)
	v_fma_f32 v72, 0, v70, v71
	v_pk_mul_f32 v[156:157], v[70:71], v[68:69]
	v_fmac_f32_e32 v69, v68, v72
	s_waitcnt lgkmcnt(3)
	v_fma_f32 v68, v106, v69, v107
	v_fma_f32 v68, v104, v68, v105
	s_waitcnt lgkmcnt(1)
	v_fma_f32 v68, v90, v68, v91
	v_fma_f32 v68, v88, v68, v89
	ds_read2_b64 v[100:103], v186 offset1:1
	ds_read2_b64 v[108:111], v185 offset1:1
	s_waitcnt lgkmcnt(2)
	v_fma_f32 v68, v94, v68, v95
	v_fma_f32 v68, v92, v68, v93
	v_fma_f32 v68, v98, v68, v99
	v_fma_f32 v68, v96, v68, v97
	s_waitcnt lgkmcnt(1)
	v_fma_f32 v68, v102, v68, v103
	v_fma_f32 v68, v100, v68, v101
	s_waitcnt lgkmcnt(0)
	v_fma_f32 v68, v110, v68, v111
	v_fma_f32 v68, v108, v68, v109
	v_fma_f32 v68, v86, v68, v87
	v_fma_f32 v91, v84, v68, v85
	v_or_b32_e32 v68, 0xfffff0, v0
	v_mad_i32_i24 v68, v68, s9, 32
	v_add3_u32 v2, v68, v113, v2
	s_barrier
	ds_read_b128 v[68:71], v2 offset:26112
	ds_read_b128 v[72:75], v2 offset:26176
	v_sub_u32_e32 v2, v2, v112
	v_mov_b32_e32 v112, v190
	v_mov_b32_e32 v113, v191
	v_mov_b32_e32 v114, v192
	v_mov_b32_e32 v115, v193
	v_mov_b32_e32 v116, v206
	v_mov_b32_e32 v117, v207
	v_mov_b32_e32 v118, v208
	v_mov_b32_e32 v119, v209
	s_waitcnt lgkmcnt(1)
	v_mfma_f32_16x16x32_bf16 v[76:79], v[56:59], v[68:71], 0
	ds_read_b64 v[120:121], v2 offset:26112
	s_waitcnt lgkmcnt(0)
	v_lshlrev_b32_e32 v99, 16, v120
	v_mfma_f32_16x16x32_bf16 v[76:79], v[64:67], v[72:75], v[76:79]
	v_and_b32_e32 v111, 0xffff0000, v120
	v_lshlrev_b32_e32 v122, 16, v121
	v_and_b32_e32 v123, 0xffff0000, v121
	v_mfma_f32_16x16x32_bf16 v[80:83], v[52:55], v[68:71], 0
	v_mfma_f32_16x16x32_bf16 v[80:83], v[60:63], v[72:75], v[80:83]
	s_waitcnt vmcnt(1)
	s_nop 1
	v_add_f32_e32 v76, v76, v112
	v_mul_f32_e32 v76, 0xbfb8aa3b, v76
	v_exp_f32_e32 v76, v76
	s_waitcnt vmcnt(0)
	s_nop 0
	v_add_f32_e32 v80, v80, v116
	v_mul_f32_e32 v80, 0xbfb8aa3b, v80
	v_exp_f32_e32 v80, v80
	v_add_f32_e32 v76, 1.0, v76
	v_rcp_f32_e32 v76, v76
	v_add_f32_e32 v80, 1.0, v80
	v_rcp_f32_e32 v80, v80
	v_mul_f32_e32 v76, 0xc1000000, v76
	v_mul_f32_e32 v76, v1, v76
	v_mul_f32_e32 v76, 0x3fb8aa3b, v76
	v_exp_f32_e32 v120, v76
	s_nop 0
	v_sub_f32_e32 v76, 1.0, v120
	v_add_f32_e32 v112, 1.0, v120
	v_mul_f32_e32 v76, v76, v112
	v_max_f32_e32 v76, 0, v76
	v_sqrt_f32_e32 v76, v76
	s_nop 0
	v_mul_f32_e32 v76, v80, v76
	v_mul_f32_e32 v121, v76, v99
	v_add_f32_e32 v76, v77, v113
	v_mul_f32_e32 v76, 0xbfb8aa3b, v76
	v_exp_f32_e32 v76, v76
	v_add_f32_e32 v77, v81, v117
	v_mul_f32_e32 v77, 0xbfb8aa3b, v77
	v_exp_f32_e32 v77, v77
	v_add_f32_e32 v76, 1.0, v76
	v_rcp_f32_e32 v76, v76
	v_add_f32_e32 v77, 1.0, v77
	v_rcp_f32_e32 v77, v77
	v_mul_f32_e32 v76, 0xc1000000, v76
	v_mul_f32_e32 v76, v158, v76
	v_mul_f32_e32 v76, 0x3fb8aa3b, v76
	v_exp_f32_e32 v76, v76
	s_nop 0
	v_sub_f32_e32 v80, 1.0, v76
	v_add_f32_e32 v81, 1.0, v76
	v_mul_f32_e32 v80, v80, v81
	v_max_f32_e32 v80, 0, v80
	v_sqrt_f32_e32 v80, v80
	s_nop 0
	v_mul_f32_e32 v77, v77, v80
	v_mul_f32_e32 v77, v77, v111
	ds_write2_b64 v177, v[120:121], v[76:77] offset1:17
	v_add_f32_e32 v76, v78, v114
	v_mul_f32_e32 v76, 0xbfb8aa3b, v76
	v_exp_f32_e32 v76, v76
	v_add_f32_e32 v77, v82, v118
	v_mul_f32_e32 v77, 0xbfb8aa3b, v77
	v_exp_f32_e32 v77, v77
	v_add_f32_e32 v76, 1.0, v76
	v_rcp_f32_e32 v76, v76
	v_add_f32_e32 v77, 1.0, v77
	v_rcp_f32_e32 v77, v77
	v_mul_f32_e32 v76, 0xc1000000, v76
	v_mul_f32_e32 v76, v159, v76
	v_mul_f32_e32 v76, 0x3fb8aa3b, v76
	v_exp_f32_e32 v76, v76
	s_nop 0
	v_sub_f32_e32 v78, 1.0, v76
	v_add_f32_e32 v80, 1.0, v76
	v_mul_f32_e32 v78, v78, v80
	v_max_f32_e32 v78, 0, v78
	v_sqrt_f32_e32 v78, v78
	s_nop 0
	v_mul_f32_e32 v77, v77, v78
	v_add_f32_e32 v78, v79, v115
	v_mul_f32_e32 v78, 0xbfb8aa3b, v78
	v_exp_f32_e32 v78, v78
	v_add_f32_e32 v79, v83, v119
	v_mul_f32_e32 v79, 0xbfb8aa3b, v79
	v_exp_f32_e32 v79, v79
	v_add_f32_e32 v78, 1.0, v78
	v_rcp_f32_e32 v78, v78
	v_mul_f32_e32 v77, v77, v122
	v_add_f32_e32 v79, 1.0, v79
	v_rcp_f32_e32 v79, v79
	v_mul_f32_e32 v78, 0xc1000000, v78
	v_mul_f32_e32 v78, v160, v78
	v_mul_f32_e32 v78, 0x3fb8aa3b, v78
	v_exp_f32_e32 v78, v78
	s_nop 0
	v_sub_f32_e32 v80, 1.0, v78
	v_add_f32_e32 v81, 1.0, v78
	v_mul_f32_e32 v80, v80, v81
	v_max_f32_e32 v80, 0, v80
	v_sqrt_f32_e32 v80, v80
	s_nop 0
	v_mul_f32_e32 v79, v79, v80
	v_mul_f32_e32 v79, v79, v123
	ds_write2_b64 v177, v[76:77], v[78:79] offset0:34 offset1:51
	v_mov_b32_e32 v112, v194
	v_mov_b32_e32 v113, v195
	v_mov_b32_e32 v114, v196
	v_mov_b32_e32 v115, v197
	v_mov_b32_e32 v116, v210
	v_mov_b32_e32 v117, v211
	v_mov_b32_e32 v118, v212
	v_mov_b32_e32 v119, v213
	v_mfma_f32_16x16x32_bf16 v[76:79], v[40:43], v[68:71], 0
	ds_read_b64 v[120:121], v2 offset:26144
	s_waitcnt lgkmcnt(0)
	v_lshlrev_b32_e32 v99, 16, v120
	v_mfma_f32_16x16x32_bf16 v[80:83], v[48:51], v[72:75], v[76:79]
	v_and_b32_e32 v111, 0xffff0000, v120
	v_lshlrev_b32_e32 v122, 16, v121
	v_and_b32_e32 v123, 0xffff0000, v121
	v_mfma_f32_16x16x32_bf16 v[76:79], v[36:39], v[68:71], 0
	v_mfma_f32_16x16x32_bf16 v[76:79], v[44:47], v[72:75], v[76:79]
	s_waitcnt vmcnt(1)
	s_nop 1
	v_add_f32_e32 v80, v80, v112
	v_mul_f32_e32 v80, 0xbfb8aa3b, v80
	v_exp_f32_e32 v80, v80
	s_waitcnt vmcnt(0)
	s_nop 0
	v_add_f32_e32 v76, v76, v116
	v_mul_f32_e32 v76, 0xbfb8aa3b, v76
	v_exp_f32_e32 v76, v76
	v_add_f32_e32 v80, 1.0, v80
	v_rcp_f32_e32 v80, v80
	v_add_f32_e32 v77, v77, v117
	v_add_f32_e32 v76, 1.0, v76
	v_rcp_f32_e32 v76, v76
	v_mul_f32_e32 v80, 0xc1000000, v80
	v_mul_f32_e32 v80, v161, v80
	v_mul_f32_e32 v80, 0x3fb8aa3b, v80
	v_exp_f32_e32 v120, v80
	v_mul_f32_e32 v77, 0xbfb8aa3b, v77
	v_exp_f32_e32 v77, v77
	v_add_f32_e32 v79, v79, v119
	v_sub_f32_e32 v80, 1.0, v120
	v_add_f32_e32 v112, 1.0, v120
	v_mul_f32_e32 v80, v80, v112
	v_max_f32_e32 v80, 0, v80
	v_sqrt_f32_e32 v80, v80
	v_add_f32_e32 v77, 1.0, v77
	v_rcp_f32_e32 v77, v77
	v_mul_f32_e32 v79, 0xbfb8aa3b, v79
	v_mul_f32_e32 v76, v76, v80
	v_mul_f32_e32 v121, v76, v99
	v_add_f32_e32 v76, v81, v113
	v_mul_f32_e32 v76, 0xbfb8aa3b, v76
	v_exp_f32_e32 v76, v76
	v_exp_f32_e32 v79, v79
	v_add_f32_e32 v76, 1.0, v76
	v_rcp_f32_e32 v76, v76
	v_add_f32_e32 v79, 1.0, v79
	v_rcp_f32_e32 v79, v79
	v_mul_f32_e32 v76, 0xc1000000, v76
	v_mul_f32_e32 v76, v162, v76
	v_mul_f32_e32 v76, 0x3fb8aa3b, v76
	v_exp_f32_e32 v76, v76
	s_nop 0
	v_sub_f32_e32 v80, 1.0, v76
	v_add_f32_e32 v81, 1.0, v76
	v_mul_f32_e32 v80, v80, v81
	v_max_f32_e32 v80, 0, v80
	v_sqrt_f32_e32 v80, v80
	s_nop 0
	v_mul_f32_e32 v77, v77, v80
	v_mul_f32_e32 v77, v77, v111
	ds_write2_b64 v178, v[120:121], v[76:77] offset0:16 offset1:33
	v_add_f32_e32 v76, v82, v114
	v_mul_f32_e32 v76, 0xbfb8aa3b, v76
	v_exp_f32_e32 v76, v76
	v_add_f32_e32 v77, v78, v118
	v_mul_f32_e32 v77, 0xbfb8aa3b, v77
	v_exp_f32_e32 v77, v77
	v_add_f32_e32 v76, 1.0, v76
	v_rcp_f32_e32 v76, v76
	v_add_f32_e32 v77, 1.0, v77
	v_rcp_f32_e32 v77, v77
	v_mul_f32_e32 v76, 0xc1000000, v76
	v_mul_f32_e32 v76, v164, v76
	v_mul_f32_e32 v76, 0x3fb8aa3b, v76
	v_exp_f32_e32 v76, v76
	s_nop 0
	v_sub_f32_e32 v78, 1.0, v76
	v_add_f32_e32 v80, 1.0, v76
	v_mul_f32_e32 v78, v78, v80
	v_max_f32_e32 v78, 0, v78
	v_sqrt_f32_e32 v78, v78
	s_nop 0
	v_mul_f32_e32 v77, v77, v78
	v_add_f32_e32 v78, v83, v115
	v_mul_f32_e32 v78, 0xbfb8aa3b, v78
	v_exp_f32_e32 v78, v78
	v_mul_f32_e32 v77, v77, v122
	v_add_f32_e32 v78, 1.0, v78
	v_rcp_f32_e32 v78, v78
	s_nop 0
	v_mul_f32_e32 v78, 0xc1000000, v78
	v_mul_f32_e32 v78, v166, v78
	v_mul_f32_e32 v78, 0x3fb8aa3b, v78
	v_exp_f32_e32 v78, v78
	s_nop 0
	v_sub_f32_e32 v80, 1.0, v78
	v_add_f32_e32 v81, 1.0, v78
	v_mul_f32_e32 v80, v80, v81
	v_max_f32_e32 v80, 0, v80
	v_sqrt_f32_e32 v80, v80
	s_nop 0
	v_mul_f32_e32 v79, v79, v80
	v_mul_f32_e32 v79, v79, v123
	ds_write2_b64 v178, v[76:77], v[78:79] offset0:50 offset1:67
	v_mov_b32_e32 v112, v198
	v_mov_b32_e32 v113, v199
	v_mov_b32_e32 v114, v200
	v_mov_b32_e32 v115, v201
	v_mov_b32_e32 v116, v214
	v_mov_b32_e32 v117, v215
	v_mov_b32_e32 v118, v216
	v_mov_b32_e32 v119, v217
	v_mfma_f32_16x16x32_bf16 v[76:79], v[24:27], v[68:71], 0
	ds_read_b64 v[120:121], v2 offset:26176
	s_waitcnt lgkmcnt(0)
	v_lshlrev_b32_e32 v99, 16, v120
	v_mfma_f32_16x16x32_bf16 v[80:83], v[32:35], v[72:75], v[76:79]
	v_and_b32_e32 v111, 0xffff0000, v120
	v_lshlrev_b32_e32 v122, 16, v121
	v_and_b32_e32 v123, 0xffff0000, v121
	v_mfma_f32_16x16x32_bf16 v[76:79], v[20:23], v[68:71], 0
	v_mfma_f32_16x16x32_bf16 v[76:79], v[28:31], v[72:75], v[76:79]
	s_waitcnt vmcnt(1)
	s_nop 1
	v_add_f32_e32 v80, v80, v112
	v_mul_f32_e32 v80, 0xbfb8aa3b, v80
	v_exp_f32_e32 v80, v80
	s_waitcnt vmcnt(0)
	s_nop 0
	v_add_f32_e32 v76, v76, v116
	v_mul_f32_e32 v76, 0xbfb8aa3b, v76
	v_exp_f32_e32 v76, v76
	v_add_f32_e32 v80, 1.0, v80
	v_rcp_f32_e32 v80, v80
	v_add_f32_e32 v77, v77, v117
	v_add_f32_e32 v76, 1.0, v76
	v_rcp_f32_e32 v76, v76
	v_mul_f32_e32 v80, 0xc1000000, v80
	v_mul_f32_e32 v80, v163, v80
	v_mul_f32_e32 v80, 0x3fb8aa3b, v80
	v_exp_f32_e32 v120, v80
	v_mul_f32_e32 v77, 0xbfb8aa3b, v77
	v_exp_f32_e32 v77, v77
	v_add_f32_e32 v79, v79, v119
	v_sub_f32_e32 v80, 1.0, v120
	v_add_f32_e32 v112, 1.0, v120
	v_mul_f32_e32 v80, v80, v112
	v_max_f32_e32 v80, 0, v80
	v_sqrt_f32_e32 v80, v80
	v_add_f32_e32 v77, 1.0, v77
	v_rcp_f32_e32 v77, v77
	v_mul_f32_e32 v79, 0xbfb8aa3b, v79
	v_mul_f32_e32 v76, v76, v80
	v_mul_f32_e32 v121, v76, v99
	v_add_f32_e32 v76, v81, v113
	v_mul_f32_e32 v76, 0xbfb8aa3b, v76
	v_exp_f32_e32 v76, v76
	v_exp_f32_e32 v79, v79
	v_add_f32_e32 v76, 1.0, v76
	v_rcp_f32_e32 v76, v76
	v_add_f32_e32 v79, 1.0, v79
	v_rcp_f32_e32 v79, v79
	v_mul_f32_e32 v76, 0xc1000000, v76
	v_mul_f32_e32 v76, v165, v76
	v_mul_f32_e32 v76, 0x3fb8aa3b, v76
	v_exp_f32_e32 v76, v76
	s_nop 0
	v_sub_f32_e32 v80, 1.0, v76
	v_add_f32_e32 v81, 1.0, v76
	v_mul_f32_e32 v80, v80, v81
	v_max_f32_e32 v80, 0, v80
	v_sqrt_f32_e32 v80, v80
	s_nop 0
	v_mul_f32_e32 v77, v77, v80
	v_mul_f32_e32 v77, v77, v111
	ds_write2_b64 v179, v[120:121], v[76:77] offset0:32 offset1:49
	v_add_f32_e32 v76, v82, v114
	v_mul_f32_e32 v76, 0xbfb8aa3b, v76
	v_exp_f32_e32 v76, v76
	v_add_f32_e32 v77, v78, v118
	v_mul_f32_e32 v77, 0xbfb8aa3b, v77
	v_exp_f32_e32 v77, v77
	v_add_f32_e32 v76, 1.0, v76
	v_rcp_f32_e32 v76, v76
	v_add_f32_e32 v77, 1.0, v77
	v_rcp_f32_e32 v77, v77
	v_mul_f32_e32 v76, 0xc1000000, v76
	v_mul_f32_e32 v76, v167, v76
	v_mul_f32_e32 v76, 0x3fb8aa3b, v76
	v_exp_f32_e32 v76, v76
	s_nop 0
	v_sub_f32_e32 v78, 1.0, v76
	v_add_f32_e32 v80, 1.0, v76
	v_mul_f32_e32 v78, v78, v80
	v_max_f32_e32 v78, 0, v78
	v_sqrt_f32_e32 v78, v78
	s_nop 0
	v_mul_f32_e32 v77, v77, v78
	v_add_f32_e32 v78, v83, v115
	v_mul_f32_e32 v78, 0xbfb8aa3b, v78
	v_exp_f32_e32 v78, v78
	v_mul_f32_e32 v77, v77, v122
	v_add_f32_e32 v78, 1.0, v78
	v_rcp_f32_e32 v78, v78
	s_nop 0
	v_mul_f32_e32 v78, 0xc1000000, v78
	v_mul_f32_e32 v78, v168, v78
	v_mul_f32_e32 v78, 0x3fb8aa3b, v78
	v_exp_f32_e32 v78, v78
	s_nop 0
	v_sub_f32_e32 v80, 1.0, v78
	v_add_f32_e32 v81, 1.0, v78
	v_mul_f32_e32 v80, v80, v81
	v_max_f32_e32 v80, 0, v80
	v_sqrt_f32_e32 v80, v80
	s_nop 0
	v_mul_f32_e32 v79, v79, v80
	v_mul_f32_e32 v79, v79, v123
	ds_write2_b64 v179, v[76:77], v[78:79] offset0:66 offset1:83
	v_mfma_f32_16x16x32_bf16 v[76:79], v[8:11], v[68:71], 0
	v_mfma_f32_16x16x32_bf16 v[68:71], v[4:7], v[68:71], 0
	v_mfma_f32_16x16x32_bf16 v[76:79], v[16:19], v[72:75], v[76:79]
	v_mfma_f32_16x16x32_bf16 v[68:71], v[12:15], v[72:75], v[68:71]
	v_mov_b32_e32 v72, v202
	v_mov_b32_e32 v73, v203
	v_mov_b32_e32 v74, v204
	v_mov_b32_e32 v75, v205
	v_mov_b32_e32 v80, v240
	v_mov_b32_e32 v81, v241
	v_mov_b32_e32 v82, v242
	v_mov_b32_e32 v83, v243
	ds_read_b64 v[112:113], v2 offset:26208
	s_waitcnt lgkmcnt(0)
	v_lshlrev_b32_e32 v2, 16, v112
	v_and_b32_e32 v99, 0xffff0000, v112
	v_lshlrev_b32_e32 v111, 16, v113
	v_and_b32_e32 v114, 0xffff0000, v113
	s_waitcnt vmcnt(1)
	v_add_f32_e32 v72, v76, v72
	v_mul_f32_e32 v72, 0xbfb8aa3b, v72
	v_exp_f32_e32 v72, v72
	s_waitcnt vmcnt(0)
	v_add_f32_e32 v68, v68, v80
	v_mul_f32_e32 v68, 0xbfb8aa3b, v68
	v_exp_f32_e32 v68, v68
	v_add_f32_e32 v72, 1.0, v72
	v_rcp_f32_e32 v72, v72
	v_add_f32_e32 v68, 1.0, v68
	v_rcp_f32_e32 v68, v68
	v_mul_f32_e32 v72, 0xc1000000, v72
	v_mul_f32_e32 v72, v169, v72
	v_mul_f32_e32 v72, 0x3fb8aa3b, v72
	v_exp_f32_e32 v112, v72
	s_nop 0
	v_sub_f32_e32 v72, 1.0, v112
	v_add_f32_e32 v76, 1.0, v112
	v_mul_f32_e32 v72, v72, v76
	v_max_f32_e32 v72, 0, v72
	v_sqrt_f32_e32 v72, v72
	s_nop 0
	v_mul_f32_e32 v68, v68, v72
	v_mul_f32_e32 v113, v68, v2
	v_add_f32_e32 v2, v77, v73
	v_mul_f32_e32 v2, 0xbfb8aa3b, v2
	v_exp_f32_e32 v2, v2
	v_add_f32_e32 v68, v69, v81
	v_mul_f32_e32 v68, 0xbfb8aa3b, v68
	v_exp_f32_e32 v68, v68
	v_add_f32_e32 v2, 1.0, v2
	v_rcp_f32_e32 v2, v2
	v_add_f32_e32 v68, 1.0, v68
	v_rcp_f32_e32 v69, v68
	v_mul_f32_e32 v2, 0xc1000000, v2
	v_mul_f32_e32 v2, v170, v2
	v_mul_f32_e32 v2, 0x3fb8aa3b, v2
	v_exp_f32_e32 v68, v2
	s_nop 0
	v_sub_f32_e32 v2, 1.0, v68
	v_add_f32_e32 v72, 1.0, v68
	v_mul_f32_e32 v2, v2, v72
	v_max_f32_e32 v2, 0, v2
	v_sqrt_f32_e32 v2, v2
	s_nop 0
	v_mul_f32_e32 v2, v69, v2
	v_mul_f32_e32 v69, v2, v99
	v_add_f32_e32 v2, v78, v74
	v_mul_f32_e32 v2, 0xbfb8aa3b, v2
	v_exp_f32_e32 v2, v2
	ds_write2_b64 v175, v[112:113], v[68:69] offset0:48 offset1:65
	v_add_f32_e32 v68, v70, v82
	v_mul_f32_e32 v68, 0xbfb8aa3b, v68
	v_add_f32_e32 v2, 1.0, v2
	v_rcp_f32_e32 v2, v2
	v_exp_f32_e32 v68, v68
	v_mul_f32_e32 v2, 0xc1000000, v2
	v_mul_f32_e32 v2, v172, v2
	v_add_f32_e32 v68, 1.0, v68
	v_mul_f32_e32 v2, 0x3fb8aa3b, v2
	v_rcp_f32_e32 v69, v68
	v_exp_f32_e32 v68, v2
	s_nop 0
	v_sub_f32_e32 v2, 1.0, v68
	v_add_f32_e32 v70, 1.0, v68
	v_mul_f32_e32 v2, v2, v70
	v_max_f32_e32 v2, 0, v2
	v_sqrt_f32_e32 v2, v2
	v_add_f32_e32 v70, v71, v83
	v_mul_f32_e32 v70, 0xbfb8aa3b, v70
	v_exp_f32_e32 v70, v70
	v_mul_f32_e32 v2, v69, v2
	v_mul_f32_e32 v69, v2, v111
	v_add_f32_e32 v2, v79, v75
	v_mul_f32_e32 v2, 0xbfb8aa3b, v2
	v_exp_f32_e32 v2, v2
	v_add_f32_e32 v70, 1.0, v70
	v_rcp_f32_e32 v71, v70
	v_add_f32_e32 v2, 1.0, v2
	v_rcp_f32_e32 v2, v2
	s_nop 0
	v_mul_f32_e32 v2, 0xc1000000, v2
	v_mul_f32_e32 v2, v173, v2
	v_mul_f32_e32 v2, 0x3fb8aa3b, v2
	v_exp_f32_e32 v70, v2
	s_nop 0
	v_sub_f32_e32 v2, 1.0, v70
	v_add_f32_e32 v72, 1.0, v70
	v_mul_f32_e32 v2, v2, v72
	v_max_f32_e32 v2, 0, v2
	v_sqrt_f32_e32 v2, v2
	s_nop 0
	v_mul_f32_e32 v2, v71, v2
	v_mul_f32_e32 v71, v2, v114
	ds_write2_b64 v175, v[68:69], v[70:71] offset0:82 offset1:99
	s_waitcnt lgkmcnt(0)
	s_barrier
	ds_read2_b64 v[124:127], v183 offset1:1
	ds_read2_b64 v[68:71], v184 offset1:1
	ds_read2_b64 v[128:131], v180 offset1:1
	ds_read2_b64 v[80:83], v171 offset1:1
	ds_read2_b64 v[132:135], v182 offset1:1
	ds_read2_b64 v[136:139], v181 offset1:1
	ds_read2_b64 v[72:75], v186 offset1:1
	ds_read2_b64 v[76:79], v185 offset1:1
	s_waitcnt lgkmcnt(0)
	s_barrier
	ds_read_b128 v[112:115], v176 offset:8704
	ds_read_b128 v[116:119], v176 offset:8768
	v_mov_b32_e32 v144, v190
	v_mov_b32_e32 v145, v191
	v_mov_b32_e32 v146, v192
	v_mov_b32_e32 v147, v193
	v_mov_b32_e32 v148, v206
	v_mov_b32_e32 v149, v207
	v_mov_b32_e32 v150, v208
	v_mov_b32_e32 v151, v209
	s_waitcnt lgkmcnt(1)
	v_mfma_f32_16x16x32_bf16 v[120:123], v[56:59], v[112:115], 0
	v_fma_f32 v2, v91, v126, v127
	v_fma_f32 v2, v124, v2, v125
	v_fma_f32 v2, v130, v2, v131
	s_waitcnt lgkmcnt(0)
	v_mfma_f32_16x16x32_bf16 v[120:123], v[64:67], v[116:119], v[120:123]
	v_fma_f32 v2, v128, v2, v129
	v_fma_f32 v2, v134, v2, v135
	v_fma_f32 v2, v132, v2, v133
	v_mfma_f32_16x16x32_bf16 v[140:143], v[52:55], v[112:115], 0
	v_fma_f32 v2, v138, v2, v139
	v_fma_f32 v2, v136, v2, v137
	ds_read_b64 v[188:189], v174 offset:8704
	v_fma_f32 v2, v70, v2, v71
	v_mfma_f32_16x16x32_bf16 v[140:143], v[60:63], v[116:119], v[140:143]
	v_fma_f32 v2, v68, v2, v69
	v_fma_f32 v2, v74, v2, v75
	v_fma_f32 v2, v72, v2, v73
	v_fma_f32 v2, v78, v2, v79
	s_waitcnt lgkmcnt(0)
	v_lshlrev_b32_e32 v71, 16, v188
	v_and_b32_e32 v79, 0xffff0000, v188
	v_lshlrev_b32_e32 v91, 16, v189
	v_and_b32_e32 v99, 0xffff0000, v189
	v_fma_f32 v2, v76, v2, v77
	v_fma_f32 v2, v82, v2, v83
	v_fma_f32 v2, v80, v2, v81
	s_waitcnt vmcnt(1)
	v_add_f32_e32 v111, v120, v144
	v_mul_f32_e32 v111, 0xbfb8aa3b, v111
	v_exp_f32_e32 v111, v111
	s_waitcnt vmcnt(0)
	v_add_f32_e32 v120, v140, v148
	v_mul_f32_e32 v120, 0xbfb8aa3b, v120
	v_exp_f32_e32 v120, v120
	v_add_f32_e32 v111, 1.0, v111
	v_rcp_f32_e32 v111, v111
	v_add_f32_e32 v120, 1.0, v120
	v_rcp_f32_e32 v120, v120
	v_mul_f32_e32 v111, 0xc1000000, v111
	v_mul_f32_e32 v111, v1, v111
	v_mul_f32_e32 v111, 0x3fb8aa3b, v111
	v_exp_f32_e32 v188, v111
	s_nop 0
	v_sub_f32_e32 v111, 1.0, v188
	v_add_f32_e32 v127, 1.0, v188
	v_mul_f32_e32 v111, v111, v127
	v_max_f32_e32 v111, 0, v111
	v_sqrt_f32_e32 v111, v111
	s_nop 0
	v_mul_f32_e32 v111, v120, v111
	v_mul_f32_e32 v189, v111, v71
	v_add_f32_e32 v71, v121, v145
	v_mul_f32_e32 v71, 0xbfb8aa3b, v71
	v_exp_f32_e32 v71, v71
	v_add_f32_e32 v111, v141, v149
	v_mul_f32_e32 v111, 0xbfb8aa3b, v111
	v_exp_f32_e32 v111, v111
	v_add_f32_e32 v71, 1.0, v71
	v_rcp_f32_e32 v71, v71
	v_add_f32_e32 v111, 1.0, v111
	v_rcp_f32_e32 v111, v111
	v_mul_f32_e32 v71, 0xc1000000, v71
	v_mul_f32_e32 v71, v158, v71
	v_mul_f32_e32 v71, 0x3fb8aa3b, v71
	v_exp_f32_e32 v120, v71
	s_nop 0
	v_sub_f32_e32 v71, 1.0, v120
	v_add_f32_e32 v121, 1.0, v120
	v_mul_f32_e32 v71, v71, v121
	v_max_f32_e32 v71, 0, v71
	v_sqrt_f32_e32 v71, v71
	s_nop 0
	v_mul_f32_e32 v71, v111, v71
	v_mul_f32_e32 v121, v71, v79
	v_add_f32_e32 v71, v122, v146
	v_mul_f32_e32 v71, 0xbfb8aa3b, v71
	v_exp_f32_e32 v71, v71
	ds_write2_b64 v177, v[188:189], v[120:121] offset1:17
	v_add_f32_e32 v79, v142, v150
	v_mul_f32_e32 v79, 0xbfb8aa3b, v79
	v_add_f32_e32 v71, 1.0, v71
	v_rcp_f32_e32 v71, v71
	v_exp_f32_e32 v79, v79
	v_mul_f32_e32 v71, 0xc1000000, v71
	v_mul_f32_e32 v71, v159, v71
	v_mul_f32_e32 v71, 0x3fb8aa3b, v71
	v_exp_f32_e32 v120, v71
	v_add_f32_e32 v79, 1.0, v79
	v_rcp_f32_e32 v79, v79
	v_sub_f32_e32 v71, 1.0, v120
	v_add_f32_e32 v111, 1.0, v120
	v_mul_f32_e32 v71, v71, v111
	v_max_f32_e32 v71, 0, v71
	v_sqrt_f32_e32 v71, v71
	s_nop 0
	v_mul_f32_e32 v71, v79, v71
	v_mul_f32_e32 v121, v71, v91
	v_add_f32_e32 v71, v123, v147
	v_mul_f32_e32 v71, 0xbfb8aa3b, v71
	v_exp_f32_e32 v71, v71
	v_add_f32_e32 v79, v143, v151
	v_mul_f32_e32 v79, 0xbfb8aa3b, v79
	v_exp_f32_e32 v79, v79
	v_add_f32_e32 v71, 1.0, v71
	v_rcp_f32_e32 v71, v71
	v_add_f32_e32 v79, 1.0, v79
	v_rcp_f32_e32 v79, v79
	v_mul_f32_e32 v71, 0xc1000000, v71
	v_mul_f32_e32 v71, v160, v71
	v_mul_f32_e32 v71, 0x3fb8aa3b, v71
	v_exp_f32_e32 v122, v71
	s_nop 0
	v_sub_f32_e32 v71, 1.0, v122
	v_add_f32_e32 v91, 1.0, v122
	v_mul_f32_e32 v71, v71, v91
	v_max_f32_e32 v71, 0, v71
	v_sqrt_f32_e32 v71, v71
	s_nop 0
	v_mul_f32_e32 v71, v79, v71
	v_mul_f32_e32 v123, v71, v99
	ds_write2_b64 v177, v[120:121], v[122:123] offset0:34 offset1:51
	v_mov_b32_e32 v144, v194
	v_mov_b32_e32 v145, v195
	v_mov_b32_e32 v146, v196
	v_mov_b32_e32 v147, v197
	v_mov_b32_e32 v148, v210
	v_mov_b32_e32 v149, v211
	v_mov_b32_e32 v150, v212
	v_mov_b32_e32 v151, v213
	v_mfma_f32_16x16x32_bf16 v[120:123], v[40:43], v[112:115], 0
	ds_read_b64 v[188:189], v174 offset:8736
	s_waitcnt lgkmcnt(0)
	v_lshlrev_b32_e32 v71, 16, v188
	v_mfma_f32_16x16x32_bf16 v[140:143], v[48:51], v[116:119], v[120:123]
	v_and_b32_e32 v79, 0xffff0000, v188
	v_lshlrev_b32_e32 v91, 16, v189
	v_and_b32_e32 v99, 0xffff0000, v189
	v_mfma_f32_16x16x32_bf16 v[120:123], v[36:39], v[112:115], 0
	v_mfma_f32_16x16x32_bf16 v[120:123], v[44:47], v[116:119], v[120:123]
	s_waitcnt vmcnt(1)
	s_nop 1
	v_add_f32_e32 v111, v140, v144
	v_mul_f32_e32 v111, 0xbfb8aa3b, v111
	v_exp_f32_e32 v111, v111
	s_waitcnt vmcnt(0)
	s_nop 0
	v_add_f32_e32 v120, v120, v148
	v_mul_f32_e32 v120, 0xbfb8aa3b, v120
	v_exp_f32_e32 v120, v120
	v_add_f32_e32 v111, 1.0, v111
	v_rcp_f32_e32 v111, v111
	v_add_f32_e32 v120, 1.0, v120
	v_rcp_f32_e32 v120, v120
	v_mul_f32_e32 v111, 0xc1000000, v111
	v_mul_f32_e32 v111, v161, v111
	v_mul_f32_e32 v111, 0x3fb8aa3b, v111
	v_exp_f32_e32 v188, v111
	s_nop 0
	v_sub_f32_e32 v111, 1.0, v188
	v_add_f32_e32 v127, 1.0, v188
	v_mul_f32_e32 v111, v111, v127
	v_max_f32_e32 v111, 0, v111
	v_sqrt_f32_e32 v111, v111
	s_nop 0
	v_mul_f32_e32 v111, v120, v111
	v_mul_f32_e32 v189, v111, v71
	v_add_f32_e32 v71, v141, v145
	v_mul_f32_e32 v71, 0xbfb8aa3b, v71
	v_exp_f32_e32 v71, v71
	v_add_f32_e32 v111, v121, v149
	v_mul_f32_e32 v111, 0xbfb8aa3b, v111
	v_exp_f32_e32 v111, v111
	v_add_f32_e32 v71, 1.0, v71
	v_rcp_f32_e32 v71, v71
	v_add_f32_e32 v111, 1.0, v111
	v_rcp_f32_e32 v111, v111
	v_mul_f32_e32 v71, 0xc1000000, v71
	v_mul_f32_e32 v71, v162, v71
	v_mul_f32_e32 v71, 0x3fb8aa3b, v71
	v_exp_f32_e32 v120, v71
	s_nop 0
	v_sub_f32_e32 v71, 1.0, v120
	v_add_f32_e32 v121, 1.0, v120
	v_mul_f32_e32 v71, v71, v121
	v_max_f32_e32 v71, 0, v71
	v_sqrt_f32_e32 v71, v71
	s_nop 0
	v_mul_f32_e32 v71, v111, v71
	v_mul_f32_e32 v121, v71, v79
	v_add_f32_e32 v71, v142, v146
	v_mul_f32_e32 v71, 0xbfb8aa3b, v71
	v_exp_f32_e32 v71, v71
	ds_write2_b64 v178, v[188:189], v[120:121] offset0:16 offset1:33
	v_add_f32_e32 v79, v122, v150
	v_mul_f32_e32 v79, 0xbfb8aa3b, v79
	v_add_f32_e32 v71, 1.0, v71
	v_rcp_f32_e32 v71, v71
	v_exp_f32_e32 v79, v79
	v_mul_f32_e32 v71, 0xc1000000, v71
	v_mul_f32_e32 v71, v164, v71
	v_mul_f32_e32 v71, 0x3fb8aa3b, v71
	v_exp_f32_e32 v120, v71
	v_add_f32_e32 v79, 1.0, v79
	v_rcp_f32_e32 v79, v79
	v_sub_f32_e32 v71, 1.0, v120
	v_add_f32_e32 v111, 1.0, v120
	v_mul_f32_e32 v71, v71, v111
	v_max_f32_e32 v71, 0, v71
	v_sqrt_f32_e32 v71, v71
	s_nop 0
	v_mul_f32_e32 v71, v79, v71
	v_mul_f32_e32 v121, v71, v91
	v_add_f32_e32 v71, v143, v147
	v_mul_f32_e32 v71, 0xbfb8aa3b, v71
	v_exp_f32_e32 v71, v71
	v_add_f32_e32 v79, v123, v151
	v_mul_f32_e32 v79, 0xbfb8aa3b, v79
	v_exp_f32_e32 v79, v79
	v_add_f32_e32 v71, 1.0, v71
	v_rcp_f32_e32 v71, v71
	v_add_f32_e32 v79, 1.0, v79
	v_rcp_f32_e32 v79, v79
	v_mul_f32_e32 v71, 0xc1000000, v71
	v_mul_f32_e32 v71, v166, v71
	v_mul_f32_e32 v71, 0x3fb8aa3b, v71
	v_exp_f32_e32 v122, v71
	s_nop 0
	v_sub_f32_e32 v71, 1.0, v122
	v_add_f32_e32 v91, 1.0, v122
	v_mul_f32_e32 v71, v71, v91
	v_max_f32_e32 v71, 0, v71
	v_sqrt_f32_e32 v71, v71
	s_nop 0
	v_mul_f32_e32 v71, v79, v71
	v_mul_f32_e32 v123, v71, v99
	ds_write2_b64 v178, v[120:121], v[122:123] offset0:50 offset1:67
	v_mov_b32_e32 v144, v198
	v_mov_b32_e32 v145, v199
	v_mov_b32_e32 v146, v200
	v_mov_b32_e32 v147, v201
	v_mov_b32_e32 v148, v214
	v_mov_b32_e32 v149, v215
	v_mov_b32_e32 v150, v216
	v_mov_b32_e32 v151, v217
	v_mfma_f32_16x16x32_bf16 v[120:123], v[24:27], v[112:115], 0
	ds_read_b64 v[188:189], v174 offset:8768
	s_waitcnt lgkmcnt(0)
	v_lshlrev_b32_e32 v71, 16, v188
	v_mfma_f32_16x16x32_bf16 v[140:143], v[32:35], v[116:119], v[120:123]
	v_and_b32_e32 v79, 0xffff0000, v188
	v_lshlrev_b32_e32 v91, 16, v189
	v_and_b32_e32 v99, 0xffff0000, v189
	v_mfma_f32_16x16x32_bf16 v[120:123], v[20:23], v[112:115], 0
	v_mfma_f32_16x16x32_bf16 v[120:123], v[28:31], v[116:119], v[120:123]
	s_waitcnt vmcnt(1)
	s_nop 1
	v_add_f32_e32 v111, v140, v144
	v_mul_f32_e32 v111, 0xbfb8aa3b, v111
	v_exp_f32_e32 v111, v111
	s_waitcnt vmcnt(0)
	s_nop 0
	v_add_f32_e32 v120, v120, v148
	v_mul_f32_e32 v120, 0xbfb8aa3b, v120
	v_exp_f32_e32 v120, v120
	v_add_f32_e32 v111, 1.0, v111
	v_rcp_f32_e32 v111, v111
	v_add_f32_e32 v120, 1.0, v120
	v_rcp_f32_e32 v120, v120
	v_mul_f32_e32 v111, 0xc1000000, v111
	v_mul_f32_e32 v111, v163, v111
	v_mul_f32_e32 v111, 0x3fb8aa3b, v111
	v_exp_f32_e32 v188, v111
	s_nop 0
	v_sub_f32_e32 v111, 1.0, v188
	v_add_f32_e32 v127, 1.0, v188
	v_mul_f32_e32 v111, v111, v127
	v_max_f32_e32 v111, 0, v111
	v_sqrt_f32_e32 v111, v111
	s_nop 0
	v_mul_f32_e32 v111, v120, v111
	v_mul_f32_e32 v189, v111, v71
	v_add_f32_e32 v71, v141, v145
	v_mul_f32_e32 v71, 0xbfb8aa3b, v71
	v_exp_f32_e32 v71, v71
	v_add_f32_e32 v111, v121, v149
	v_mul_f32_e32 v111, 0xbfb8aa3b, v111
	v_exp_f32_e32 v111, v111
	v_add_f32_e32 v71, 1.0, v71
	v_rcp_f32_e32 v71, v71
	v_add_f32_e32 v111, 1.0, v111
	v_rcp_f32_e32 v111, v111
	v_mul_f32_e32 v71, 0xc1000000, v71
	v_mul_f32_e32 v71, v165, v71
	v_mul_f32_e32 v71, 0x3fb8aa3b, v71
	v_exp_f32_e32 v120, v71
	s_nop 0
	v_sub_f32_e32 v71, 1.0, v120
	v_add_f32_e32 v121, 1.0, v120
	v_mul_f32_e32 v71, v71, v121
	v_max_f32_e32 v71, 0, v71
	v_sqrt_f32_e32 v71, v71
	s_nop 0
	v_mul_f32_e32 v71, v111, v71
	v_mul_f32_e32 v121, v71, v79
	v_add_f32_e32 v71, v142, v146
	v_mul_f32_e32 v71, 0xbfb8aa3b, v71
	v_exp_f32_e32 v71, v71
	ds_write2_b64 v179, v[188:189], v[120:121] offset0:32 offset1:49
	v_add_f32_e32 v79, v122, v150
	v_mul_f32_e32 v79, 0xbfb8aa3b, v79
	v_add_f32_e32 v71, 1.0, v71
	v_rcp_f32_e32 v71, v71
	v_exp_f32_e32 v79, v79
	v_mul_f32_e32 v71, 0xc1000000, v71
	v_mul_f32_e32 v71, v167, v71
	v_mul_f32_e32 v71, 0x3fb8aa3b, v71
	v_exp_f32_e32 v120, v71
	v_add_f32_e32 v79, 1.0, v79
	v_rcp_f32_e32 v79, v79
	v_sub_f32_e32 v71, 1.0, v120
	v_add_f32_e32 v111, 1.0, v120
	v_mul_f32_e32 v71, v71, v111
	v_max_f32_e32 v71, 0, v71
	v_sqrt_f32_e32 v71, v71
	s_nop 0
	v_mul_f32_e32 v71, v79, v71
	v_mul_f32_e32 v121, v71, v91
	v_add_f32_e32 v71, v143, v147
	v_mul_f32_e32 v71, 0xbfb8aa3b, v71
	v_exp_f32_e32 v71, v71
	v_add_f32_e32 v79, v123, v151
	v_mul_f32_e32 v79, 0xbfb8aa3b, v79
	v_exp_f32_e32 v79, v79
	v_add_f32_e32 v71, 1.0, v71
	v_rcp_f32_e32 v71, v71
	v_add_f32_e32 v79, 1.0, v79
	v_rcp_f32_e32 v79, v79
	v_mul_f32_e32 v71, 0xc1000000, v71
	v_mul_f32_e32 v71, v168, v71
	v_mul_f32_e32 v71, 0x3fb8aa3b, v71
	v_exp_f32_e32 v122, v71
	s_nop 0
	v_sub_f32_e32 v71, 1.0, v122
	v_add_f32_e32 v91, 1.0, v122
	v_mul_f32_e32 v71, v71, v91
	v_max_f32_e32 v71, 0, v71
	v_sqrt_f32_e32 v71, v71
	s_nop 0
	v_mul_f32_e32 v71, v79, v71
	v_mul_f32_e32 v123, v71, v99
	ds_write2_b64 v179, v[120:121], v[122:123] offset0:66 offset1:83
	v_mfma_f32_16x16x32_bf16 v[120:123], v[8:11], v[112:115], 0
	v_mfma_f32_16x16x32_bf16 v[112:115], v[4:7], v[112:115], 0
	v_mfma_f32_16x16x32_bf16 v[120:123], v[16:19], v[116:119], v[120:123]
	v_mfma_f32_16x16x32_bf16 v[112:115], v[12:15], v[116:119], v[112:115]
	v_mov_b32_e32 v116, v202
	v_mov_b32_e32 v117, v203
	v_mov_b32_e32 v118, v204
	v_mov_b32_e32 v119, v205
	v_mov_b32_e32 v140, v240
	v_mov_b32_e32 v141, v241
	v_mov_b32_e32 v142, v242
	v_mov_b32_e32 v143, v243
	ds_read_b64 v[144:145], v174 offset:8800
	s_waitcnt lgkmcnt(0)
	v_lshlrev_b32_e32 v71, 16, v144
	v_and_b32_e32 v79, 0xffff0000, v144
	v_lshlrev_b32_e32 v91, 16, v145
	v_and_b32_e32 v99, 0xffff0000, v145
	s_waitcnt vmcnt(1)
	v_add_f32_e32 v111, v120, v116
	v_mul_f32_e32 v111, 0xbfb8aa3b, v111
	v_exp_f32_e32 v111, v111
	s_waitcnt vmcnt(0)
	v_add_f32_e32 v112, v112, v140
	v_mul_f32_e32 v112, 0xbfb8aa3b, v112
	v_exp_f32_e32 v112, v112
	v_add_f32_e32 v111, 1.0, v111
	v_rcp_f32_e32 v111, v111
	v_add_f32_e32 v112, 1.0, v112
	v_rcp_f32_e32 v112, v112
	v_mul_f32_e32 v111, 0xc1000000, v111
	v_mul_f32_e32 v111, v169, v111
	v_mul_f32_e32 v111, 0x3fb8aa3b, v111
	v_exp_f32_e32 v144, v111
	s_nop 0
	v_sub_f32_e32 v111, 1.0, v144
	v_add_f32_e32 v116, 1.0, v144
	v_mul_f32_e32 v111, v111, v116
	v_max_f32_e32 v111, 0, v111
	v_sqrt_f32_e32 v111, v111
	v_mov_b32_e32 v116, v156
	v_mul_f32_e32 v111, v112, v111
	v_mul_f32_e32 v145, v111, v71
	v_add_f32_e32 v71, v121, v117
	v_mul_f32_e32 v71, 0xbfb8aa3b, v71
	v_exp_f32_e32 v71, v71
	v_add_f32_e32 v111, v113, v141
	v_mul_f32_e32 v111, 0xbfb8aa3b, v111
	v_exp_f32_e32 v111, v111
	v_add_f32_e32 v71, 1.0, v71
	v_rcp_f32_e32 v71, v71
	v_add_f32_e32 v111, 1.0, v111
	v_rcp_f32_e32 v111, v111
	v_mul_f32_e32 v71, 0xc1000000, v71
	v_mul_f32_e32 v71, v170, v71
	v_mul_f32_e32 v71, 0x3fb8aa3b, v71
	v_exp_f32_e32 v112, v71
	s_nop 0
	v_sub_f32_e32 v71, 1.0, v112
	v_add_f32_e32 v113, 1.0, v112
	v_mul_f32_e32 v71, v71, v113
	v_max_f32_e32 v71, 0, v71
	v_sqrt_f32_e32 v71, v71
	s_nop 0
	v_mul_f32_e32 v71, v111, v71
	v_mul_f32_e32 v113, v71, v79
	v_add_f32_e32 v71, v122, v118
	v_mul_f32_e32 v71, 0xbfb8aa3b, v71
	v_exp_f32_e32 v71, v71
	ds_write2_b64 v175, v[144:145], v[112:113] offset0:48 offset1:65
	v_add_f32_e32 v79, v114, v142
	v_mul_f32_e32 v79, 0xbfb8aa3b, v79
	v_add_f32_e32 v71, 1.0, v71
	v_rcp_f32_e32 v71, v71
	v_exp_f32_e32 v79, v79
	v_mov_b32_e32 v118, v106
	v_pk_mul_f32 v[106:107], v[156:157], v[106:107]
	v_mul_f32_e32 v71, 0xc1000000, v71
	v_mul_f32_e32 v71, v172, v71
	v_mul_f32_e32 v71, 0x3fb8aa3b, v71
	v_exp_f32_e32 v112, v71
	v_add_f32_e32 v79, 1.0, v79
	v_rcp_f32_e32 v79, v79
	v_pk_mul_f32 v[140:141], v[106:107], v[104:105]
	v_sub_f32_e32 v71, 1.0, v112
	v_add_f32_e32 v111, 1.0, v112
	v_mul_f32_e32 v71, v71, v111
	v_max_f32_e32 v71, 0, v71
	v_sqrt_f32_e32 v71, v71
	s_nop 0
	v_mul_f32_e32 v71, v79, v71
	v_mul_f32_e32 v113, v71, v91
	v_add_f32_e32 v71, v123, v119
	v_mul_f32_e32 v71, 0xbfb8aa3b, v71
	v_exp_f32_e32 v71, v71
	v_add_f32_e32 v79, v115, v143
	v_mul_f32_e32 v79, 0xbfb8aa3b, v79
	v_exp_f32_e32 v79, v79
	v_add_f32_e32 v71, 1.0, v71
	v_rcp_f32_e32 v71, v71
	v_add_f32_e32 v79, 1.0, v79
	v_rcp_f32_e32 v79, v79
	v_mul_f32_e32 v71, 0xc1000000, v71
	v_mul_f32_e32 v71, v173, v71
	v_mul_f32_e32 v71, 0x3fb8aa3b, v71
	v_exp_f32_e32 v114, v71
	s_nop 0
	v_sub_f32_e32 v71, 1.0, v114
	v_add_f32_e32 v91, 1.0, v114
	v_mul_f32_e32 v71, v71, v91
	v_max_f32_e32 v71, 0, v71
	v_sqrt_f32_e32 v71, v71
	s_nop 0
	v_mul_f32_e32 v71, v79, v71
	v_mul_f32_e32 v115, v71, v99
	ds_write2_b64 v175, v[112:113], v[114:115] offset0:82 offset1:99
	s_waitcnt lgkmcnt(0)
	s_barrier
	ds_read2_b64 v[112:115], v183 offset1:1
	s_waitcnt lgkmcnt(0)
	v_fma_f32 v117, v2, v114, v115
	v_mov_b32_e32 v119, v112
	v_pk_fma_f32 v[104:105], v[116:117], v[118:119], v[112:113]
	s_nop 0
	v_mov_b32_e32 v141, v105
	ds_read2_b64 v[120:123], v180 offset1:1
	ds_read2_b64 v[116:119], v182 offset1:1
	ds_read2_b64 v[104:107], v181 offset1:1
	s_waitcnt lgkmcnt(2)
	v_mov_b32_e32 v91, v122
	v_pk_mul_f32 v[142:143], v[140:141], v[90:91]
	v_pk_fma_f32 v[90:91], v[140:141], v[90:91], v[122:123]
	v_pk_mul_f32 v[88:89], v[142:143], v[88:89]
	v_mov_b32_e32 v140, v94
	v_mov_b32_e32 v90, v88
	v_mov_b32_e32 v141, v120
	v_pk_mul_f32 v[88:89], v[88:89], v[94:95]
	v_pk_fma_f32 v[90:91], v[90:91], v[140:141], v[120:121]
	v_pk_mul_f32 v[88:89], v[88:89], v[92:93]
	s_waitcnt lgkmcnt(1)
	v_mov_b32_e32 v99, v118
	v_mov_b32_e32 v89, v91
	v_pk_mul_f32 v[90:91], v[88:89], v[98:99]
	v_pk_fma_f32 v[88:89], v[88:89], v[98:99], v[118:119]
	v_pk_mul_f32 v[90:91], v[90:91], v[96:97]
	v_mov_b32_e32 v92, v102
	v_mov_b32_e32 v88, v90
	v_mov_b32_e32 v93, v116
	v_pk_mul_f32 v[90:91], v[90:91], v[102:103]
	v_pk_fma_f32 v[88:89], v[88:89], v[92:93], v[116:117]
	v_pk_mul_f32 v[90:91], v[90:91], v[100:101]
	s_waitcnt lgkmcnt(0)
	v_mov_b32_e32 v111, v106
	v_mov_b32_e32 v91, v89
	v_pk_mul_f32 v[88:89], v[90:91], v[110:111]
	v_pk_fma_f32 v[98:99], v[90:91], v[110:111], v[106:107]
	v_pk_mul_f32 v[96:97], v[88:89], v[108:109]
	ds_read2_b64 v[92:95], v184 offset1:1
	ds_read2_b64 v[88:91], v186 offset1:1
	v_mov_b32_e32 v98, v96
	v_mov_b32_e32 v100, v86
	v_mov_b32_e32 v101, v104
	v_pk_mul_f32 v[86:87], v[96:97], v[86:87]
	s_waitcnt lgkmcnt(1)
	v_mov_b32_e32 v127, v94
	v_pk_mul_f32 v[84:85], v[86:87], v[84:85]
	v_pk_fma_f32 v[86:87], v[98:99], v[100:101], v[104:105]
	v_mov_b32_e32 v96, v130
	v_mov_b32_e32 v85, v87
	v_pk_mul_f32 v[86:87], v[84:85], v[126:127]
	v_pk_fma_f32 v[84:85], v[84:85], v[126:127], v[94:95]
	v_pk_mul_f32 v[86:87], v[86:87], v[124:125]
	v_mov_b32_e32 v97, v92
	v_mov_b32_e32 v84, v86
	v_pk_mul_f32 v[86:87], v[86:87], v[130:131]
	v_pk_fma_f32 v[84:85], v[84:85], v[96:97], v[92:93]
	v_pk_mul_f32 v[86:87], v[86:87], v[128:129]
	s_waitcnt lgkmcnt(0)
	v_mov_b32_e32 v135, v90
	v_mov_b32_e32 v87, v85
	v_pk_mul_f32 v[84:85], v[86:87], v[134:135]
	v_pk_fma_f32 v[86:87], v[86:87], v[134:135], v[90:91]
	v_pk_mul_f32 v[84:85], v[84:85], v[132:133]
	v_mov_b32_e32 v96, v138
	v_mov_b32_e32 v86, v84
	v_mov_b32_e32 v97, v88
	v_pk_mul_f32 v[84:85], v[84:85], v[138:139]
	s_nop 0
	v_pk_mul_f32 v[124:125], v[84:85], v[136:137]
	v_pk_fma_f32 v[84:85], v[86:87], v[96:97], v[88:89]
	s_nop 0
	v_mov_b32_e32 v125, v85
	ds_read2_b64 v[84:87], v185 offset1:1
	ds_read2_b64 v[96:99], v171 offset1:1
	s_waitcnt lgkmcnt(0)
	s_barrier
	ds_read_b128 v[100:103], v176
	ds_read_b128 v[108:111], v176 offset:64
	s_waitcnt lgkmcnt(1)
	v_mfma_f32_16x16x32_bf16 v[56:59], v[56:59], v[100:103], 0
	v_mfma_f32_16x16x32_bf16 v[52:55], v[52:55], v[100:103], 0
	s_waitcnt lgkmcnt(0)
	v_mfma_f32_16x16x32_bf16 v[56:59], v[64:67], v[108:111], v[56:59]
	v_mfma_f32_16x16x32_bf16 v[52:55], v[60:63], v[108:111], v[52:55]
	v_mov_b32_e32 v60, v190
	v_mov_b32_e32 v61, v191
	v_mov_b32_e32 v62, v192
	v_mov_b32_e32 v63, v193
	v_mov_b32_e32 v64, v206
	v_mov_b32_e32 v65, v207
	v_mov_b32_e32 v66, v208
	v_mov_b32_e32 v67, v209
	ds_read_b64 v[126:127], v174
	s_waitcnt lgkmcnt(0)
	v_lshlrev_b32_e32 v2, 16, v126
	v_and_b32_e32 v71, 0xffff0000, v126
	v_lshlrev_b32_e32 v79, 16, v127
	v_and_b32_e32 v95, 0xffff0000, v127
	v_mfma_f32_16x16x32_bf16 v[40:43], v[40:43], v[100:103], 0
	s_waitcnt vmcnt(1)
	v_add_f32_e32 v56, v56, v60
	v_mul_f32_e32 v56, 0xbfb8aa3b, v56
	v_exp_f32_e32 v56, v56
	s_waitcnt vmcnt(0)
	v_add_f32_e32 v52, v52, v64
	v_mul_f32_e32 v52, 0xbfb8aa3b, v52
	v_exp_f32_e32 v52, v52
	v_add_f32_e32 v56, 1.0, v56
	v_rcp_f32_e32 v56, v56
	v_mfma_f32_16x16x32_bf16 v[36:39], v[36:39], v[100:103], 0
	v_add_f32_e32 v52, 1.0, v52
	v_rcp_f32_e32 v52, v52
	v_mul_f32_e32 v56, 0xc1000000, v56
	v_mul_f32_e32 v1, v1, v56
	v_mul_f32_e32 v1, 0x3fb8aa3b, v1
	v_exp_f32_e32 v126, v1
	v_mfma_f32_16x16x32_bf16 v[40:43], v[48:51], v[108:111], v[40:43]
	v_sub_f32_e32 v1, 1.0, v126
	v_add_f32_e32 v56, 1.0, v126
	v_mul_f32_e32 v1, v1, v56
	v_max_f32_e32 v1, 0, v1
	v_sqrt_f32_e32 v1, v1
	v_mfma_f32_16x16x32_bf16 v[36:39], v[44:47], v[108:111], v[36:39]
	v_mul_f32_e32 v1, v52, v1
	v_mul_f32_e32 v127, v1, v2
	v_add_f32_e32 v1, v57, v61
	v_mul_f32_e32 v1, 0xbfb8aa3b, v1
	v_exp_f32_e32 v1, v1
	v_add_f32_e32 v2, v53, v65
	v_mul_f32_e32 v2, 0xbfb8aa3b, v2
	v_exp_f32_e32 v2, v2
	v_add_f32_e32 v1, 1.0, v1
	v_rcp_f32_e32 v1, v1
	v_mfma_f32_16x16x32_bf16 v[24:27], v[24:27], v[100:103], 0
	v_add_f32_e32 v2, 1.0, v2
	v_rcp_f32_e32 v2, v2
	v_mul_f32_e32 v1, 0xc1000000, v1
	v_mul_f32_e32 v1, v158, v1
	v_mul_f32_e32 v1, 0x3fb8aa3b, v1
	v_exp_f32_e32 v52, v1
	v_mfma_f32_16x16x32_bf16 v[20:23], v[20:23], v[100:103], 0
	v_sub_f32_e32 v1, 1.0, v52
	v_add_f32_e32 v53, 1.0, v52
	v_mul_f32_e32 v1, v1, v53
	v_max_f32_e32 v1, 0, v1
	v_sqrt_f32_e32 v1, v1
	v_mfma_f32_16x16x32_bf16 v[24:27], v[32:35], v[108:111], v[24:27]
	v_mul_f32_e32 v1, v2, v1
	v_mul_f32_e32 v53, v1, v71
	v_add_f32_e32 v1, v58, v62
	v_mul_f32_e32 v1, 0xbfb8aa3b, v1
	v_exp_f32_e32 v1, v1
	ds_write2_b64 v177, v[126:127], v[52:53] offset1:17
	v_add_f32_e32 v2, v54, v66
	v_mul_f32_e32 v2, 0xbfb8aa3b, v2
	v_add_f32_e32 v1, 1.0, v1
	v_rcp_f32_e32 v1, v1
	v_exp_f32_e32 v2, v2
	v_mfma_f32_16x16x32_bf16 v[20:23], v[28:31], v[108:111], v[20:23]
	v_mov_b32_e32 v71, v86
	v_mul_f32_e32 v1, 0xc1000000, v1
	v_mul_f32_e32 v1, v159, v1
	v_mul_f32_e32 v1, 0x3fb8aa3b, v1
	v_exp_f32_e32 v52, v1
	v_add_f32_e32 v2, 1.0, v2
	v_rcp_f32_e32 v2, v2
	v_mfma_f32_16x16x32_bf16 v[8:11], v[8:11], v[100:103], 0
	v_sub_f32_e32 v1, 1.0, v52
	v_add_f32_e32 v53, 1.0, v52
	v_mul_f32_e32 v1, v1, v53
	v_max_f32_e32 v1, 0, v1
	v_sqrt_f32_e32 v1, v1
	v_mfma_f32_16x16x32_bf16 v[4:7], v[4:7], v[100:103], 0
	v_mul_f32_e32 v1, v2, v1
	v_mul_f32_e32 v53, v1, v79
	v_add_f32_e32 v1, v59, v63
	v_mul_f32_e32 v1, 0xbfb8aa3b, v1
	v_exp_f32_e32 v1, v1
	v_add_f32_e32 v2, v55, v67
	v_mul_f32_e32 v2, 0xbfb8aa3b, v2
	v_exp_f32_e32 v2, v2
	v_add_f32_e32 v1, 1.0, v1
	v_rcp_f32_e32 v1, v1
	v_mfma_f32_16x16x32_bf16 v[8:11], v[16:19], v[108:111], v[8:11]
	v_add_f32_e32 v2, 1.0, v2
	v_rcp_f32_e32 v2, v2
	v_mul_f32_e32 v1, 0xc1000000, v1
	v_mul_f32_e32 v1, v160, v1
	v_mul_f32_e32 v1, 0x3fb8aa3b, v1
	v_exp_f32_e32 v54, v1
	v_mfma_f32_16x16x32_bf16 v[4:7], v[12:15], v[108:111], v[4:7]
	v_mov_b32_e32 v79, v98
	v_sub_f32_e32 v1, 1.0, v54
	v_add_f32_e32 v55, 1.0, v54
	v_mul_f32_e32 v1, v1, v55
	v_max_f32_e32 v1, 0, v1
	v_sqrt_f32_e32 v1, v1
	s_nop 0
	v_mul_f32_e32 v1, v2, v1
	v_mul_f32_e32 v55, v1, v95
	ds_write2_b64 v177, v[52:53], v[54:55] offset0:34 offset1:51
	v_mov_b32_e32 v44, v194
	v_mov_b32_e32 v45, v195
	v_mov_b32_e32 v46, v196
	v_mov_b32_e32 v47, v197
	v_mov_b32_e32 v48, v210
	v_mov_b32_e32 v49, v211
	v_mov_b32_e32 v50, v212
	v_mov_b32_e32 v51, v213
	ds_read_b64 v[52:53], v174 offset:32
	s_waitcnt lgkmcnt(0)
	v_lshlrev_b32_e32 v1, 16, v52
	v_and_b32_e32 v2, 0xffff0000, v52
	v_lshlrev_b32_e32 v54, 16, v53
	v_and_b32_e32 v55, 0xffff0000, v53
	s_waitcnt vmcnt(1)
	v_add_f32_e32 v40, v40, v44
	v_mul_f32_e32 v40, 0xbfb8aa3b, v40
	v_exp_f32_e32 v40, v40
	s_waitcnt vmcnt(0)
	v_add_f32_e32 v36, v36, v48
	v_mul_f32_e32 v36, 0xbfb8aa3b, v36
	v_exp_f32_e32 v36, v36
	v_add_f32_e32 v40, 1.0, v40
	v_rcp_f32_e32 v40, v40
	v_add_f32_e32 v36, 1.0, v36
	v_rcp_f32_e32 v36, v36
	v_mul_f32_e32 v40, 0xc1000000, v40
	v_mul_f32_e32 v40, v161, v40
	v_mul_f32_e32 v40, 0x3fb8aa3b, v40
	v_exp_f32_e32 v52, v40
	s_nop 0
	v_sub_f32_e32 v40, 1.0, v52
	v_add_f32_e32 v44, 1.0, v52
	v_mul_f32_e32 v40, v40, v44
	v_max_f32_e32 v40, 0, v40
	v_sqrt_f32_e32 v40, v40
	s_nop 0
	v_mul_f32_e32 v36, v36, v40
	v_mul_f32_e32 v53, v36, v1
	v_add_f32_e32 v1, v41, v45
	v_mul_f32_e32 v1, 0xbfb8aa3b, v1
	v_exp_f32_e32 v1, v1
	v_add_f32_e32 v36, v37, v49
	v_mul_f32_e32 v36, 0xbfb8aa3b, v36
	v_exp_f32_e32 v36, v36
	v_add_f32_e32 v1, 1.0, v1
	v_rcp_f32_e32 v1, v1
	v_add_f32_e32 v36, 1.0, v36
	v_rcp_f32_e32 v37, v36
	v_mul_f32_e32 v1, 0xc1000000, v1
	v_mul_f32_e32 v1, v162, v1
	v_mul_f32_e32 v1, 0x3fb8aa3b, v1
	v_exp_f32_e32 v36, v1
	s_nop 0
	v_sub_f32_e32 v1, 1.0, v36
	v_add_f32_e32 v40, 1.0, v36
	v_mul_f32_e32 v1, v1, v40
	v_max_f32_e32 v1, 0, v1
	v_sqrt_f32_e32 v1, v1
	s_nop 0
	v_mul_f32_e32 v1, v37, v1
	v_mul_f32_e32 v37, v1, v2
	v_add_f32_e32 v1, v42, v46
	v_mul_f32_e32 v1, 0xbfb8aa3b, v1
	v_exp_f32_e32 v1, v1
	ds_write2_b64 v178, v[52:53], v[36:37] offset0:16 offset1:33
	v_add_f32_e32 v2, v38, v50
	v_mul_f32_e32 v2, 0xbfb8aa3b, v2
	v_add_f32_e32 v1, 1.0, v1
	v_rcp_f32_e32 v1, v1
	v_exp_f32_e32 v2, v2
	v_mul_f32_e32 v1, 0xc1000000, v1
	v_mul_f32_e32 v1, v164, v1
	v_mul_f32_e32 v1, 0x3fb8aa3b, v1
	v_exp_f32_e32 v36, v1
	v_add_f32_e32 v2, 1.0, v2
	v_rcp_f32_e32 v2, v2
	v_sub_f32_e32 v1, 1.0, v36
	v_add_f32_e32 v37, 1.0, v36
	v_mul_f32_e32 v1, v1, v37
	v_max_f32_e32 v1, 0, v1
	v_sqrt_f32_e32 v1, v1
	s_nop 0
	v_mul_f32_e32 v1, v2, v1
	v_mul_f32_e32 v37, v1, v54
	v_add_f32_e32 v1, v43, v47
	v_mul_f32_e32 v1, 0xbfb8aa3b, v1
	v_exp_f32_e32 v1, v1
	v_add_f32_e32 v2, v39, v51
	v_mul_f32_e32 v2, 0xbfb8aa3b, v2
	v_exp_f32_e32 v2, v2
	v_add_f32_e32 v1, 1.0, v1
	v_rcp_f32_e32 v1, v1
	v_add_f32_e32 v2, 1.0, v2
	v_rcp_f32_e32 v2, v2
	v_mul_f32_e32 v1, 0xc1000000, v1
	v_mul_f32_e32 v1, v166, v1
	v_mul_f32_e32 v1, 0x3fb8aa3b, v1
	v_exp_f32_e32 v38, v1
	s_nop 0
	v_sub_f32_e32 v1, 1.0, v38
	v_add_f32_e32 v39, 1.0, v38
	v_mul_f32_e32 v1, v1, v39
	v_max_f32_e32 v1, 0, v1
	v_sqrt_f32_e32 v1, v1
	s_nop 0
	v_mul_f32_e32 v1, v2, v1
	v_mul_f32_e32 v39, v1, v55
	ds_write2_b64 v178, v[36:37], v[38:39] offset0:50 offset1:67
	v_mov_b32_e32 v28, v198
	v_mov_b32_e32 v29, v199
	v_mov_b32_e32 v30, v200
	v_mov_b32_e32 v31, v201
	v_mov_b32_e32 v32, v214
	v_mov_b32_e32 v33, v215
	v_mov_b32_e32 v34, v216
	v_mov_b32_e32 v35, v217
	ds_read_b64 v[36:37], v174 offset:64
	s_waitcnt lgkmcnt(0)
	v_lshlrev_b32_e32 v1, 16, v36
	v_and_b32_e32 v2, 0xffff0000, v36
	v_lshlrev_b32_e32 v38, 16, v37
	v_and_b32_e32 v39, 0xffff0000, v37
	s_waitcnt vmcnt(1)
	v_add_f32_e32 v24, v24, v28
	v_mul_f32_e32 v24, 0xbfb8aa3b, v24
	v_exp_f32_e32 v24, v24
	s_waitcnt vmcnt(0)
	v_add_f32_e32 v20, v20, v32
	v_mul_f32_e32 v20, 0xbfb8aa3b, v20
	v_exp_f32_e32 v20, v20
	v_add_f32_e32 v24, 1.0, v24
	v_rcp_f32_e32 v24, v24
	v_mov_b32_e32 v32, v98
	v_add_f32_e32 v20, 1.0, v20
	v_rcp_f32_e32 v20, v20
	v_mul_f32_e32 v24, 0xc1000000, v24
	v_mul_f32_e32 v24, v163, v24
	v_mul_f32_e32 v24, 0x3fb8aa3b, v24
	v_exp_f32_e32 v36, v24
	s_nop 0
	v_sub_f32_e32 v24, 1.0, v36
	v_add_f32_e32 v28, 1.0, v36
	v_mul_f32_e32 v24, v24, v28
	v_max_f32_e32 v24, 0, v24
	v_sqrt_f32_e32 v24, v24
	s_nop 0
	v_mul_f32_e32 v20, v20, v24
	v_mul_f32_e32 v37, v20, v1
	v_add_f32_e32 v1, v25, v29
	v_mul_f32_e32 v1, 0xbfb8aa3b, v1
	v_exp_f32_e32 v1, v1
	v_add_f32_e32 v20, v21, v33
	v_mul_f32_e32 v20, 0xbfb8aa3b, v20
	v_exp_f32_e32 v20, v20
	v_add_f32_e32 v1, 1.0, v1
	v_rcp_f32_e32 v1, v1
	v_add_f32_e32 v20, 1.0, v20
	v_rcp_f32_e32 v21, v20
	v_mul_f32_e32 v1, 0xc1000000, v1
	v_mul_f32_e32 v1, v165, v1
	v_mul_f32_e32 v1, 0x3fb8aa3b, v1
	v_exp_f32_e32 v20, v1
	s_nop 0
	v_sub_f32_e32 v1, 1.0, v20
	v_add_f32_e32 v24, 1.0, v20
	v_mul_f32_e32 v1, v1, v24
	v_max_f32_e32 v1, 0, v1
	v_sqrt_f32_e32 v1, v1
	s_nop 0
	v_mul_f32_e32 v1, v21, v1
	v_mul_f32_e32 v21, v1, v2
	v_add_f32_e32 v1, v26, v30
	v_mul_f32_e32 v1, 0xbfb8aa3b, v1
	v_exp_f32_e32 v1, v1
	ds_write2_b64 v179, v[36:37], v[20:21] offset0:32 offset1:49
	v_add_f32_e32 v2, v22, v34
	v_mul_f32_e32 v2, 0xbfb8aa3b, v2
	v_add_f32_e32 v1, 1.0, v1
	v_rcp_f32_e32 v1, v1
	v_exp_f32_e32 v2, v2
	v_mul_f32_e32 v1, 0xc1000000, v1
	v_mul_f32_e32 v1, v167, v1
	v_mul_f32_e32 v1, 0x3fb8aa3b, v1
	v_exp_f32_e32 v20, v1
	v_add_f32_e32 v2, 1.0, v2
	v_rcp_f32_e32 v2, v2
	v_sub_f32_e32 v1, 1.0, v20
	v_add_f32_e32 v21, 1.0, v20
	v_mul_f32_e32 v1, v1, v21
	v_max_f32_e32 v1, 0, v1
	v_sqrt_f32_e32 v1, v1
	s_nop 0
	v_mul_f32_e32 v1, v2, v1
	v_mul_f32_e32 v21, v1, v38
	v_add_f32_e32 v1, v27, v31
	v_mul_f32_e32 v1, 0xbfb8aa3b, v1
	v_exp_f32_e32 v1, v1
	v_add_f32_e32 v2, v23, v35
	v_mul_f32_e32 v2, 0xbfb8aa3b, v2
	v_exp_f32_e32 v2, v2
	v_add_f32_e32 v1, 1.0, v1
	v_rcp_f32_e32 v1, v1
	v_add_f32_e32 v2, 1.0, v2
	v_rcp_f32_e32 v2, v2
	v_mul_f32_e32 v1, 0xc1000000, v1
	v_mul_f32_e32 v1, v168, v1
	v_mul_f32_e32 v1, 0x3fb8aa3b, v1
	v_exp_f32_e32 v22, v1
	s_nop 0
	v_sub_f32_e32 v1, 1.0, v22
	v_add_f32_e32 v23, 1.0, v22
	v_mul_f32_e32 v1, v1, v23
	v_max_f32_e32 v1, 0, v1
	v_sqrt_f32_e32 v1, v1
	s_nop 0
	v_mul_f32_e32 v1, v2, v1
	v_mul_f32_e32 v23, v1, v39
	ds_write2_b64 v179, v[20:21], v[22:23] offset0:66 offset1:83
	v_mov_b32_e32 v12, v202
	v_mov_b32_e32 v13, v203
	v_mov_b32_e32 v14, v204
	v_mov_b32_e32 v15, v205
	v_mov_b32_e32 v16, v240
	v_mov_b32_e32 v17, v241
	v_mov_b32_e32 v18, v242
	v_mov_b32_e32 v19, v243
	ds_read_b64 v[20:21], v174 offset:96
	s_waitcnt lgkmcnt(0)
	v_lshlrev_b32_e32 v1, 16, v20
	v_and_b32_e32 v2, 0xffff0000, v20
	v_lshlrev_b32_e32 v22, 16, v21
	v_and_b32_e32 v23, 0xffff0000, v21
	s_waitcnt vmcnt(1)
	v_add_f32_e32 v8, v8, v12
	v_mul_f32_e32 v8, 0xbfb8aa3b, v8
	v_exp_f32_e32 v8, v8
	s_waitcnt vmcnt(0)
	v_add_f32_e32 v4, v4, v16
	v_mul_f32_e32 v4, 0xbfb8aa3b, v4
	v_exp_f32_e32 v4, v4
	v_add_f32_e32 v8, 1.0, v8
	v_rcp_f32_e32 v8, v8
	v_add_f32_e32 v4, 1.0, v4
	v_rcp_f32_e32 v4, v4
	v_mul_f32_e32 v8, 0xc1000000, v8
	v_mul_f32_e32 v8, v169, v8
	v_mul_f32_e32 v8, 0x3fb8aa3b, v8
	v_exp_f32_e32 v20, v8
	s_nop 0
	v_sub_f32_e32 v8, 1.0, v20
	v_add_f32_e32 v12, 1.0, v20
	v_mul_f32_e32 v8, v8, v12
	v_max_f32_e32 v8, 0, v8
	v_sqrt_f32_e32 v8, v8
	s_nop 0
	v_mul_f32_e32 v4, v4, v8
	v_mul_f32_e32 v21, v4, v1
	v_add_f32_e32 v1, v9, v13
	v_mul_f32_e32 v1, 0xbfb8aa3b, v1
	v_exp_f32_e32 v1, v1
	v_add_f32_e32 v4, v5, v17
	v_mul_f32_e32 v4, 0xbfb8aa3b, v4
	v_exp_f32_e32 v4, v4
	v_add_f32_e32 v1, 1.0, v1
	v_rcp_f32_e32 v1, v1
	v_mov_b32_e32 v9, v84
	v_add_f32_e32 v4, 1.0, v4
	v_rcp_f32_e32 v5, v4
	v_mul_f32_e32 v1, 0xc1000000, v1
	v_mul_f32_e32 v1, v170, v1
	v_mul_f32_e32 v1, 0x3fb8aa3b, v1
	v_exp_f32_e32 v4, v1
	s_nop 0
	v_sub_f32_e32 v1, 1.0, v4
	v_add_f32_e32 v8, 1.0, v4
	v_mul_f32_e32 v1, v1, v8
	v_max_f32_e32 v1, 0, v1
	v_sqrt_f32_e32 v1, v1
	v_mov_b32_e32 v8, v74
	v_mul_f32_e32 v1, v5, v1
	v_mul_f32_e32 v5, v1, v2
	v_add_f32_e32 v1, v10, v14
	v_mul_f32_e32 v1, 0xbfb8aa3b, v1
	v_exp_f32_e32 v1, v1
	ds_write2_b64 v175, v[20:21], v[4:5] offset0:48 offset1:65
	v_add_f32_e32 v2, v6, v18
	v_mul_f32_e32 v2, 0xbfb8aa3b, v2
	v_add_f32_e32 v1, 1.0, v1
	v_rcp_f32_e32 v1, v1
	v_exp_f32_e32 v2, v2
	v_mul_f32_e32 v1, 0xc1000000, v1
	v_mul_f32_e32 v1, v172, v1
	v_mul_f32_e32 v1, 0x3fb8aa3b, v1
	v_exp_f32_e32 v4, v1
	v_add_f32_e32 v2, 1.0, v2
	v_rcp_f32_e32 v2, v2
	v_sub_f32_e32 v1, 1.0, v4
	v_add_f32_e32 v5, 1.0, v4
	v_mul_f32_e32 v1, v1, v5
	v_max_f32_e32 v1, 0, v1
	v_sqrt_f32_e32 v1, v1
	s_nop 0
	v_mul_f32_e32 v1, v2, v1
	v_mul_f32_e32 v5, v1, v22
	v_add_f32_e32 v1, v11, v15
	v_mul_f32_e32 v1, 0xbfb8aa3b, v1
	v_exp_f32_e32 v1, v1
	v_add_f32_e32 v2, v7, v19
	v_mul_f32_e32 v2, 0xbfb8aa3b, v2
	v_exp_f32_e32 v2, v2
	v_add_f32_e32 v1, 1.0, v1
	v_rcp_f32_e32 v1, v1
	v_add_f32_e32 v2, 1.0, v2
	v_rcp_f32_e32 v2, v2
	v_mul_f32_e32 v1, 0xc1000000, v1
	v_mul_f32_e32 v1, v173, v1
	v_mul_f32_e32 v1, 0x3fb8aa3b, v1
	v_exp_f32_e32 v6, v1
	s_nop 0
	v_sub_f32_e32 v1, 1.0, v6
	v_add_f32_e32 v7, 1.0, v6
	v_mul_f32_e32 v1, v1, v7
	v_max_f32_e32 v1, 0, v1
	v_sqrt_f32_e32 v1, v1
	s_nop 0
	v_mul_f32_e32 v1, v2, v1
	v_mul_f32_e32 v7, v1, v23
	ds_write2_b64 v175, v[4:5], v[6:7] offset0:82 offset1:99
	v_pk_mul_f32 v[4:5], v[124:125], v[70:71]
	v_pk_fma_f32 v[6:7], v[124:125], v[70:71], v[86:87]
	v_pk_mul_f32 v[4:5], v[4:5], v[68:69]
	s_waitcnt lgkmcnt(0)
	v_mov_b32_e32 v6, v4
	v_pk_mul_f32 v[4:5], v[4:5], v[74:75]
	v_pk_fma_f32 v[6:7], v[6:7], v[8:9], v[84:85]
	v_pk_mul_f32 v[4:5], v[4:5], v[72:73]
	s_barrier
	ds_read2_b64 v[16:19], v183 offset1:1
	v_mov_b32_e32 v5, v7
	v_pk_mul_f32 v[6:7], v[4:5], v[78:79]
	v_pk_fma_f32 v[4:5], v[4:5], v[78:79], v[98:99]
	v_pk_mul_f32 v[6:7], v[6:7], v[76:77]
	v_mov_b32_e32 v8, v82
	v_mov_b32_e32 v4, v6
	v_mov_b32_e32 v9, v96
	v_pk_mul_f32 v[6:7], v[6:7], v[82:83]
	v_pk_fma_f32 v[4:5], v[4:5], v[8:9], v[96:97]
	v_pk_mul_f32 v[6:7], v[6:7], v[80:81]
	s_waitcnt lgkmcnt(0)
	v_mov_b32_e32 v115, v18
	v_mov_b32_e32 v7, v5
	v_pk_mul_f32 v[4:5], v[6:7], v[114:115]
	ds_read2_b64 v[20:23], v180 offset1:1
	ds_read2_b64 v[24:27], v182 offset1:1
	v_pk_mul_f32 v[4:5], v[4:5], v[112:113]
	v_pk_fma_f32 v[6:7], v[6:7], v[114:115], v[18:19]
	v_mov_b32_e32 v8, v122
	v_mov_b32_e32 v6, v4
	v_mov_b32_e32 v9, v16
	v_pk_mul_f32 v[4:5], v[4:5], v[122:123]
	v_pk_fma_f32 v[6:7], v[6:7], v[8:9], v[16:17]
	v_pk_mul_f32 v[4:5], v[4:5], v[120:121]
	s_waitcnt lgkmcnt(1)
	v_mov_b32_e32 v119, v22
	v_mov_b32_e32 v5, v7
	v_pk_mul_f32 v[6:7], v[4:5], v[118:119]
	v_pk_fma_f32 v[4:5], v[4:5], v[118:119], v[22:23]
	v_pk_mul_f32 v[6:7], v[6:7], v[116:117]
	v_mov_b32_e32 v8, v106
	v_mov_b32_e32 v4, v6
	v_mov_b32_e32 v9, v20
	v_pk_mul_f32 v[6:7], v[6:7], v[106:107]
	v_pk_fma_f32 v[4:5], v[4:5], v[8:9], v[20:21]
	v_pk_mul_f32 v[6:7], v[6:7], v[104:105]
	s_waitcnt lgkmcnt(0)
	v_mov_b32_e32 v95, v26
	v_mov_b32_e32 v7, v5
	v_pk_mul_f32 v[4:5], v[6:7], v[94:95]
	v_pk_fma_f32 v[6:7], v[6:7], v[94:95], v[26:27]
	v_pk_mul_f32 v[4:5], v[4:5], v[92:93]
	v_mov_b32_e32 v8, v90
	v_mov_b32_e32 v6, v4
	v_mov_b32_e32 v9, v24
	v_pk_mul_f32 v[4:5], v[4:5], v[90:91]
	v_ashrrev_i32_e32 v1, 31, v0
	v_pk_mul_f32 v[28:29], v[4:5], v[88:89]
	v_pk_fma_f32 v[4:5], v[6:7], v[8:9], v[24:25]
	v_lshl_add_u64 v[0:1], v[0:1], 3, s[0:1]
	v_mov_b32_e32 v29, v5
	ds_read2_b64 v[12:15], v181 offset1:1
	ds_read2_b64 v[8:11], v184 offset1:1
	ds_read2_b64 v[4:7], v186 offset1:1
	s_waitcnt lgkmcnt(2)
	v_mov_b32_e32 v87, v14
	v_pk_mul_f32 v[30:31], v[28:29], v[86:87]
	v_pk_fma_f32 v[28:29], v[28:29], v[86:87], v[14:15]
	v_pk_mul_f32 v[30:31], v[30:31], v[84:85]
	v_mov_b32_e32 v33, v12
	v_mov_b32_e32 v28, v30
	v_pk_mul_f32 v[30:31], v[30:31], v[98:99]
	v_pk_fma_f32 v[28:29], v[28:29], v[32:33], v[12:13]
	v_pk_mul_f32 v[30:31], v[30:31], v[96:97]
	s_waitcnt lgkmcnt(1)
	v_mov_b32_e32 v19, v10
	v_mov_b32_e32 v31, v29
	v_pk_mul_f32 v[28:29], v[30:31], v[18:19]
	v_pk_fma_f32 v[18:19], v[30:31], v[18:19], v[10:11]
	v_pk_mul_f32 v[16:17], v[28:29], v[16:17]
	v_mov_b32_e32 v28, v22
	v_mov_b32_e32 v18, v16
	v_mov_b32_e32 v29, v8
	v_pk_mul_f32 v[16:17], v[16:17], v[22:23]
	v_pk_fma_f32 v[18:19], v[18:19], v[28:29], v[8:9]
	v_pk_mul_f32 v[16:17], v[16:17], v[20:21]
	s_waitcnt lgkmcnt(0)
	v_mov_b32_e32 v27, v6
	v_mov_b32_e32 v17, v19
	v_pk_mul_f32 v[18:19], v[16:17], v[26:27]
	v_pk_fma_f32 v[20:21], v[16:17], v[26:27], v[6:7]
	v_pk_mul_f32 v[22:23], v[18:19], v[24:25]
	ds_read2_b64 v[16:19], v185 offset1:1
	ds_read2_b64 v[24:27], v171 offset1:1
	v_mov_b32_e32 v20, v22
	v_mov_b32_e32 v28, v14
	v_mov_b32_e32 v29, v4
	v_pk_mul_f32 v[14:15], v[22:23], v[14:15]
	s_waitcnt lgkmcnt(1)
	v_mov_b32_e32 v11, v18
	v_pk_mul_f32 v[12:13], v[14:15], v[12:13]
	v_pk_fma_f32 v[14:15], v[20:21], v[28:29], v[4:5]
	s_waitcnt lgkmcnt(0)
	v_mov_b32_e32 v13, v15
	v_pk_mul_f32 v[14:15], v[12:13], v[10:11]
	v_pk_fma_f32 v[10:11], v[12:13], v[10:11], v[18:19]
	v_pk_mul_f32 v[8:9], v[14:15], v[8:9]
	v_mov_b32_e32 v12, v6
	v_mov_b32_e32 v10, v8
	v_mov_b32_e32 v13, v16
	v_pk_mul_f32 v[6:7], v[8:9], v[6:7]
	v_mov_b32_e32 v19, v26
	v_pk_mul_f32 v[4:5], v[6:7], v[4:5]
	v_pk_fma_f32 v[6:7], v[10:11], v[12:13], v[16:17]
	v_mov_b32_e32 v8, v26
	v_mov_b32_e32 v5, v7
	v_pk_mul_f32 v[6:7], v[4:5], v[18:19]
	v_pk_fma_f32 v[4:5], v[4:5], v[18:19], v[26:27]
	v_pk_mul_f32 v[6:7], v[6:7], v[16:17]
	v_mov_b32_e32 v9, v24
	v_mov_b32_e32 v4, v6
	v_pk_mul_f32 v[6:7], v[6:7], v[26:27]
	v_pk_fma_f32 v[4:5], v[4:5], v[8:9], v[24:25]
	v_pk_mul_f32 v[6:7], v[6:7], v[24:25]
	s_barrier
	v_mov_b32_e32 v7, v5
	global_store_dwordx2 v[0:1], v[6:7], off
